# select key loads prefetched per row: 259 ds_reads hoisted ahead of the compare chains
# speedup vs baseline: 1.0149x; 1.0014x over previous
; DI int tidx() { int t = __builtin_amdgcn_workitem_id_x(); asm volatile("" : "+v"(t)); return t; }
; #define SEL2(N_) { b1_select<N_>(scb + (2 * wave) * 2048, nj, mo); b1_select<N_>(scb + (2 * wave + 1) * 2048, nj, mo + 64); }
; template <int NJ>
; DI void b1_select(const float* sc, int nj, unsigned* mo) {
;   const int lane = tidx() & 63;
;   unsigned key[NJ];
; #pragma unroll
;   for (int j = 0; j < NJ; ++j) {
;     unsigned k = 0u;
;     if (j < nj) {
;       unsigned u = __float_as_uint(sc[64 * j + lane]);
;       u = (u == 0x80000000u) ? 0u : u;
;       k = (u & 0x80000000u) ? ~u : (u | 0x80000000u);
;     }
;     key[j] = k;
;   }
; PHASE_FN void phaseB(const P& p, int layer, char* lds) {
;     ...
;         switch ((nj + 3) >> 2) {
;           case 2: SEL2(8) break;
;           case 3: SEL2(12) break;
;           case 4: SEL2(16) break;
;           case 5: SEL2(20) break;
;           case 6: SEL2(24) break;
;           case 7: SEL2(28) break;
.LBB0_444:
	s_add_i32 s0, s0, 3
	s_lshr_b32 s4, s0, 2
	s_cmp_gt_u32 s8, 2
	s_mov_b32 s3, s53
	s_cselect_b64 s[6:7], -1, 0
	s_mov_b64 s[0:1], -1
	s_mov_b64 s[12:13], 0
	s_cmp_lt_i32 s4, 5
	s_mov_b64 s[10:11], 0
	v_writelane_b32 v238, s2, 54
	v_writelane_b32 v237, s26, 13
	s_waitcnt lgkmcnt(0)
	s_barrier
	v_writelane_b32 v238, s3, 55
	v_writelane_b32 v237, s8, 15
	s_cbranch_scc1 .LBB0_798
	s_cmp_gt_i32 s4, 5
	s_cbranch_scc0 .LBB0_697
	s_cmp_gt_i32 s4, 6
	s_cbranch_scc0 .LBB0_580
	s_cmp_eq_u32 s4, 7
	s_mov_b64 s[10:11], -1
	s_cbranch_scc0 .LBB0_579
	v_mov_b32_e32 v0, v158
	v_readlane_b32 s0, v238, 63
	v_and_b32_e32 v0, 63, v0
	v_cndmask_b32_e64 v3, 0, 1, s[6:7]
	v_lshl_add_u32 v30, v0, 2, s0
	ds_read_b32 v104, v30 offset:256
	ds_read_b32 v105, v30 offset:512
	ds_read_b32 v106, v30 offset:768
	ds_read_b32 v107, v30 offset:1024
	ds_read_b32 v108, v30 offset:1280
	ds_read_b32 v109, v30 offset:1536
	ds_read_b32 v110, v30 offset:1792
	ds_read_b32 v111, v30 offset:2048
	ds_read_b32 v112, v30 offset:2304
	ds_read_b32 v113, v30 offset:2560
	ds_read_b32 v114, v30 offset:2816
	ds_read_b32 v115, v30 offset:3072
	ds_read_b32 v116, v30 offset:3328
	ds_read_b32 v117, v30 offset:3584
	ds_read_b32 v118, v30 offset:3840
	ds_read_b32 v119, v30 offset:4096
	ds_read_b32 v120, v30 offset:4352
	ds_read_b32 v121, v30 offset:4608
	ds_read_b32 v122, v30 offset:4864
	ds_read_b32 v123, v30 offset:5120
	ds_read_b32 v124, v30 offset:5376
	ds_read_b32 v125, v30 offset:5632
	ds_read_b32 v126, v30 offset:5888
	ds_read_b32 v127, v30 offset:6144
	ds_read_b32 v128, v30 offset:6400
	ds_read_b32 v129, v30 offset:6656
	ds_read_b32 v130, v30 offset:6912
	ds_read_b32 v29, v30
	v_cmp_ne_u32_e64 s[0:1], 1, v3
	v_mov_b32_e32 v2, 0
	s_andn2_b64 vcc, exec, s[6:7]
	v_writelane_b32 v236, s0, 7
	v_mov_b32_e32 v5, 0
	s_nop 0
	v_writelane_b32 v236, s1, 8
	s_cbranch_vccnz .LBB0_450
	s_waitcnt lgkmcnt(0)
	v_mov_b32_e32 v3, v104
	v_cmp_ne_u32_e32 vcc, s65, v3
	s_nop 1
	v_cndmask_b32_e32 v3, 0, v3, vcc
	v_not_b32_e32 v4, v3
	v_cmp_gt_i32_e32 vcc, 0, v3
	s_nop 1
	v_cndmask_b32_e64 v5, -|v3|, v4, vcc
.LBB0_450:
	s_cmp_gt_u32 s8, 4
	s_cselect_b64 s[0:1], -1, 0
	v_writelane_b32 v236, s0, 5
	s_cmp_lt_u32 s8, 5
	s_nop 0
	v_writelane_b32 v236, s1, 6
	s_cbranch_scc1 .LBB0_452
	s_waitcnt lgkmcnt(0)
	v_mov_b32_e32 v2, v105
	v_cmp_ne_u32_e32 vcc, s65, v2
	s_nop 1
	v_cndmask_b32_e32 v2, 0, v2, vcc
	v_not_b32_e32 v3, v2
	v_cmp_gt_i32_e32 vcc, 0, v2
	s_nop 1
	v_cndmask_b32_e64 v2, -|v2|, v3, vcc
.LBB0_452:
	s_cmp_gt_u32 s8, 6
	s_cselect_b64 s[0:1], -1, 0
	v_mov_b32_e32 v3, 0
	v_writelane_b32 v236, s0, 3
	s_cmp_lt_u32 s8, 7
	v_mov_b32_e32 v7, 0
	v_writelane_b32 v236, s1, 4
	s_cbranch_scc1 .LBB0_454
	s_waitcnt lgkmcnt(0)
	v_mov_b32_e32 v4, v106
	v_cmp_ne_u32_e32 vcc, s65, v4
	s_nop 1
	v_cndmask_b32_e32 v4, 0, v4, vcc
	v_not_b32_e32 v6, v4
	v_cmp_gt_i32_e32 vcc, 0, v4
	s_nop 1
	v_cndmask_b32_e64 v7, -|v4|, v6, vcc
.LBB0_454:
	s_cmp_gt_u32 s8, 8
	s_cselect_b64 s[0:1], -1, 0
	v_writelane_b32 v236, s0, 1
	s_cmp_lt_u32 s8, 9
	s_nop 0
	v_writelane_b32 v236, s1, 2
	s_cbranch_scc1 .LBB0_456
	s_waitcnt lgkmcnt(0)
	v_mov_b32_e32 v3, v107
	v_cmp_ne_u32_e32 vcc, s65, v3
	s_nop 1
	v_cndmask_b32_e32 v3, 0, v3, vcc
	v_not_b32_e32 v4, v3
	v_cmp_gt_i32_e32 vcc, 0, v3
	s_nop 1
	v_cndmask_b32_e64 v3, -|v3|, v4, vcc
.LBB0_456:
	s_cmp_gt_u32 s8, 10
	v_mov_b32_e32 v4, 0
	s_cselect_b64 s[0:1], -1, 0
	s_cmp_lt_u32 s8, 11
	v_mov_b32_e32 v9, 0
	v_writelane_b32 v237, s0, 63
	s_nop 1
	v_writelane_b32 v236, s1, 0
	s_cbranch_scc1 .LBB0_458
	s_waitcnt lgkmcnt(0)
	v_mov_b32_e32 v6, v108
	v_cmp_ne_u32_e32 vcc, s65, v6
	s_nop 1
	v_cndmask_b32_e32 v6, 0, v6, vcc
	v_not_b32_e32 v8, v6
	v_cmp_gt_i32_e32 vcc, 0, v6
	s_nop 1
	v_cndmask_b32_e64 v9, -|v6|, v8, vcc
.LBB0_458:
	s_cmp_gt_u32 s8, 12
	s_cselect_b64 s[0:1], -1, 0
	v_writelane_b32 v237, s0, 61
	s_cmp_lt_u32 s8, 13
	s_nop 0
	v_writelane_b32 v237, s1, 62
	s_cbranch_scc1 .LBB0_460
	s_waitcnt lgkmcnt(0)
	v_mov_b32_e32 v4, v109
	v_cmp_ne_u32_e32 vcc, s65, v4
	s_nop 1
	v_cndmask_b32_e32 v4, 0, v4, vcc
	v_not_b32_e32 v6, v4
	v_cmp_gt_i32_e32 vcc, 0, v4
	s_nop 1
	v_cndmask_b32_e64 v4, -|v4|, v6, vcc
.LBB0_460:
	s_cmp_gt_u32 s8, 14
	s_cselect_b64 s[0:1], -1, 0
	v_mov_b32_e32 v6, 0
	v_writelane_b32 v237, s0, 59
	s_cmp_lt_u32 s8, 15
	v_mov_b32_e32 v11, 0
	v_writelane_b32 v237, s1, 60
	s_cbranch_scc1 .LBB0_462
	s_waitcnt lgkmcnt(0)
	v_mov_b32_e32 v8, v110
	v_cmp_ne_u32_e32 vcc, s65, v8
	s_nop 1
	v_cndmask_b32_e32 v8, 0, v8, vcc
	v_not_b32_e32 v10, v8
	v_cmp_gt_i32_e32 vcc, 0, v8
	s_nop 1
	v_cndmask_b32_e64 v11, -|v8|, v10, vcc
.LBB0_462:
	s_cmp_gt_u32 s8, 16
	s_cselect_b64 s[0:1], -1, 0
	v_writelane_b32 v237, s0, 57
	s_cmp_lt_u32 s8, 17
	s_nop 0
	v_writelane_b32 v237, s1, 58
	s_cbranch_scc1 .LBB0_464
	s_waitcnt lgkmcnt(0)
	v_mov_b32_e32 v6, v111
	v_cmp_ne_u32_e32 vcc, s65, v6
	s_nop 1
	v_cndmask_b32_e32 v6, 0, v6, vcc
	v_not_b32_e32 v8, v6
	v_cmp_gt_i32_e32 vcc, 0, v6
	s_nop 1
	v_cndmask_b32_e64 v6, -|v6|, v8, vcc
.LBB0_464:
	s_cmp_gt_u32 s8, 18
	s_cselect_b64 s[0:1], -1, 0
	v_mov_b32_e32 v8, 0
	v_writelane_b32 v237, s0, 55
	s_cmp_lt_u32 s8, 19
	v_mov_b32_e32 v13, 0
	v_writelane_b32 v237, s1, 56
	s_cbranch_scc1 .LBB0_466
	s_waitcnt lgkmcnt(0)
	v_mov_b32_e32 v10, v112
	v_cmp_ne_u32_e32 vcc, s65, v10
	s_nop 1
	v_cndmask_b32_e32 v10, 0, v10, vcc
	v_not_b32_e32 v12, v10
	v_cmp_gt_i32_e32 vcc, 0, v10
	s_nop 1
	v_cndmask_b32_e64 v13, -|v10|, v12, vcc
.LBB0_466:
	s_cmp_gt_u32 s8, 20
	s_cselect_b64 s[0:1], -1, 0
	v_writelane_b32 v237, s0, 53
	s_cmp_lt_u32 s8, 21
	s_nop 0
	v_writelane_b32 v237, s1, 54
	s_cbranch_scc1 .LBB0_468
	s_waitcnt lgkmcnt(0)
	v_mov_b32_e32 v8, v113
	v_cmp_ne_u32_e32 vcc, s65, v8
	s_nop 1
	v_cndmask_b32_e32 v8, 0, v8, vcc
	v_not_b32_e32 v10, v8
	v_cmp_gt_i32_e32 vcc, 0, v8
	s_nop 1
	v_cndmask_b32_e64 v8, -|v8|, v10, vcc
; template <int NJ>
; DI void b1_select(const float* sc, int nj, unsigned* mo) {
;     ...
; #pragma unroll
;   for (int j = 0; j < NJ; ++j) {
;     unsigned k = 0u;
;     if (j < nj) {
;       unsigned u = __float_as_uint(sc[64 * j + lane]);
;       u = (u == 0x80000000u) ? 0u : u;
;       k = (u & 0x80000000u) ? ~u : (u | 0x80000000u);
;     }
;     key[j] = k;
;   }
.LBB0_468:
	s_cmp_gt_u32 s8, 22
	s_cselect_b64 s[0:1], -1, 0
	v_mov_b32_e32 v10, 0
	v_writelane_b32 v237, s0, 51
	s_cmp_lt_u32 s8, 23
	v_mov_b32_e32 v15, 0
	v_writelane_b32 v237, s1, 52
	s_cbranch_scc1 .LBB0_470
	s_waitcnt lgkmcnt(0)
	v_mov_b32_e32 v12, v114
	v_cmp_ne_u32_e32 vcc, s65, v12
	s_nop 1
	v_cndmask_b32_e32 v12, 0, v12, vcc
	v_not_b32_e32 v14, v12
	v_cmp_gt_i32_e32 vcc, 0, v12
	s_nop 1
	v_cndmask_b32_e64 v15, -|v12|, v14, vcc
.LBB0_470:
	s_cmp_gt_u32 s8, 24
	s_cselect_b64 s[0:1], -1, 0
	v_writelane_b32 v237, s0, 49
	s_cmp_lt_u32 s8, 25
	s_nop 0
	v_writelane_b32 v237, s1, 50
	s_cbranch_scc1 .LBB0_472
	s_waitcnt lgkmcnt(0)
	v_mov_b32_e32 v10, v115
	v_cmp_ne_u32_e32 vcc, s65, v10
	s_nop 1
	v_cndmask_b32_e32 v10, 0, v10, vcc
	v_not_b32_e32 v12, v10
	v_cmp_gt_i32_e32 vcc, 0, v10
	s_nop 1
	v_cndmask_b32_e64 v10, -|v10|, v12, vcc
.LBB0_472:
	s_cmp_gt_u32 s8, 26
	s_cselect_b64 s[0:1], -1, 0
	v_mov_b32_e32 v12, 0
	v_writelane_b32 v237, s0, 23
	s_cmp_lt_u32 s8, 27
	v_mov_b32_e32 v17, 0
	v_writelane_b32 v237, s1, 24
	s_cbranch_scc1 .LBB0_474
	s_waitcnt lgkmcnt(0)
	v_mov_b32_e32 v14, v116
	v_cmp_ne_u32_e32 vcc, s65, v14
	s_nop 1
	v_cndmask_b32_e32 v14, 0, v14, vcc
	v_not_b32_e32 v16, v14
	v_cmp_gt_i32_e32 vcc, 0, v14
	s_nop 1
	v_cndmask_b32_e64 v17, -|v14|, v16, vcc
.LBB0_474:
	s_cmp_gt_u32 s8, 28
	s_cselect_b64 s[0:1], -1, 0
	v_writelane_b32 v237, s0, 47
	s_cmp_lt_u32 s8, 29
	s_nop 0
	v_writelane_b32 v237, s1, 48
	s_cbranch_scc1 .LBB0_476
	s_waitcnt lgkmcnt(0)
	v_mov_b32_e32 v12, v117
	v_cmp_ne_u32_e32 vcc, s65, v12
	s_nop 1
	v_cndmask_b32_e32 v12, 0, v12, vcc
	v_not_b32_e32 v14, v12
	v_cmp_gt_i32_e32 vcc, 0, v12
	s_nop 1
	v_cndmask_b32_e64 v12, -|v12|, v14, vcc
.LBB0_476:
	s_cmp_gt_u32 s8, 30
	s_cselect_b64 s[0:1], -1, 0
	v_mov_b32_e32 v14, 0
	v_writelane_b32 v237, s0, 45
	s_cmp_lt_u32 s8, 31
	v_mov_b32_e32 v19, 0
	v_writelane_b32 v237, s1, 46
	s_cbranch_scc1 .LBB0_478
	s_waitcnt lgkmcnt(0)
	v_mov_b32_e32 v16, v118
	v_cmp_ne_u32_e32 vcc, s65, v16
	s_nop 1
	v_cndmask_b32_e32 v16, 0, v16, vcc
	v_not_b32_e32 v18, v16
	v_cmp_gt_i32_e32 vcc, 0, v16
	s_nop 1
	v_cndmask_b32_e64 v19, -|v16|, v18, vcc
.LBB0_478:
	s_cmp_gt_u32 s8, 32
	s_cselect_b64 s[0:1], -1, 0
	v_writelane_b32 v237, s0, 43
	s_cmp_lt_u32 s8, 33
	s_nop 0
	v_writelane_b32 v237, s1, 44
	s_cbranch_scc1 .LBB0_480
	s_waitcnt lgkmcnt(0)
	v_mov_b32_e32 v14, v119
	v_cmp_ne_u32_e32 vcc, s65, v14
	s_nop 1
	v_cndmask_b32_e32 v14, 0, v14, vcc
	v_not_b32_e32 v16, v14
	v_cmp_gt_i32_e32 vcc, 0, v14
	s_nop 1
	v_cndmask_b32_e64 v14, -|v14|, v16, vcc
.LBB0_480:
	s_cmp_gt_u32 s8, 34
	s_cselect_b64 s[0:1], -1, 0
	v_mov_b32_e32 v16, 0
	v_writelane_b32 v237, s0, 41
	s_cmp_lt_u32 s8, 35
	v_mov_b32_e32 v21, 0
	v_writelane_b32 v237, s1, 42
	s_cbranch_scc1 .LBB0_482
	s_waitcnt lgkmcnt(0)
	v_mov_b32_e32 v18, v120
	v_cmp_ne_u32_e32 vcc, s65, v18
	s_nop 1
	v_cndmask_b32_e32 v18, 0, v18, vcc
	v_not_b32_e32 v20, v18
	v_cmp_gt_i32_e32 vcc, 0, v18
	s_nop 1
	v_cndmask_b32_e64 v21, -|v18|, v20, vcc
.LBB0_482:
	s_cmp_gt_u32 s8, 36
	s_cselect_b64 s[0:1], -1, 0
	v_writelane_b32 v237, s0, 39
	s_cmp_lt_u32 s8, 37
	s_nop 0
	v_writelane_b32 v237, s1, 40
	s_cbranch_scc1 .LBB0_484
	s_waitcnt lgkmcnt(0)
	v_mov_b32_e32 v16, v121
	v_cmp_ne_u32_e32 vcc, s65, v16
	s_nop 1
	v_cndmask_b32_e32 v16, 0, v16, vcc
	v_not_b32_e32 v18, v16
	v_cmp_gt_i32_e32 vcc, 0, v16
	s_nop 1
	v_cndmask_b32_e64 v16, -|v16|, v18, vcc
.LBB0_484:
	s_cmp_gt_u32 s8, 38
	s_cselect_b64 s[0:1], -1, 0
	v_mov_b32_e32 v18, 0
	v_writelane_b32 v237, s0, 35
	s_cmp_lt_u32 s8, 39
	v_mov_b32_e32 v23, 0
	v_writelane_b32 v237, s1, 36
	s_cbranch_scc1 .LBB0_486
	s_waitcnt lgkmcnt(0)
	v_mov_b32_e32 v20, v122
	v_cmp_ne_u32_e32 vcc, s65, v20
	s_nop 1
	v_cndmask_b32_e32 v20, 0, v20, vcc
	v_not_b32_e32 v22, v20
	v_cmp_gt_i32_e32 vcc, 0, v20
	s_nop 1
	v_cndmask_b32_e64 v23, -|v20|, v22, vcc
; template <int NJ>
; DI void b1_select(const float* sc, int nj, unsigned* mo) {
;     ...
; #pragma unroll
;   for (int j = 0; j < NJ; ++j) {
;     unsigned k = 0u;
;     if (j < nj) {
;       unsigned u = __float_as_uint(sc[64 * j + lane]);
;       u = (u == 0x80000000u) ? 0u : u;
;       k = (u & 0x80000000u) ? ~u : (u | 0x80000000u);
;     }
;     key[j] = k;
;   }
.LBB0_486:
	s_cmp_gt_u32 s8, 40
	s_cselect_b64 s[0:1], -1, 0
	v_writelane_b32 v237, s0, 33
	s_cmp_lt_u32 s8, 41
	s_nop 0
	v_writelane_b32 v237, s1, 34
	s_cbranch_scc1 .LBB0_488
	s_waitcnt lgkmcnt(0)
	v_mov_b32_e32 v18, v123
	v_cmp_ne_u32_e32 vcc, s65, v18
	s_nop 1
	v_cndmask_b32_e32 v18, 0, v18, vcc
	v_not_b32_e32 v20, v18
	v_cmp_gt_i32_e32 vcc, 0, v18
	s_nop 1
	v_cndmask_b32_e64 v18, -|v18|, v20, vcc
.LBB0_488:
	s_cmp_gt_u32 s8, 42
	s_cselect_b64 s[0:1], -1, 0
	v_mov_b32_e32 v20, 0
	v_writelane_b32 v237, s0, 31
	s_cmp_lt_u32 s8, 43
	v_mov_b32_e32 v25, 0
	v_writelane_b32 v237, s1, 32
	s_cbranch_scc1 .LBB0_490
	s_waitcnt lgkmcnt(0)
	v_mov_b32_e32 v22, v124
	v_cmp_ne_u32_e32 vcc, s65, v22
	s_nop 1
	v_cndmask_b32_e32 v22, 0, v22, vcc
	v_not_b32_e32 v24, v22
	v_cmp_gt_i32_e32 vcc, 0, v22
	s_nop 1
	v_cndmask_b32_e64 v25, -|v22|, v24, vcc
.LBB0_490:
	s_cmp_gt_u32 s8, 44
	s_cselect_b64 s[0:1], -1, 0
	v_writelane_b32 v237, s0, 37
	s_cmp_lt_u32 s8, 45
	s_nop 0
	v_writelane_b32 v237, s1, 38
	s_cbranch_scc1 .LBB0_492
	s_waitcnt lgkmcnt(0)
	v_mov_b32_e32 v20, v125
	v_cmp_ne_u32_e32 vcc, s65, v20
	s_nop 1
	v_cndmask_b32_e32 v20, 0, v20, vcc
	v_not_b32_e32 v22, v20
	v_cmp_gt_i32_e32 vcc, 0, v20
	s_nop 1
	v_cndmask_b32_e64 v20, -|v20|, v22, vcc
.LBB0_492:
	s_cmp_gt_u32 s8, 46
	s_cselect_b64 s[0:1], -1, 0
	v_mov_b32_e32 v22, 0
	v_writelane_b32 v237, s0, 29
	s_cmp_lt_u32 s8, 47
	v_mov_b32_e32 v26, 0
	v_writelane_b32 v237, s1, 30
	s_cbranch_scc1 .LBB0_494
	s_waitcnt lgkmcnt(0)
	v_mov_b32_e32 v24, v126
	v_cmp_ne_u32_e32 vcc, s65, v24
	s_nop 1
	v_cndmask_b32_e32 v24, 0, v24, vcc
	v_not_b32_e32 v26, v24
	v_cmp_gt_i32_e32 vcc, 0, v24
	s_nop 1
	v_cndmask_b32_e64 v26, -|v24|, v26, vcc
.LBB0_494:
	s_cmp_gt_u32 s8, 48
	s_cselect_b64 s[0:1], -1, 0
	v_writelane_b32 v237, s0, 27
	s_cmp_lt_u32 s8, 49
	s_nop 0
	v_writelane_b32 v237, s1, 28
	s_cbranch_scc1 .LBB0_496
	s_waitcnt lgkmcnt(0)
	v_mov_b32_e32 v22, v127
	v_cmp_ne_u32_e32 vcc, s65, v22
	s_nop 1
	v_cndmask_b32_e32 v22, 0, v22, vcc
	v_not_b32_e32 v24, v22
	v_cmp_gt_i32_e32 vcc, 0, v22
	s_nop 1
	v_cndmask_b32_e64 v22, -|v22|, v24, vcc
.LBB0_496:
	s_cmp_gt_u32 s8, 50
	s_cselect_b64 s[0:1], -1, 0
	v_mov_b32_e32 v24, 0
	v_writelane_b32 v237, s0, 25
	s_cmp_lt_u32 s8, 51
	v_mov_b32_e32 v27, 0
	v_writelane_b32 v237, s1, 26
	s_cbranch_scc1 .LBB0_498
	s_waitcnt lgkmcnt(0)
	v_mov_b32_e32 v27, v128
	v_cmp_ne_u32_e32 vcc, s65, v27
	s_nop 1
	v_cndmask_b32_e32 v27, 0, v27, vcc
	v_not_b32_e32 v28, v27
	v_cmp_gt_i32_e32 vcc, 0, v27
	s_nop 1
	v_cndmask_b32_e64 v27, -|v27|, v28, vcc
.LBB0_498:
	s_cmp_gt_u32 s8, 52
	s_cselect_b64 s[0:1], -1, 0
	v_writelane_b32 v236, s0, 11
	s_cmp_lt_u32 s8, 53
	s_nop 0
	v_writelane_b32 v236, s1, 12
	s_cbranch_scc1 .LBB0_500
	s_waitcnt lgkmcnt(0)
	v_mov_b32_e32 v24, v129
	v_cmp_ne_u32_e32 vcc, s65, v24
	s_nop 1
	v_cndmask_b32_e32 v24, 0, v24, vcc
	v_not_b32_e32 v28, v24
	v_cmp_gt_i32_e32 vcc, 0, v24
	s_nop 1
	v_cndmask_b32_e64 v24, -|v24|, v28, vcc
.LBB0_500:
	v_writelane_b32 v237, s6, 17
	s_cmp_gt_u32 s8, 54
	s_cselect_b64 s[0:1], -1, 0
	v_writelane_b32 v237, s7, 18
	v_writelane_b32 v237, s0, 21
	s_cmp_lt_u32 s8, 55
	v_mov_b32_e32 v28, 0
	v_writelane_b32 v237, s1, 22
	s_cbranch_scc1 .LBB0_502
	s_waitcnt lgkmcnt(0)
	v_mov_b32_e32 v28, v130
	v_cmp_ne_u32_e32 vcc, s65, v28
	s_nop 1
	v_cndmask_b32_e32 v28, 0, v28, vcc
	v_not_b32_e32 v30, v28
	v_cmp_gt_i32_e32 vcc, 0, v28
	s_nop 1
	v_cndmask_b32_e64 v28, -|v28|, v30, vcc

; template <int NJ>
; DI void b1_select(const float* sc, int nj, unsigned* mo) {
;     ...
; #pragma unroll
;   for (int j = 0; j < NJ; ++j) {
;     unsigned k = 0u;
;     if (j < nj) {
;       unsigned u = __float_as_uint(sc[64 * j + lane]);
;       u = (u == 0x80000000u) ? 0u : u;
;       k = (u & 0x80000000u) ? ~u : (u | 0x80000000u);
;     }
;     key[j] = k;
;   }
.LBB0_513:
	s_or_b64 exec, exec, s[60:61]
	v_mov_b32_e32 v0, v158
	v_readlane_b32 s0, v238, 63
	v_and_b32_e32 v0, 63, v0
	v_mov_b32_e32 v2, 0
	v_lshl_add_u32 v30, v0, 2, s0
	ds_read_b32 v104, v30 offset:8448
	ds_read_b32 v105, v30 offset:8704
	ds_read_b32 v106, v30 offset:8960
	ds_read_b32 v107, v30 offset:9216
	ds_read_b32 v108, v30 offset:9472
	ds_read_b32 v109, v30 offset:9728
	ds_read_b32 v110, v30 offset:9984
	ds_read_b32 v111, v30 offset:10240
	ds_read_b32 v112, v30 offset:10496
	ds_read_b32 v113, v30 offset:10752
	ds_read_b32 v114, v30 offset:11008
	ds_read_b32 v115, v30 offset:11264
	ds_read_b32 v116, v30 offset:11520
	ds_read_b32 v117, v30 offset:11776
	ds_read_b32 v118, v30 offset:12032
	ds_read_b32 v119, v30 offset:12288
	ds_read_b32 v120, v30 offset:12544
	ds_read_b32 v121, v30 offset:12800
	ds_read_b32 v122, v30 offset:13056
	ds_read_b32 v123, v30 offset:13312
	ds_read_b32 v124, v30 offset:13568
	ds_read_b32 v125, v30 offset:13824
	ds_read_b32 v126, v30 offset:14080
	ds_read_b32 v127, v30 offset:14336
	ds_read_b32 v128, v30 offset:14592
	ds_read_b32 v129, v30 offset:14848
	ds_read_b32 v130, v30 offset:15104
	ds_read_b32 v29, v30 offset:8192
	v_readlane_b32 s0, v236, 7
	v_readlane_b32 s1, v236, 8
	s_and_b64 vcc, exec, s[0:1]
	v_mov_b32_e32 v5, 0
	s_brev_b32 s0, 1
	s_cbranch_vccnz .LBB0_515
	s_waitcnt lgkmcnt(0)
	v_mov_b32_e32 v3, v104
	v_cmp_ne_u32_e32 vcc, s0, v3
	s_nop 1
	v_cndmask_b32_e32 v3, 0, v3, vcc
	v_not_b32_e32 v4, v3
	v_cmp_gt_i32_e32 vcc, 0, v3
	s_nop 1
	v_cndmask_b32_e64 v5, -|v3|, v4, vcc
.LBB0_515:
	v_readlane_b32 s2, v236, 5
	v_readlane_b32 s3, v236, 6
	s_andn2_b64 vcc, exec, s[2:3]
	s_cbranch_vccnz .LBB0_517
	s_waitcnt lgkmcnt(0)
	v_mov_b32_e32 v2, v105
	v_cmp_ne_u32_e32 vcc, s0, v2
	s_nop 1
	v_cndmask_b32_e32 v2, 0, v2, vcc
	v_not_b32_e32 v3, v2
	v_cmp_gt_i32_e32 vcc, 0, v2
	s_nop 1
	v_cndmask_b32_e64 v2, -|v2|, v3, vcc
.LBB0_517:
	v_readlane_b32 s2, v236, 3
	v_readlane_b32 s3, v236, 4
	v_mov_b32_e32 v3, 0
	s_andn2_b64 vcc, exec, s[2:3]
	v_mov_b32_e32 v7, 0
	s_cbranch_vccnz .LBB0_519
	s_waitcnt lgkmcnt(0)
	v_mov_b32_e32 v4, v106
	v_cmp_ne_u32_e32 vcc, s0, v4
	s_nop 1
	v_cndmask_b32_e32 v4, 0, v4, vcc
	v_not_b32_e32 v6, v4
	v_cmp_gt_i32_e32 vcc, 0, v4
	s_nop 1
	v_cndmask_b32_e64 v7, -|v4|, v6, vcc
.LBB0_519:
	v_readlane_b32 s2, v236, 1
	v_readlane_b32 s3, v236, 2
	s_andn2_b64 vcc, exec, s[2:3]
	s_cbranch_vccnz .LBB0_521
	s_waitcnt lgkmcnt(0)
	v_mov_b32_e32 v3, v107
	v_cmp_ne_u32_e32 vcc, s0, v3
	s_nop 1
	v_cndmask_b32_e32 v3, 0, v3, vcc
	v_not_b32_e32 v4, v3
	v_cmp_gt_i32_e32 vcc, 0, v3
	s_nop 1
	v_cndmask_b32_e64 v3, -|v3|, v4, vcc
.LBB0_521:
	v_readlane_b32 s2, v237, 63
	v_readlane_b32 s3, v236, 0
	v_mov_b32_e32 v4, 0
	s_andn2_b64 vcc, exec, s[2:3]
	v_mov_b32_e32 v9, 0
	s_cbranch_vccnz .LBB0_523
	s_waitcnt lgkmcnt(0)
	v_mov_b32_e32 v6, v108
	v_cmp_ne_u32_e32 vcc, s0, v6
	s_nop 1
	v_cndmask_b32_e32 v6, 0, v6, vcc
	v_not_b32_e32 v8, v6
	v_cmp_gt_i32_e32 vcc, 0, v6
	s_nop 1
	v_cndmask_b32_e64 v9, -|v6|, v8, vcc
.LBB0_523:
	v_readlane_b32 s2, v237, 61
	v_readlane_b32 s3, v237, 62
	s_andn2_b64 vcc, exec, s[2:3]
	s_cbranch_vccnz .LBB0_525
	s_waitcnt lgkmcnt(0)
	v_mov_b32_e32 v4, v109
	v_cmp_ne_u32_e32 vcc, s0, v4
	s_nop 1
	v_cndmask_b32_e32 v4, 0, v4, vcc
	v_not_b32_e32 v6, v4
	v_cmp_gt_i32_e32 vcc, 0, v4
	s_nop 1
	v_cndmask_b32_e64 v4, -|v4|, v6, vcc
.LBB0_525:
	v_readlane_b32 s2, v237, 59
	v_readlane_b32 s3, v237, 60
	v_mov_b32_e32 v6, 0
	s_andn2_b64 vcc, exec, s[2:3]
	v_mov_b32_e32 v11, 0
	s_cbranch_vccnz .LBB0_527
	s_waitcnt lgkmcnt(0)
	v_mov_b32_e32 v8, v110
	v_cmp_ne_u32_e32 vcc, s0, v8
	s_nop 1
	v_cndmask_b32_e32 v8, 0, v8, vcc
	v_not_b32_e32 v10, v8
	v_cmp_gt_i32_e32 vcc, 0, v8
	s_nop 1
	v_cndmask_b32_e64 v11, -|v8|, v10, vcc
.LBB0_527:
	v_readlane_b32 s2, v237, 57
	v_readlane_b32 s3, v237, 58
	s_andn2_b64 vcc, exec, s[2:3]
	s_cbranch_vccnz .LBB0_529
	s_waitcnt lgkmcnt(0)
	v_mov_b32_e32 v6, v111
	v_cmp_ne_u32_e32 vcc, s0, v6
	s_nop 1
	v_cndmask_b32_e32 v6, 0, v6, vcc
	v_not_b32_e32 v8, v6
	v_cmp_gt_i32_e32 vcc, 0, v6
	s_nop 1
	v_cndmask_b32_e64 v6, -|v6|, v8, vcc
.LBB0_529:
	v_readlane_b32 s2, v237, 55
	v_readlane_b32 s3, v237, 56
	v_mov_b32_e32 v8, 0
	s_andn2_b64 vcc, exec, s[2:3]
	v_mov_b32_e32 v13, 0
	s_cbranch_vccnz .LBB0_531
	s_waitcnt lgkmcnt(0)
	v_mov_b32_e32 v10, v112
	v_cmp_ne_u32_e32 vcc, s0, v10
	s_nop 1
	v_cndmask_b32_e32 v10, 0, v10, vcc
	v_not_b32_e32 v12, v10
	v_cmp_gt_i32_e32 vcc, 0, v10
	s_nop 1
	v_cndmask_b32_e64 v13, -|v10|, v12, vcc
.LBB0_531:
	v_readlane_b32 s2, v237, 53
	v_readlane_b32 s3, v237, 54
	s_andn2_b64 vcc, exec, s[2:3]
	s_cbranch_vccnz .LBB0_533
	s_waitcnt lgkmcnt(0)
	v_mov_b32_e32 v8, v113
	v_cmp_ne_u32_e32 vcc, s0, v8
	s_nop 1
	v_cndmask_b32_e32 v8, 0, v8, vcc
	v_not_b32_e32 v10, v8
	v_cmp_gt_i32_e32 vcc, 0, v8
	s_nop 1
	v_cndmask_b32_e64 v8, -|v8|, v10, vcc
.LBB0_533:
	v_readlane_b32 s2, v237, 51
	v_readlane_b32 s3, v237, 52
	v_mov_b32_e32 v10, 0
	s_andn2_b64 vcc, exec, s[2:3]
	v_mov_b32_e32 v15, 0
	s_cbranch_vccnz .LBB0_535
	s_waitcnt lgkmcnt(0)
	v_mov_b32_e32 v12, v114
	v_cmp_ne_u32_e32 vcc, s0, v12
	s_nop 1
	v_cndmask_b32_e32 v12, 0, v12, vcc
	v_not_b32_e32 v14, v12
	v_cmp_gt_i32_e32 vcc, 0, v12
	s_nop 1
	v_cndmask_b32_e64 v15, -|v12|, v14, vcc
.LBB0_535:
	v_readlane_b32 s2, v237, 49
	v_readlane_b32 s3, v237, 50
	s_andn2_b64 vcc, exec, s[2:3]
	s_cbranch_vccnz .LBB0_537
	s_waitcnt lgkmcnt(0)
	v_mov_b32_e32 v10, v115
	v_cmp_ne_u32_e32 vcc, s0, v10
	s_nop 1
	v_cndmask_b32_e32 v10, 0, v10, vcc
	v_not_b32_e32 v12, v10
	v_cmp_gt_i32_e32 vcc, 0, v10
	s_nop 1
	v_cndmask_b32_e64 v10, -|v10|, v12, vcc
; template <int NJ>
; DI void b1_select(const float* sc, int nj, unsigned* mo) {
;     ...
; #pragma unroll
;   for (int j = 0; j < NJ; ++j) {
;     unsigned k = 0u;
;     if (j < nj) {
;       unsigned u = __float_as_uint(sc[64 * j + lane]);
;       u = (u == 0x80000000u) ? 0u : u;
;       k = (u & 0x80000000u) ? ~u : (u | 0x80000000u);
;     }
;     key[j] = k;
;   }
.LBB0_537:
	v_readlane_b32 s2, v237, 23
	v_readlane_b32 s3, v237, 24
	v_mov_b32_e32 v12, 0
	s_andn2_b64 vcc, exec, s[2:3]
	v_mov_b32_e32 v17, 0
	s_cbranch_vccnz .LBB0_539
	s_waitcnt lgkmcnt(0)
	v_mov_b32_e32 v14, v116
	v_cmp_ne_u32_e32 vcc, s0, v14
	s_nop 1
	v_cndmask_b32_e32 v14, 0, v14, vcc
	v_not_b32_e32 v16, v14
	v_cmp_gt_i32_e32 vcc, 0, v14
	s_nop 1
	v_cndmask_b32_e64 v17, -|v14|, v16, vcc
.LBB0_539:
	v_readlane_b32 s2, v237, 47
	v_readlane_b32 s3, v237, 48
	s_andn2_b64 vcc, exec, s[2:3]
	s_cbranch_vccnz .LBB0_541
	s_waitcnt lgkmcnt(0)
	v_mov_b32_e32 v12, v117
	v_cmp_ne_u32_e32 vcc, s0, v12
	s_nop 1
	v_cndmask_b32_e32 v12, 0, v12, vcc
	v_not_b32_e32 v14, v12
	v_cmp_gt_i32_e32 vcc, 0, v12
	s_nop 1
	v_cndmask_b32_e64 v12, -|v12|, v14, vcc
.LBB0_541:
	v_readlane_b32 s2, v237, 45
	v_readlane_b32 s3, v237, 46
	v_mov_b32_e32 v14, 0
	s_andn2_b64 vcc, exec, s[2:3]
	v_mov_b32_e32 v19, 0
	s_cbranch_vccnz .LBB0_543
	s_waitcnt lgkmcnt(0)
	v_mov_b32_e32 v16, v118
	v_cmp_ne_u32_e32 vcc, s0, v16
	s_nop 1
	v_cndmask_b32_e32 v16, 0, v16, vcc
	v_not_b32_e32 v18, v16
	v_cmp_gt_i32_e32 vcc, 0, v16
	s_nop 1
	v_cndmask_b32_e64 v19, -|v16|, v18, vcc
.LBB0_543:
	v_readlane_b32 s2, v237, 43
	v_readlane_b32 s3, v237, 44
	s_andn2_b64 vcc, exec, s[2:3]
	s_cbranch_vccnz .LBB0_545
	s_waitcnt lgkmcnt(0)
	v_mov_b32_e32 v14, v119
	v_cmp_ne_u32_e32 vcc, s0, v14
	s_nop 1
	v_cndmask_b32_e32 v14, 0, v14, vcc
	v_not_b32_e32 v16, v14
	v_cmp_gt_i32_e32 vcc, 0, v14
	s_nop 1
	v_cndmask_b32_e64 v14, -|v14|, v16, vcc
.LBB0_545:
	v_readlane_b32 s2, v237, 41
	v_readlane_b32 s3, v237, 42
	v_mov_b32_e32 v16, 0
	s_andn2_b64 vcc, exec, s[2:3]
	v_mov_b32_e32 v21, 0
	s_cbranch_vccnz .LBB0_547
	s_waitcnt lgkmcnt(0)
	v_mov_b32_e32 v18, v120
	v_cmp_ne_u32_e32 vcc, s0, v18
	s_nop 1
	v_cndmask_b32_e32 v18, 0, v18, vcc
	v_not_b32_e32 v20, v18
	v_cmp_gt_i32_e32 vcc, 0, v18
	s_nop 1
	v_cndmask_b32_e64 v21, -|v18|, v20, vcc
.LBB0_547:
	v_readlane_b32 s2, v237, 39
	v_readlane_b32 s3, v237, 40
	s_andn2_b64 vcc, exec, s[2:3]
	s_cbranch_vccnz .LBB0_549
	s_waitcnt lgkmcnt(0)
	v_mov_b32_e32 v16, v121
	v_cmp_ne_u32_e32 vcc, s0, v16
	s_nop 1
	v_cndmask_b32_e32 v16, 0, v16, vcc
	v_not_b32_e32 v18, v16
	v_cmp_gt_i32_e32 vcc, 0, v16
	s_nop 1
	v_cndmask_b32_e64 v16, -|v16|, v18, vcc
.LBB0_549:
	v_readlane_b32 s2, v237, 35
	v_readlane_b32 s3, v237, 36
	v_mov_b32_e32 v18, 0
	s_andn2_b64 vcc, exec, s[2:3]
	v_mov_b32_e32 v23, 0
	s_cbranch_vccnz .LBB0_551
	s_waitcnt lgkmcnt(0)
	v_mov_b32_e32 v20, v122
	v_cmp_ne_u32_e32 vcc, s0, v20
	s_nop 1
	v_cndmask_b32_e32 v20, 0, v20, vcc
	v_not_b32_e32 v22, v20
	v_cmp_gt_i32_e32 vcc, 0, v20
	s_nop 1
	v_cndmask_b32_e64 v23, -|v20|, v22, vcc
.LBB0_551:
	v_readlane_b32 s2, v237, 33
	v_readlane_b32 s3, v237, 34
	s_andn2_b64 vcc, exec, s[2:3]
	s_cbranch_vccnz .LBB0_553
	s_waitcnt lgkmcnt(0)
	v_mov_b32_e32 v18, v123
	v_cmp_ne_u32_e32 vcc, s0, v18
	s_nop 1
	v_cndmask_b32_e32 v18, 0, v18, vcc
	v_not_b32_e32 v20, v18
	v_cmp_gt_i32_e32 vcc, 0, v18
	s_nop 1
	v_cndmask_b32_e64 v18, -|v18|, v20, vcc
.LBB0_553:
	v_readlane_b32 s2, v237, 31
	v_readlane_b32 s3, v237, 32
	v_mov_b32_e32 v20, 0
	s_andn2_b64 vcc, exec, s[2:3]
	v_mov_b32_e32 v25, 0
	s_cbranch_vccnz .LBB0_555
	s_waitcnt lgkmcnt(0)
	v_mov_b32_e32 v22, v124
	v_cmp_ne_u32_e32 vcc, s0, v22
	s_nop 1
	v_cndmask_b32_e32 v22, 0, v22, vcc
	v_not_b32_e32 v24, v22
	v_cmp_gt_i32_e32 vcc, 0, v22
	s_nop 1
	v_cndmask_b32_e64 v25, -|v22|, v24, vcc
.LBB0_555:
	v_readlane_b32 s2, v237, 37
	v_readlane_b32 s3, v237, 38
	s_andn2_b64 vcc, exec, s[2:3]
	s_cbranch_vccnz .LBB0_557
	s_waitcnt lgkmcnt(0)
	v_mov_b32_e32 v20, v125
	v_cmp_ne_u32_e32 vcc, s0, v20
	s_nop 1
	v_cndmask_b32_e32 v20, 0, v20, vcc
	v_not_b32_e32 v22, v20
	v_cmp_gt_i32_e32 vcc, 0, v20
	s_nop 1
	v_cndmask_b32_e64 v20, -|v20|, v22, vcc
.LBB0_557:
	v_readlane_b32 s2, v237, 29
	v_readlane_b32 s3, v237, 30
	v_mov_b32_e32 v22, 0
	s_andn2_b64 vcc, exec, s[2:3]
	v_mov_b32_e32 v26, 0
	s_cbranch_vccnz .LBB0_559
	s_waitcnt lgkmcnt(0)
	v_mov_b32_e32 v24, v126
	v_cmp_ne_u32_e32 vcc, s0, v24
	s_nop 1
	v_cndmask_b32_e32 v24, 0, v24, vcc
	v_not_b32_e32 v26, v24
	v_cmp_gt_i32_e32 vcc, 0, v24
	s_nop 1
	v_cndmask_b32_e64 v26, -|v24|, v26, vcc
.LBB0_559:
	v_readlane_b32 s2, v237, 27
	v_readlane_b32 s3, v237, 28
	s_andn2_b64 vcc, exec, s[2:3]
	s_cbranch_vccnz .LBB0_561
	s_waitcnt lgkmcnt(0)
	v_mov_b32_e32 v22, v127
	v_cmp_ne_u32_e32 vcc, s0, v22
	s_nop 1
	v_cndmask_b32_e32 v22, 0, v22, vcc
	v_not_b32_e32 v24, v22
	v_cmp_gt_i32_e32 vcc, 0, v22
	s_nop 1
	v_cndmask_b32_e64 v22, -|v22|, v24, vcc
.LBB0_561:
	v_readlane_b32 s2, v237, 25
	v_readlane_b32 s3, v237, 26
	v_mov_b32_e32 v24, 0
	s_andn2_b64 vcc, exec, s[2:3]
	v_mov_b32_e32 v28, 0
	s_cbranch_vccnz .LBB0_563
	s_waitcnt lgkmcnt(0)
	v_mov_b32_e32 v27, v128
	v_cmp_ne_u32_e32 vcc, s0, v27
	s_nop 1
	v_cndmask_b32_e32 v27, 0, v27, vcc
	v_not_b32_e32 v28, v27
	v_cmp_gt_i32_e32 vcc, 0, v27
	s_nop 1
	v_cndmask_b32_e64 v28, -|v27|, v28, vcc
.LBB0_563:
	v_readlane_b32 s2, v236, 11
	v_readlane_b32 s3, v236, 12
	s_andn2_b64 vcc, exec, s[2:3]
	s_cbranch_vccnz .LBB0_565
	s_waitcnt lgkmcnt(0)
	v_mov_b32_e32 v24, v129
	v_cmp_ne_u32_e32 vcc, s0, v24
	s_nop 1
	v_cndmask_b32_e32 v24, 0, v24, vcc
	v_not_b32_e32 v27, v24
	v_cmp_gt_i32_e32 vcc, 0, v24
	s_nop 1
	v_cndmask_b32_e64 v24, -|v24|, v27, vcc
.LBB0_565:
	v_readlane_b32 s2, v237, 21
	v_readlane_b32 s3, v237, 22
	v_mov_b32_e32 v27, 0
	s_andn2_b64 vcc, exec, s[2:3]
	s_cbranch_vccnz .LBB0_567
	s_waitcnt lgkmcnt(0)
	v_mov_b32_e32 v27, v130
	v_cmp_ne_u32_e32 vcc, s0, v27
	s_nop 1
	v_cndmask_b32_e32 v27, 0, v27, vcc
	v_not_b32_e32 v30, v27
	v_cmp_gt_i32_e32 vcc, 0, v27
	s_nop 1
	v_cndmask_b32_e64 v27, -|v27|, v30, vcc

; template <int NJ>
; DI void b1_select(const float* sc, int nj, unsigned* mo) {
;     ...
; #pragma unroll
;   for (int j = 0; j < NJ; ++j) {
;     unsigned k = 0u;
;     if (j < nj) {
;       unsigned u = __float_as_uint(sc[64 * j + lane]);
;       u = (u == 0x80000000u) ? 0u : u;
;       k = (u & 0x80000000u) ? ~u : (u | 0x80000000u);
;     }
;     key[j] = k;
;   }
.LBB0_580:
	s_and_b64 vcc, exec, s[0:1]
	s_cbranch_vccz .LBB0_696
	v_mov_b32_e32 v0, v158
	v_readlane_b32 s0, v238, 63
	v_and_b32_e32 v0, 63, v0
	v_cndmask_b32_e64 v3, 0, 1, s[6:7]
	v_lshl_add_u32 v26, v0, 2, s0
	ds_read_b32 v104, v26 offset:256
	ds_read_b32 v105, v26 offset:512
	ds_read_b32 v106, v26 offset:768
	ds_read_b32 v107, v26 offset:1024
	ds_read_b32 v108, v26 offset:1280
	ds_read_b32 v109, v26 offset:1536
	ds_read_b32 v110, v26 offset:1792
	ds_read_b32 v111, v26 offset:2048
	ds_read_b32 v112, v26 offset:2304
	ds_read_b32 v113, v26 offset:2560
	ds_read_b32 v114, v26 offset:2816
	ds_read_b32 v115, v26 offset:3072
	ds_read_b32 v116, v26 offset:3328
	ds_read_b32 v117, v26 offset:3584
	ds_read_b32 v118, v26 offset:3840
	ds_read_b32 v119, v26 offset:4096
	ds_read_b32 v120, v26 offset:4352
	ds_read_b32 v121, v26 offset:4608
	ds_read_b32 v122, v26 offset:4864
	ds_read_b32 v123, v26 offset:5120
	ds_read_b32 v124, v26 offset:5376
	ds_read_b32 v125, v26 offset:5632
	ds_read_b32 v126, v26 offset:5888
	ds_read_b32 v25, v26
	v_mov_b32_e32 v2, 0
	v_cmp_ne_u32_e64 s[70:71], 1, v3
	s_andn2_b64 vcc, exec, s[6:7]
	v_mov_b32_e32 v5, 0
	s_cbranch_vccnz .LBB0_583
	s_waitcnt lgkmcnt(0)
	v_mov_b32_e32 v3, v104
	v_cmp_ne_u32_e32 vcc, s65, v3
	s_nop 1
	v_cndmask_b32_e32 v3, 0, v3, vcc
	v_not_b32_e32 v4, v3
	v_cmp_gt_i32_e32 vcc, 0, v3
	s_nop 1
	v_cndmask_b32_e64 v5, -|v3|, v4, vcc

; template <int NJ>
; DI void b1_select(const float* sc, int nj, unsigned* mo) {
;     ...
; #pragma unroll
;   for (int j = 0; j < NJ; ++j) {
;     unsigned k = 0u;
;     if (j < nj) {
;       unsigned u = __float_as_uint(sc[64 * j + lane]);
;       u = (u == 0x80000000u) ? 0u : u;
;       k = (u & 0x80000000u) ? ~u : (u | 0x80000000u);
;     }
;     key[j] = k;
;   }
.LBB0_587:
	s_cmp_gt_u32 s8, 8
	s_cselect_b64 s[66:67], -1, 0
	s_cmp_lt_u32 s8, 9
	s_cbranch_scc1 .LBB0_589
	s_waitcnt lgkmcnt(0)
	v_mov_b32_e32 v3, v107
	v_cmp_ne_u32_e32 vcc, s65, v3
	s_nop 1
	v_cndmask_b32_e32 v3, 0, v3, vcc
	v_not_b32_e32 v4, v3
	v_cmp_gt_i32_e32 vcc, 0, v3
	s_nop 1
	v_cndmask_b32_e64 v3, -|v3|, v4, vcc
.LBB0_589:
	s_cmp_gt_u32 s8, 10
	v_mov_b32_e32 v4, 0
	s_cselect_b64 s[68:69], -1, 0
	s_cmp_lt_u32 s8, 11
	v_mov_b32_e32 v9, 0
	s_cbranch_scc1 .LBB0_591
	s_waitcnt lgkmcnt(0)
	v_mov_b32_e32 v6, v108
	v_cmp_ne_u32_e32 vcc, s65, v6
	s_nop 1
	v_cndmask_b32_e32 v6, 0, v6, vcc
	v_not_b32_e32 v8, v6
	v_cmp_gt_i32_e32 vcc, 0, v6
	s_nop 1
	v_cndmask_b32_e64 v9, -|v6|, v8, vcc
.LBB0_591:
	s_cmp_gt_u32 s8, 12
	s_cselect_b64 s[0:1], -1, 0
	v_writelane_b32 v236, s0, 1
	s_cmp_lt_u32 s8, 13
	s_nop 0
	v_writelane_b32 v236, s1, 2
	s_cbranch_scc1 .LBB0_593
	s_waitcnt lgkmcnt(0)
	v_mov_b32_e32 v4, v109
	v_cmp_ne_u32_e32 vcc, s65, v4
	s_nop 1
	v_cndmask_b32_e32 v4, 0, v4, vcc
	v_not_b32_e32 v6, v4
	v_cmp_gt_i32_e32 vcc, 0, v4
	s_nop 1
	v_cndmask_b32_e64 v4, -|v4|, v6, vcc
.LBB0_593:
	s_cmp_gt_u32 s8, 14
	v_mov_b32_e32 v6, 0
	s_cselect_b64 s[74:75], -1, 0
	s_cmp_lt_u32 s8, 15
	v_mov_b32_e32 v11, 0
	s_cbranch_scc1 .LBB0_595
	s_waitcnt lgkmcnt(0)
	v_mov_b32_e32 v8, v110
	v_cmp_ne_u32_e32 vcc, s65, v8
	s_nop 1
	v_cndmask_b32_e32 v8, 0, v8, vcc
	v_not_b32_e32 v10, v8
	v_cmp_gt_i32_e32 vcc, 0, v8
	s_nop 1
	v_cndmask_b32_e64 v11, -|v8|, v10, vcc
.LBB0_595:
	s_cmp_gt_u32 s8, 16
	s_cselect_b64 s[0:1], -1, 0
	s_cmp_lt_u32 s8, 17
	v_writelane_b32 v237, s0, 63
	s_nop 1
	v_writelane_b32 v236, s1, 0
	s_cbranch_scc1 .LBB0_597
	s_waitcnt lgkmcnt(0)
	v_mov_b32_e32 v6, v111
	v_cmp_ne_u32_e32 vcc, s65, v6
	s_nop 1
	v_cndmask_b32_e32 v6, 0, v6, vcc
	v_not_b32_e32 v8, v6
	v_cmp_gt_i32_e32 vcc, 0, v6
	s_nop 1
	v_cndmask_b32_e64 v6, -|v6|, v8, vcc
.LBB0_597:
	s_cmp_gt_u32 s8, 18
	s_cselect_b64 s[0:1], -1, 0
	v_mov_b32_e32 v8, 0
	v_writelane_b32 v237, s0, 61
	s_cmp_lt_u32 s8, 19
	v_mov_b32_e32 v13, 0
	v_writelane_b32 v237, s1, 62
	s_cbranch_scc1 .LBB0_599
	s_waitcnt lgkmcnt(0)
	v_mov_b32_e32 v10, v112
	v_cmp_ne_u32_e32 vcc, s65, v10
	s_nop 1
	v_cndmask_b32_e32 v10, 0, v10, vcc
	v_not_b32_e32 v12, v10
	v_cmp_gt_i32_e32 vcc, 0, v10
	s_nop 1
	v_cndmask_b32_e64 v13, -|v10|, v12, vcc
.LBB0_599:
	s_cmp_gt_u32 s8, 20
	s_cselect_b64 s[0:1], -1, 0
	v_writelane_b32 v237, s0, 59
	s_cmp_lt_u32 s8, 21
	s_nop 0
	v_writelane_b32 v237, s1, 60
	s_cbranch_scc1 .LBB0_601
	s_waitcnt lgkmcnt(0)
	v_mov_b32_e32 v8, v113
	v_cmp_ne_u32_e32 vcc, s65, v8
	s_nop 1
	v_cndmask_b32_e32 v8, 0, v8, vcc
	v_not_b32_e32 v10, v8
	v_cmp_gt_i32_e32 vcc, 0, v8
	s_nop 1
	v_cndmask_b32_e64 v8, -|v8|, v10, vcc
.LBB0_601:
	s_cmp_gt_u32 s8, 22
	s_cselect_b64 s[0:1], -1, 0
	v_mov_b32_e32 v10, 0
	v_writelane_b32 v237, s0, 57
	s_cmp_lt_u32 s8, 23
	v_mov_b32_e32 v15, 0
	v_writelane_b32 v237, s1, 58
	s_cbranch_scc1 .LBB0_603
	s_waitcnt lgkmcnt(0)
	v_mov_b32_e32 v12, v114
	v_cmp_ne_u32_e32 vcc, s65, v12
	s_nop 1
	v_cndmask_b32_e32 v12, 0, v12, vcc
	v_not_b32_e32 v14, v12
	v_cmp_gt_i32_e32 vcc, 0, v12
	s_nop 1
	v_cndmask_b32_e64 v15, -|v12|, v14, vcc
.LBB0_603:
	s_cmp_gt_u32 s8, 24
	s_cselect_b64 s[0:1], -1, 0
	v_writelane_b32 v237, s0, 55
	s_cmp_lt_u32 s8, 25
	s_nop 0
	v_writelane_b32 v237, s1, 56
	s_cbranch_scc1 .LBB0_605
	s_waitcnt lgkmcnt(0)
	v_mov_b32_e32 v10, v115
	v_cmp_ne_u32_e32 vcc, s65, v10
	s_nop 1
	v_cndmask_b32_e32 v10, 0, v10, vcc
	v_not_b32_e32 v12, v10
	v_cmp_gt_i32_e32 vcc, 0, v10
	s_nop 1
	v_cndmask_b32_e64 v10, -|v10|, v12, vcc
.LBB0_605:
	s_cmp_gt_u32 s8, 26
	s_cselect_b64 s[0:1], -1, 0
	v_mov_b32_e32 v12, 0
	v_writelane_b32 v237, s0, 53
	s_cmp_lt_u32 s8, 27
	v_mov_b32_e32 v17, 0
	v_writelane_b32 v237, s1, 54
	s_cbranch_scc1 .LBB0_607
	s_waitcnt lgkmcnt(0)
	v_mov_b32_e32 v14, v116
	v_cmp_ne_u32_e32 vcc, s65, v14
	s_nop 1
	v_cndmask_b32_e32 v14, 0, v14, vcc
	v_not_b32_e32 v16, v14
	v_cmp_gt_i32_e32 vcc, 0, v14
	s_nop 1
	v_cndmask_b32_e64 v17, -|v14|, v16, vcc
; template <int NJ>
; DI void b1_select(const float* sc, int nj, unsigned* mo) {
;     ...
; #pragma unroll
;   for (int j = 0; j < NJ; ++j) {
;     unsigned k = 0u;
;     if (j < nj) {
;       unsigned u = __float_as_uint(sc[64 * j + lane]);
;       u = (u == 0x80000000u) ? 0u : u;
;       k = (u & 0x80000000u) ? ~u : (u | 0x80000000u);
;     }
;     key[j] = k;
;   }
.LBB0_607:
	s_cmp_gt_u32 s8, 28
	s_cselect_b64 s[0:1], -1, 0
	v_writelane_b32 v237, s0, 51
	s_cmp_lt_u32 s8, 29
	s_nop 0
	v_writelane_b32 v237, s1, 52
	s_cbranch_scc1 .LBB0_609
	s_waitcnt lgkmcnt(0)
	v_mov_b32_e32 v12, v117
	v_cmp_ne_u32_e32 vcc, s65, v12
	s_nop 1
	v_cndmask_b32_e32 v12, 0, v12, vcc
	v_not_b32_e32 v14, v12
	v_cmp_gt_i32_e32 vcc, 0, v12
	s_nop 1
	v_cndmask_b32_e64 v12, -|v12|, v14, vcc
.LBB0_609:
	s_cmp_gt_u32 s8, 30
	s_cselect_b64 s[0:1], -1, 0
	v_mov_b32_e32 v14, 0
	v_writelane_b32 v237, s0, 49
	s_cmp_lt_u32 s8, 31
	v_mov_b32_e32 v19, 0
	v_writelane_b32 v237, s1, 50
	s_cbranch_scc1 .LBB0_611
	s_waitcnt lgkmcnt(0)
	v_mov_b32_e32 v16, v118
	v_cmp_ne_u32_e32 vcc, s65, v16
	s_nop 1
	v_cndmask_b32_e32 v16, 0, v16, vcc
	v_not_b32_e32 v18, v16
	v_cmp_gt_i32_e32 vcc, 0, v16
	s_nop 1
	v_cndmask_b32_e64 v19, -|v16|, v18, vcc
.LBB0_611:
	s_cmp_gt_u32 s8, 32
	s_cselect_b64 s[0:1], -1, 0
	v_writelane_b32 v237, s0, 23
	s_cmp_lt_u32 s8, 33
	s_nop 0
	v_writelane_b32 v237, s1, 24
	s_cbranch_scc1 .LBB0_613
	s_waitcnt lgkmcnt(0)
	v_mov_b32_e32 v14, v119
	v_cmp_ne_u32_e32 vcc, s65, v14
	s_nop 1
	v_cndmask_b32_e32 v14, 0, v14, vcc
	v_not_b32_e32 v16, v14
	v_cmp_gt_i32_e32 vcc, 0, v14
	s_nop 1
	v_cndmask_b32_e64 v14, -|v14|, v16, vcc
.LBB0_613:
	s_cmp_gt_u32 s8, 34
	s_cselect_b64 s[0:1], -1, 0
	v_mov_b32_e32 v16, 0
	v_writelane_b32 v237, s0, 47
	s_cmp_lt_u32 s8, 35
	v_mov_b32_e32 v21, 0
	v_writelane_b32 v237, s1, 48
	s_cbranch_scc1 .LBB0_615
	s_waitcnt lgkmcnt(0)
	v_mov_b32_e32 v18, v120
	v_cmp_ne_u32_e32 vcc, s65, v18
	s_nop 1
	v_cndmask_b32_e32 v18, 0, v18, vcc
	v_not_b32_e32 v20, v18
	v_cmp_gt_i32_e32 vcc, 0, v18
	s_nop 1
	v_cndmask_b32_e64 v21, -|v18|, v20, vcc
.LBB0_615:
	s_cmp_gt_u32 s8, 36
	s_cselect_b64 s[0:1], -1, 0
	v_writelane_b32 v237, s0, 45
	s_cmp_lt_u32 s8, 37
	s_nop 0
	v_writelane_b32 v237, s1, 46
	s_cbranch_scc1 .LBB0_617
	s_waitcnt lgkmcnt(0)
	v_mov_b32_e32 v16, v121
	v_cmp_ne_u32_e32 vcc, s65, v16
	s_nop 1
	v_cndmask_b32_e32 v16, 0, v16, vcc
	v_not_b32_e32 v18, v16
	v_cmp_gt_i32_e32 vcc, 0, v16
	s_nop 1
	v_cndmask_b32_e64 v16, -|v16|, v18, vcc
.LBB0_617:
	s_cmp_gt_u32 s8, 38
	s_cselect_b64 s[0:1], -1, 0
	v_mov_b32_e32 v18, 0
	v_writelane_b32 v237, s0, 43
	s_cmp_lt_u32 s8, 39
	v_mov_b32_e32 v22, 0
	v_writelane_b32 v237, s1, 44
	s_cbranch_scc1 .LBB0_619
	s_waitcnt lgkmcnt(0)
	v_mov_b32_e32 v20, v122
	v_cmp_ne_u32_e32 vcc, s65, v20
	s_nop 1
	v_cndmask_b32_e32 v20, 0, v20, vcc
	v_not_b32_e32 v22, v20
	v_cmp_gt_i32_e32 vcc, 0, v20
	s_nop 1
	v_cndmask_b32_e64 v22, -|v20|, v22, vcc
.LBB0_619:
	s_cmp_gt_u32 s8, 40
	s_cselect_b64 s[0:1], -1, 0
	v_writelane_b32 v237, s0, 41
	s_cmp_lt_u32 s8, 41
	s_nop 0
	v_writelane_b32 v237, s1, 42
	s_cbranch_scc1 .LBB0_621
	s_waitcnt lgkmcnt(0)
	v_mov_b32_e32 v18, v123
	v_cmp_ne_u32_e32 vcc, s65, v18
	s_nop 1
	v_cndmask_b32_e32 v18, 0, v18, vcc
	v_not_b32_e32 v20, v18
	v_cmp_gt_i32_e32 vcc, 0, v18
	s_nop 1
	v_cndmask_b32_e64 v18, -|v18|, v20, vcc
.LBB0_621:
	s_cmp_gt_u32 s8, 42
	s_cselect_b64 s[0:1], -1, 0
	v_mov_b32_e32 v20, 0
	v_writelane_b32 v237, s0, 39
	s_cmp_lt_u32 s8, 43
	v_mov_b32_e32 v23, 0
	v_writelane_b32 v237, s1, 40
	s_cbranch_scc1 .LBB0_623
	s_waitcnt lgkmcnt(0)
	v_mov_b32_e32 v23, v124
	v_cmp_ne_u32_e32 vcc, s65, v23
	s_nop 1
	v_cndmask_b32_e32 v23, 0, v23, vcc
	v_not_b32_e32 v24, v23
	v_cmp_gt_i32_e32 vcc, 0, v23
	s_nop 1
	v_cndmask_b32_e64 v23, -|v23|, v24, vcc
.LBB0_623:
	s_cmp_gt_u32 s8, 44
	s_cselect_b64 s[0:1], -1, 0
	v_writelane_b32 v237, s0, 35
	s_cmp_lt_u32 s8, 45
	s_nop 0
	v_writelane_b32 v237, s1, 36
	s_cbranch_scc1 .LBB0_625
	s_waitcnt lgkmcnt(0)
	v_mov_b32_e32 v20, v125
	v_cmp_ne_u32_e32 vcc, s65, v20
	s_nop 1
	v_cndmask_b32_e32 v20, 0, v20, vcc
	v_not_b32_e32 v24, v20
	v_cmp_gt_i32_e32 vcc, 0, v20
	s_nop 1
	v_cndmask_b32_e64 v20, -|v20|, v24, vcc
.LBB0_625:
	s_cmp_gt_u32 s8, 46
	s_cselect_b64 s[0:1], -1, 0
	v_writelane_b32 v237, s6, 17
	v_writelane_b32 v236, s0, 7
	s_cmp_lt_u32 s8, 47
	v_mov_b32_e32 v24, 0
	v_writelane_b32 v237, s7, 18
	v_writelane_b32 v236, s1, 8
	s_cbranch_scc1 .LBB0_627
	s_waitcnt lgkmcnt(0)
	v_mov_b32_e32 v24, v126
	v_cmp_ne_u32_e32 vcc, s65, v24
	s_nop 1
	v_cndmask_b32_e32 v24, 0, v24, vcc
	v_not_b32_e32 v26, v24
	v_cmp_gt_i32_e32 vcc, 0, v24
	s_nop 1
	v_cndmask_b32_e64 v24, -|v24|, v26, vcc

; template <int NJ>
; DI void b1_select(const float* sc, int nj, unsigned* mo) {
;     ...
; #pragma unroll
;   for (int j = 0; j < NJ; ++j) {
;     unsigned k = 0u;
;     if (j < nj) {
;       unsigned u = __float_as_uint(sc[64 * j + lane]);
;       u = (u == 0x80000000u) ? 0u : u;
;       k = (u & 0x80000000u) ? ~u : (u | 0x80000000u);
;     }
;     key[j] = k;
;   }
.LBB0_638:
	s_or_b64 exec, exec, s[52:53]
	v_mov_b32_e32 v0, v158
	v_readlane_b32 s0, v238, 63
	v_and_b32_e32 v0, 63, v0
	v_mov_b32_e32 v2, 0
	v_lshl_add_u32 v26, v0, 2, s0
	ds_read_b32 v104, v26 offset:8448
	ds_read_b32 v105, v26 offset:8704
	ds_read_b32 v106, v26 offset:8960
	ds_read_b32 v107, v26 offset:9472
	ds_read_b32 v108, v26 offset:9728
	ds_read_b32 v109, v26 offset:9984
	ds_read_b32 v110, v26 offset:10240
	ds_read_b32 v111, v26 offset:10496
	ds_read_b32 v112, v26 offset:10752
	ds_read_b32 v113, v26 offset:11008
	ds_read_b32 v114, v26 offset:11264
	ds_read_b32 v115, v26 offset:11520
	ds_read_b32 v116, v26 offset:11776
	ds_read_b32 v117, v26 offset:12032
	ds_read_b32 v118, v26 offset:12288
	ds_read_b32 v119, v26 offset:12544
	ds_read_b32 v120, v26 offset:12800
	ds_read_b32 v121, v26 offset:13056
	ds_read_b32 v122, v26 offset:13312
	ds_read_b32 v123, v26 offset:13568
	ds_read_b32 v124, v26 offset:13824
	ds_read_b32 v125, v26 offset:14080
	ds_read_b32 v25, v26 offset:8192
	s_and_b64 vcc, exec, s[70:71]
	v_mov_b32_e32 v3, 0
	v_readlane_b32 s12, v238, 40
	s_mov_b32 s70, 0x10000
	s_mov_b32 s71, 0x18000
	s_movk_i32 s92, 0x80
	s_movk_i32 s93, 0x300
	s_movk_i32 s94, 0x2080
	s_brev_b32 s0, 1
	v_readlane_b32 s13, v238, 41
	s_cbranch_vccnz .LBB0_640
	s_waitcnt lgkmcnt(0)
	v_mov_b32_e32 v3, v104
	v_cmp_ne_u32_e32 vcc, s0, v3
	s_nop 1
	v_cndmask_b32_e32 v3, 0, v3, vcc
	v_not_b32_e32 v4, v3
	v_cmp_gt_i32_e32 vcc, 0, v3
	s_nop 1
	v_cndmask_b32_e64 v3, -|v3|, v4, vcc
.LBB0_640:
	v_readlane_b32 s2, v236, 5
	v_readlane_b32 s3, v236, 6
	s_andn2_b64 vcc, exec, s[2:3]
	v_readlane_b32 s97, v238, 42
	s_movk_i32 s95, 0x104
	s_cbranch_vccnz .LBB0_642
	s_waitcnt lgkmcnt(0)
	v_mov_b32_e32 v2, v105
	v_cmp_ne_u32_e32 vcc, s0, v2
	s_nop 1
	v_cndmask_b32_e32 v2, 0, v2, vcc
	v_not_b32_e32 v4, v2
	v_cmp_gt_i32_e32 vcc, 0, v2
	s_nop 1
	v_cndmask_b32_e64 v2, -|v2|, v4, vcc
.LBB0_642:
	v_readlane_b32 s2, v236, 3
	v_readlane_b32 s3, v236, 4
	v_mov_b32_e32 v4, 0
	s_andn2_b64 vcc, exec, s[2:3]
	v_mov_b32_e32 v7, 0
	s_cbranch_vccnz .LBB0_689
	s_waitcnt lgkmcnt(0)
	v_mov_b32_e32 v5, v106
	v_cmp_ne_u32_e32 vcc, s0, v5
	s_nop 1
	v_cndmask_b32_e32 v5, 0, v5, vcc
	v_not_b32_e32 v6, v5
	v_cmp_gt_i32_e32 vcc, 0, v5
	s_nop 1
	v_cndmask_b32_e64 v7, -|v5|, v6, vcc
	s_andn2_b64 vcc, exec, s[66:67]
	s_cbranch_vccz .LBB0_690

; template <int NJ>
; DI void b1_select(const float* sc, int nj, unsigned* mo) {
;     ...
; #pragma unroll
;   for (int j = 0; j < NJ; ++j) {
;     unsigned k = 0u;
;     if (j < nj) {
;       unsigned u = __float_as_uint(sc[64 * j + lane]);
;       u = (u == 0x80000000u) ? 0u : u;
;       k = (u & 0x80000000u) ? ~u : (u | 0x80000000u);
;     }
;     key[j] = k;
;   }
.LBB0_645:
	s_waitcnt lgkmcnt(0)
	v_mov_b32_e32 v6, v107
	v_cmp_ne_u32_e32 vcc, s0, v6
	s_nop 1
	v_cndmask_b32_e32 v6, 0, v6, vcc
	v_not_b32_e32 v8, v6
	v_cmp_gt_i32_e32 vcc, 0, v6
	s_nop 1
	v_cndmask_b32_e64 v9, -|v6|, v8, vcc
.LBB0_646:
	v_readlane_b32 s2, v236, 1
	v_readlane_b32 s3, v236, 2
	s_andn2_b64 vcc, exec, s[2:3]
	s_cbranch_vccnz .LBB0_648
	s_waitcnt lgkmcnt(0)
	v_mov_b32_e32 v5, v108
	v_cmp_ne_u32_e32 vcc, s0, v5
	s_nop 1
	v_cndmask_b32_e32 v5, 0, v5, vcc
	v_not_b32_e32 v6, v5
	v_cmp_gt_i32_e32 vcc, 0, v5
	s_nop 1
	v_cndmask_b32_e64 v5, -|v5|, v6, vcc
.LBB0_648:
	v_mov_b32_e32 v6, 0
	s_andn2_b64 vcc, exec, s[74:75]
	v_mov_b32_e32 v11, 0
	s_cbranch_vccnz .LBB0_650
	s_waitcnt lgkmcnt(0)
	v_mov_b32_e32 v8, v109
	v_cmp_ne_u32_e32 vcc, s0, v8
	s_nop 1
	v_cndmask_b32_e32 v8, 0, v8, vcc
	v_not_b32_e32 v10, v8
	v_cmp_gt_i32_e32 vcc, 0, v8
	s_nop 1
	v_cndmask_b32_e64 v11, -|v8|, v10, vcc
.LBB0_650:
	v_readlane_b32 s2, v237, 63
	v_readlane_b32 s3, v236, 0
	s_andn2_b64 vcc, exec, s[2:3]
	s_cbranch_vccnz .LBB0_652
	s_waitcnt lgkmcnt(0)
	v_mov_b32_e32 v6, v110
	v_cmp_ne_u32_e32 vcc, s0, v6
	s_nop 1
	v_cndmask_b32_e32 v6, 0, v6, vcc
	v_not_b32_e32 v8, v6
	v_cmp_gt_i32_e32 vcc, 0, v6
	s_nop 1
	v_cndmask_b32_e64 v6, -|v6|, v8, vcc
.LBB0_652:
	v_readlane_b32 s2, v237, 61
	v_readlane_b32 s3, v237, 62
	v_mov_b32_e32 v8, 0
	s_andn2_b64 vcc, exec, s[2:3]
	v_mov_b32_e32 v13, 0
	s_cbranch_vccnz .LBB0_654
	s_waitcnt lgkmcnt(0)
	v_mov_b32_e32 v10, v111
	v_cmp_ne_u32_e32 vcc, s0, v10
	s_nop 1
	v_cndmask_b32_e32 v10, 0, v10, vcc
	v_not_b32_e32 v12, v10
	v_cmp_gt_i32_e32 vcc, 0, v10
	s_nop 1
	v_cndmask_b32_e64 v13, -|v10|, v12, vcc
.LBB0_654:
	v_readlane_b32 s2, v237, 59
	v_readlane_b32 s3, v237, 60
	s_andn2_b64 vcc, exec, s[2:3]
	s_cbranch_vccnz .LBB0_656
	s_waitcnt lgkmcnt(0)
	v_mov_b32_e32 v8, v112
	v_cmp_ne_u32_e32 vcc, s0, v8
	s_nop 1
	v_cndmask_b32_e32 v8, 0, v8, vcc
	v_not_b32_e32 v10, v8
	v_cmp_gt_i32_e32 vcc, 0, v8
	s_nop 1
	v_cndmask_b32_e64 v8, -|v8|, v10, vcc
.LBB0_656:
	v_readlane_b32 s2, v237, 57
	v_readlane_b32 s3, v237, 58
	v_mov_b32_e32 v10, 0
	s_andn2_b64 vcc, exec, s[2:3]
	v_mov_b32_e32 v15, 0
	s_cbranch_vccnz .LBB0_658
	s_waitcnt lgkmcnt(0)
	v_mov_b32_e32 v12, v113
	v_cmp_ne_u32_e32 vcc, s0, v12
	s_nop 1
	v_cndmask_b32_e32 v12, 0, v12, vcc
	v_not_b32_e32 v14, v12
	v_cmp_gt_i32_e32 vcc, 0, v12
	s_nop 1
	v_cndmask_b32_e64 v15, -|v12|, v14, vcc
.LBB0_658:
	v_readlane_b32 s2, v237, 55
	v_readlane_b32 s3, v237, 56
	s_andn2_b64 vcc, exec, s[2:3]
	s_cbranch_vccnz .LBB0_660
	s_waitcnt lgkmcnt(0)
	v_mov_b32_e32 v10, v114
	v_cmp_ne_u32_e32 vcc, s0, v10
	s_nop 1
	v_cndmask_b32_e32 v10, 0, v10, vcc
	v_not_b32_e32 v12, v10
	v_cmp_gt_i32_e32 vcc, 0, v10
	s_nop 1
	v_cndmask_b32_e64 v10, -|v10|, v12, vcc
.LBB0_660:
	v_readlane_b32 s2, v237, 53
	v_readlane_b32 s3, v237, 54
	v_mov_b32_e32 v12, 0
	s_andn2_b64 vcc, exec, s[2:3]
	v_mov_b32_e32 v17, 0
	s_cbranch_vccnz .LBB0_662
	s_waitcnt lgkmcnt(0)
	v_mov_b32_e32 v14, v115
	v_cmp_ne_u32_e32 vcc, s0, v14
	s_nop 1
	v_cndmask_b32_e32 v14, 0, v14, vcc
	v_not_b32_e32 v16, v14
	v_cmp_gt_i32_e32 vcc, 0, v14
	s_nop 1
	v_cndmask_b32_e64 v17, -|v14|, v16, vcc
.LBB0_662:
	v_readlane_b32 s2, v237, 51
	v_readlane_b32 s3, v237, 52
	s_andn2_b64 vcc, exec, s[2:3]
	s_cbranch_vccnz .LBB0_664
	s_waitcnt lgkmcnt(0)
	v_mov_b32_e32 v12, v116
	v_cmp_ne_u32_e32 vcc, s0, v12
	s_nop 1
	v_cndmask_b32_e32 v12, 0, v12, vcc
	v_not_b32_e32 v14, v12
	v_cmp_gt_i32_e32 vcc, 0, v12
	s_nop 1
	v_cndmask_b32_e64 v12, -|v12|, v14, vcc
.LBB0_664:
	v_readlane_b32 s2, v237, 49
	v_readlane_b32 s3, v237, 50
	v_mov_b32_e32 v14, 0
	s_andn2_b64 vcc, exec, s[2:3]
	v_mov_b32_e32 v19, 0
	s_cbranch_vccnz .LBB0_666
	s_waitcnt lgkmcnt(0)
	v_mov_b32_e32 v16, v117
	v_cmp_ne_u32_e32 vcc, s0, v16
	s_nop 1
	v_cndmask_b32_e32 v16, 0, v16, vcc
	v_not_b32_e32 v18, v16
	v_cmp_gt_i32_e32 vcc, 0, v16
	s_nop 1
	v_cndmask_b32_e64 v19, -|v16|, v18, vcc
.LBB0_666:
	v_readlane_b32 s2, v237, 23
	v_readlane_b32 s3, v237, 24
	s_andn2_b64 vcc, exec, s[2:3]
	s_cbranch_vccnz .LBB0_668
	s_waitcnt lgkmcnt(0)
	v_mov_b32_e32 v14, v118
	v_cmp_ne_u32_e32 vcc, s0, v14
	s_nop 1
	v_cndmask_b32_e32 v14, 0, v14, vcc
	v_not_b32_e32 v16, v14
	v_cmp_gt_i32_e32 vcc, 0, v14
	s_nop 1
	v_cndmask_b32_e64 v14, -|v14|, v16, vcc
.LBB0_668:
	v_readlane_b32 s2, v237, 47
	v_readlane_b32 s3, v237, 48
	v_mov_b32_e32 v16, 0
	s_andn2_b64 vcc, exec, s[2:3]
	v_mov_b32_e32 v21, 0
	s_cbranch_vccnz .LBB0_670
	s_waitcnt lgkmcnt(0)
	v_mov_b32_e32 v18, v119
	v_cmp_ne_u32_e32 vcc, s0, v18
	s_nop 1
	v_cndmask_b32_e32 v18, 0, v18, vcc
	v_not_b32_e32 v20, v18
	v_cmp_gt_i32_e32 vcc, 0, v18
	s_nop 1
	v_cndmask_b32_e64 v21, -|v18|, v20, vcc
.LBB0_670:
	v_readlane_b32 s2, v237, 45
	v_readlane_b32 s3, v237, 46
	s_andn2_b64 vcc, exec, s[2:3]
	s_cbranch_vccnz .LBB0_672
	s_waitcnt lgkmcnt(0)
	v_mov_b32_e32 v16, v120
	v_cmp_ne_u32_e32 vcc, s0, v16
	s_nop 1
	v_cndmask_b32_e32 v16, 0, v16, vcc
	v_not_b32_e32 v18, v16
	v_cmp_gt_i32_e32 vcc, 0, v16
	s_nop 1
	v_cndmask_b32_e64 v16, -|v16|, v18, vcc
.LBB0_672:
	v_readlane_b32 s2, v237, 43
	v_readlane_b32 s3, v237, 44
	v_mov_b32_e32 v18, 0
	s_andn2_b64 vcc, exec, s[2:3]
	v_mov_b32_e32 v22, 0
	s_cbranch_vccnz .LBB0_674
	s_waitcnt lgkmcnt(0)
	v_mov_b32_e32 v20, v121
	v_cmp_ne_u32_e32 vcc, s0, v20
	s_nop 1
	v_cndmask_b32_e32 v20, 0, v20, vcc
	v_not_b32_e32 v22, v20
	v_cmp_gt_i32_e32 vcc, 0, v20
	s_nop 1
	v_cndmask_b32_e64 v22, -|v20|, v22, vcc
.LBB0_674:
	v_readlane_b32 s2, v237, 41
	v_readlane_b32 s3, v237, 42
	s_andn2_b64 vcc, exec, s[2:3]
	s_cbranch_vccnz .LBB0_676
	s_waitcnt lgkmcnt(0)
	v_mov_b32_e32 v18, v122
	v_cmp_ne_u32_e32 vcc, s0, v18
	s_nop 1
	v_cndmask_b32_e32 v18, 0, v18, vcc
	v_not_b32_e32 v20, v18
	v_cmp_gt_i32_e32 vcc, 0, v18
	s_nop 1
	v_cndmask_b32_e64 v18, -|v18|, v20, vcc
.LBB0_676:
	v_readlane_b32 s2, v237, 39
	v_readlane_b32 s3, v237, 40
	v_mov_b32_e32 v20, 0
	s_andn2_b64 vcc, exec, s[2:3]
	v_mov_b32_e32 v23, 0
	s_cbranch_vccnz .LBB0_678
	s_waitcnt lgkmcnt(0)
	v_mov_b32_e32 v23, v123
	v_cmp_ne_u32_e32 vcc, s0, v23
	s_nop 1
	v_cndmask_b32_e32 v23, 0, v23, vcc
	v_not_b32_e32 v24, v23
	v_cmp_gt_i32_e32 vcc, 0, v23
	s_nop 1
	v_cndmask_b32_e64 v23, -|v23|, v24, vcc
.LBB0_678:
	v_readlane_b32 s2, v237, 35
	v_readlane_b32 s3, v237, 36
	s_andn2_b64 vcc, exec, s[2:3]
	s_cbranch_vccnz .LBB0_680
	s_waitcnt lgkmcnt(0)
	v_mov_b32_e32 v20, v124
	v_cmp_ne_u32_e32 vcc, s0, v20
	s_nop 1
	v_cndmask_b32_e32 v20, 0, v20, vcc
	v_not_b32_e32 v24, v20
	v_cmp_gt_i32_e32 vcc, 0, v20
	s_nop 1
	v_cndmask_b32_e64 v20, -|v20|, v24, vcc
.LBB0_680:
	v_readlane_b32 s2, v236, 7
	v_readlane_b32 s3, v236, 8
	v_mov_b32_e32 v24, 0
	s_andn2_b64 vcc, exec, s[2:3]
	s_cbranch_vccnz .LBB0_682
	s_waitcnt lgkmcnt(0)
	v_mov_b32_e32 v24, v125
	v_cmp_ne_u32_e32 vcc, s0, v24
	s_nop 1
	v_cndmask_b32_e32 v24, 0, v24, vcc
	v_not_b32_e32 v26, v24
	v_cmp_gt_i32_e32 vcc, 0, v24
	s_nop 1
	v_cndmask_b32_e64 v24, -|v24|, v26, vcc

; template <int NJ>
; DI void b1_select(const float* sc, int nj, unsigned* mo) {
;     ...
; #pragma unroll
;   for (int j = 0; j < NJ; ++j) {
;     unsigned k = 0u;
;     if (j < nj) {
;       unsigned u = __float_as_uint(sc[64 * j + lane]);
;       u = (u == 0x80000000u) ? 0u : u;
;       k = (u & 0x80000000u) ? ~u : (u | 0x80000000u);
;     }
;     key[j] = k;
;   }
.LBB0_697:
	s_and_b64 vcc, exec, s[0:1]
	s_cbranch_vccz .LBB0_797
	v_mov_b32_e32 v0, v158
	v_readlane_b32 s0, v238, 63
	v_and_b32_e32 v0, 63, v0
	v_cndmask_b32_e64 v3, 0, 1, s[6:7]
	v_lshl_add_u32 v22, v0, 2, s0
	ds_read_b32 v104, v22 offset:256
	ds_read_b32 v105, v22 offset:512
	ds_read_b32 v106, v22 offset:768
	ds_read_b32 v107, v22 offset:1024
	ds_read_b32 v108, v22 offset:1280
	ds_read_b32 v109, v22 offset:1536
	ds_read_b32 v110, v22 offset:1792
	ds_read_b32 v111, v22 offset:2048
	ds_read_b32 v112, v22 offset:2304
	ds_read_b32 v113, v22 offset:2560
	ds_read_b32 v114, v22 offset:2816
	ds_read_b32 v115, v22 offset:3072
	ds_read_b32 v116, v22 offset:3328
	ds_read_b32 v117, v22 offset:3584
	ds_read_b32 v118, v22 offset:3840
	ds_read_b32 v119, v22 offset:4096
	ds_read_b32 v120, v22 offset:4352
	ds_read_b32 v121, v22 offset:4608
	ds_read_b32 v122, v22 offset:4864
	ds_read_b32 v21, v22
	v_cmp_ne_u32_e64 s[0:1], 1, v3
	v_mov_b32_e32 v2, 0
	s_andn2_b64 vcc, exec, s[6:7]
	v_writelane_b32 v236, s0, 5
	v_mov_b32_e32 v4, 0
	s_nop 0
	v_writelane_b32 v236, s1, 6
	s_cbranch_vccnz .LBB0_700
	s_waitcnt lgkmcnt(0)
	v_mov_b32_e32 v3, v104
	v_cmp_ne_u32_e32 vcc, s65, v3
	s_nop 1
	v_cndmask_b32_e32 v3, 0, v3, vcc
	v_not_b32_e32 v4, v3
	v_cmp_gt_i32_e32 vcc, 0, v3
	s_nop 1
	v_cndmask_b32_e64 v4, -|v3|, v4, vcc
.LBB0_700:
	s_cmp_gt_u32 s8, 4
	s_cselect_b64 s[0:1], -1, 0
	v_writelane_b32 v236, s0, 3
	s_cmp_lt_u32 s8, 5
	s_nop 0
	v_writelane_b32 v236, s1, 4
	s_cbranch_scc1 .LBB0_702
	s_waitcnt lgkmcnt(0)
	v_mov_b32_e32 v2, v105
	v_cmp_ne_u32_e32 vcc, s65, v2
	s_nop 1
	v_cndmask_b32_e32 v2, 0, v2, vcc
	v_not_b32_e32 v3, v2
	v_cmp_gt_i32_e32 vcc, 0, v2
	s_nop 1
	v_cndmask_b32_e64 v2, -|v2|, v3, vcc
.LBB0_702:
	s_cmp_gt_u32 s8, 6
	s_cselect_b64 s[0:1], -1, 0
	v_mov_b32_e32 v3, 0
	v_writelane_b32 v236, s0, 1
	s_cmp_lt_u32 s8, 7
	v_mov_b32_e32 v7, 0
	v_writelane_b32 v236, s1, 2
	s_cbranch_scc1 .LBB0_704
	s_waitcnt lgkmcnt(0)
	v_mov_b32_e32 v5, v106
	v_cmp_ne_u32_e32 vcc, s65, v5
	s_nop 1
	v_cndmask_b32_e32 v5, 0, v5, vcc
	v_not_b32_e32 v6, v5
	v_cmp_gt_i32_e32 vcc, 0, v5
	s_nop 1
	v_cndmask_b32_e64 v7, -|v5|, v6, vcc
.LBB0_704:
	s_cmp_gt_u32 s8, 8
	s_cselect_b64 s[0:1], -1, 0
	s_cmp_lt_u32 s8, 9
	v_writelane_b32 v237, s0, 63
	s_nop 1
	v_writelane_b32 v236, s1, 0
	s_cbranch_scc1 .LBB0_706
	s_waitcnt lgkmcnt(0)
	v_mov_b32_e32 v3, v107
	v_cmp_ne_u32_e32 vcc, s65, v3
	s_nop 1
	v_cndmask_b32_e32 v3, 0, v3, vcc
	v_not_b32_e32 v5, v3
	v_cmp_gt_i32_e32 vcc, 0, v3
	s_nop 1
	v_cndmask_b32_e64 v3, -|v3|, v5, vcc
.LBB0_706:
	s_cmp_gt_u32 s8, 10
	v_mov_b32_e32 v5, 0
	s_cselect_b64 s[70:71], -1, 0
	s_cmp_lt_u32 s8, 11
	v_mov_b32_e32 v9, 0
	s_cbranch_scc1 .LBB0_708
	s_waitcnt lgkmcnt(0)
	v_mov_b32_e32 v6, v108
	v_cmp_ne_u32_e32 vcc, s65, v6
	s_nop 1
	v_cndmask_b32_e32 v6, 0, v6, vcc
	v_not_b32_e32 v8, v6
	v_cmp_gt_i32_e32 vcc, 0, v6
	s_nop 1
	v_cndmask_b32_e64 v9, -|v6|, v8, vcc
.LBB0_708:
	s_cmp_gt_u32 s8, 12
	s_cselect_b64 s[58:59], -1, 0
	s_cmp_lt_u32 s8, 13
	s_cbranch_scc1 .LBB0_710
	s_waitcnt lgkmcnt(0)
	v_mov_b32_e32 v5, v109
	v_cmp_ne_u32_e32 vcc, s65, v5
	s_nop 1
	v_cndmask_b32_e32 v5, 0, v5, vcc
	v_not_b32_e32 v6, v5
	v_cmp_gt_i32_e32 vcc, 0, v5
	s_nop 1
	v_cndmask_b32_e64 v5, -|v5|, v6, vcc
.LBB0_710:
	s_cmp_gt_u32 s8, 14
	v_mov_b32_e32 v6, 0
	s_cselect_b64 s[60:61], -1, 0
	s_cmp_lt_u32 s8, 15
	v_mov_b32_e32 v10, 0
	s_cbranch_scc1 .LBB0_712
	s_waitcnt lgkmcnt(0)
	v_mov_b32_e32 v8, v110
	v_cmp_ne_u32_e32 vcc, s65, v8
	s_nop 1
	v_cndmask_b32_e32 v8, 0, v8, vcc
	v_not_b32_e32 v10, v8
	v_cmp_gt_i32_e32 vcc, 0, v8
	s_nop 1
	v_cndmask_b32_e64 v10, -|v8|, v10, vcc
.LBB0_712:
	s_cmp_gt_u32 s8, 16
	s_cselect_b64 s[66:67], -1, 0
	s_cmp_lt_u32 s8, 17
	s_cbranch_scc1 .LBB0_714
	s_waitcnt lgkmcnt(0)
	v_mov_b32_e32 v6, v111
	v_cmp_ne_u32_e32 vcc, s65, v6
	s_nop 1
	v_cndmask_b32_e32 v6, 0, v6, vcc
	v_not_b32_e32 v8, v6
	v_cmp_gt_i32_e32 vcc, 0, v6
	s_nop 1
	v_cndmask_b32_e64 v6, -|v6|, v8, vcc
.LBB0_714:
	s_cmp_gt_u32 s8, 18
	v_mov_b32_e32 v8, 0
	s_cselect_b64 s[68:69], -1, 0
	s_cmp_lt_u32 s8, 19
	v_mov_b32_e32 v12, 0
	s_cbranch_scc1 .LBB0_716
	s_waitcnt lgkmcnt(0)
	v_mov_b32_e32 v11, v112
	v_cmp_ne_u32_e32 vcc, s65, v11
	s_nop 1
	v_cndmask_b32_e32 v11, 0, v11, vcc
	v_not_b32_e32 v12, v11
	v_cmp_gt_i32_e32 vcc, 0, v11
	s_nop 1
	v_cndmask_b32_e64 v12, -|v11|, v12, vcc
; template <int NJ>
; DI void b1_select(const float* sc, int nj, unsigned* mo) {
;     ...
; #pragma unroll
;   for (int j = 0; j < NJ; ++j) {
;     unsigned k = 0u;
;     if (j < nj) {
;       unsigned u = __float_as_uint(sc[64 * j + lane]);
;       u = (u == 0x80000000u) ? 0u : u;
;       k = (u & 0x80000000u) ? ~u : (u | 0x80000000u);
;     }
;     key[j] = k;
;   }
.LBB0_716:
	s_cmp_gt_u32 s8, 20
	s_cselect_b64 s[0:1], -1, 0
	v_writelane_b32 v237, s0, 61
	s_cmp_lt_u32 s8, 21
	s_nop 0
	v_writelane_b32 v237, s1, 62
	s_cbranch_scc1 .LBB0_718
	s_waitcnt lgkmcnt(0)
	v_mov_b32_e32 v8, v113
	v_cmp_ne_u32_e32 vcc, s65, v8
	s_nop 1
	v_cndmask_b32_e32 v8, 0, v8, vcc
	v_not_b32_e32 v11, v8
	v_cmp_gt_i32_e32 vcc, 0, v8
	s_nop 1
	v_cndmask_b32_e64 v8, -|v8|, v11, vcc
.LBB0_718:
	s_cmp_gt_u32 s8, 22
	v_mov_b32_e32 v11, 0
	s_cselect_b64 s[74:75], -1, 0
	s_cmp_lt_u32 s8, 23
	v_mov_b32_e32 v15, 0
	s_cbranch_scc1 .LBB0_720
	s_waitcnt lgkmcnt(0)
	v_mov_b32_e32 v13, v114
	v_cmp_ne_u32_e32 vcc, s65, v13
	s_nop 1
	v_cndmask_b32_e32 v13, 0, v13, vcc
	v_not_b32_e32 v14, v13
	v_cmp_gt_i32_e32 vcc, 0, v13
	s_nop 1
	v_cndmask_b32_e64 v15, -|v13|, v14, vcc
.LBB0_720:
	s_cmp_gt_u32 s8, 24
	s_cselect_b64 s[94:95], -1, 0
	s_cmp_lt_u32 s8, 25
	s_cbranch_scc1 .LBB0_722
	s_waitcnt lgkmcnt(0)
	v_mov_b32_e32 v11, v115
	v_cmp_ne_u32_e32 vcc, s65, v11
	s_nop 1
	v_cndmask_b32_e32 v11, 0, v11, vcc
	v_not_b32_e32 v13, v11
	v_cmp_gt_i32_e32 vcc, 0, v11
	s_nop 1
	v_cndmask_b32_e64 v11, -|v11|, v13, vcc
.LBB0_722:
	s_cmp_gt_u32 s8, 26
	s_cselect_b64 s[0:1], -1, 0
	v_mov_b32_e32 v13, 0
	v_writelane_b32 v237, s0, 59
	s_cmp_lt_u32 s8, 27
	v_mov_b32_e32 v17, 0
	v_writelane_b32 v237, s1, 60
	s_cbranch_scc1 .LBB0_724
	s_waitcnt lgkmcnt(0)
	v_mov_b32_e32 v14, v116
	v_cmp_ne_u32_e32 vcc, s65, v14
	s_nop 1
	v_cndmask_b32_e32 v14, 0, v14, vcc
	v_not_b32_e32 v16, v14
	v_cmp_gt_i32_e32 vcc, 0, v14
	s_nop 1
	v_cndmask_b32_e64 v17, -|v14|, v16, vcc
.LBB0_724:
	s_cmp_gt_u32 s8, 28
	s_cselect_b64 s[62:63], -1, 0
	s_cmp_lt_u32 s8, 29
	s_cbranch_scc1 .LBB0_726
	s_waitcnt lgkmcnt(0)
	v_mov_b32_e32 v13, v117
	v_cmp_ne_u32_e32 vcc, s65, v13
	s_nop 1
	v_cndmask_b32_e32 v13, 0, v13, vcc
	v_not_b32_e32 v14, v13
	v_cmp_gt_i32_e32 vcc, 0, v13
	s_nop 1
	v_cndmask_b32_e64 v13, -|v13|, v14, vcc
.LBB0_726:
	s_cmp_gt_u32 s8, 30
	s_cselect_b64 s[0:1], -1, 0
	v_mov_b32_e32 v14, 0
	v_writelane_b32 v237, s0, 57
	s_cmp_lt_u32 s8, 31
	v_mov_b32_e32 v18, 0
	v_writelane_b32 v237, s1, 58
	s_cbranch_scc1 .LBB0_728
	s_waitcnt lgkmcnt(0)
	v_mov_b32_e32 v16, v118
	v_cmp_ne_u32_e32 vcc, s65, v16
	s_nop 1
	v_cndmask_b32_e32 v16, 0, v16, vcc
	v_not_b32_e32 v18, v16
	v_cmp_gt_i32_e32 vcc, 0, v16
	s_nop 1
	v_cndmask_b32_e64 v18, -|v16|, v18, vcc
.LBB0_728:
	s_cmp_gt_u32 s8, 32
	s_brev_b32 s56, 1
	s_cselect_b64 s[64:65], -1, 0
	s_cmp_lt_u32 s8, 33
	s_cbranch_scc1 .LBB0_730
	s_waitcnt lgkmcnt(0)
	v_mov_b32_e32 v14, v119
	v_cmp_ne_u32_e32 vcc, s56, v14
	s_nop 1
	v_cndmask_b32_e32 v14, 0, v14, vcc
	v_not_b32_e32 v16, v14
	v_cmp_gt_i32_e32 vcc, 0, v14
	s_nop 1
	v_cndmask_b32_e64 v14, -|v14|, v16, vcc
.LBB0_730:
	s_cmp_gt_u32 s8, 34
	s_cselect_b64 s[0:1], -1, 0
	v_mov_b32_e32 v16, 0
	v_writelane_b32 v237, s0, 55
	s_cmp_lt_u32 s8, 35
	v_mov_b32_e32 v19, 0
	v_writelane_b32 v237, s1, 56
	s_cbranch_scc1 .LBB0_732
	s_waitcnt lgkmcnt(0)
	v_mov_b32_e32 v19, v120
	v_cmp_ne_u32_e32 vcc, s56, v19
	s_nop 1
	v_cndmask_b32_e32 v19, 0, v19, vcc
	v_not_b32_e32 v20, v19
	v_cmp_gt_i32_e32 vcc, 0, v19
	s_nop 1
	v_cndmask_b32_e64 v19, -|v19|, v20, vcc
.LBB0_732:
	s_cmp_gt_u32 s8, 36
	s_cselect_b64 s[0:1], -1, 0
	v_writelane_b32 v237, s0, 53
	s_cmp_lt_u32 s8, 37
	s_nop 0
	v_writelane_b32 v237, s1, 54
	s_cbranch_scc1 .LBB0_734
	s_waitcnt lgkmcnt(0)
	v_mov_b32_e32 v16, v121
	v_cmp_ne_u32_e32 vcc, s56, v16
	s_nop 1
	v_cndmask_b32_e32 v16, 0, v16, vcc
	v_not_b32_e32 v20, v16
	v_cmp_gt_i32_e32 vcc, 0, v16
	s_nop 1
	v_cndmask_b32_e64 v16, -|v16|, v20, vcc
.LBB0_734:
	s_cmp_gt_u32 s8, 38
	s_cselect_b64 s[0:1], -1, 0
	v_writelane_b32 v237, s6, 17
	v_writelane_b32 v236, s0, 7
	s_cmp_lt_u32 s8, 39
	v_mov_b32_e32 v20, 0
	v_writelane_b32 v237, s7, 18
	v_writelane_b32 v236, s1, 8
	s_cbranch_scc1 .LBB0_736
	s_waitcnt lgkmcnt(0)
	v_mov_b32_e32 v20, v122
	v_cmp_ne_u32_e32 vcc, s56, v20
	s_nop 1
	v_cndmask_b32_e32 v20, 0, v20, vcc
	v_not_b32_e32 v22, v20
	v_cmp_gt_i32_e32 vcc, 0, v20
	s_nop 1
	v_cndmask_b32_e64 v20, -|v20|, v22, vcc

; template <int NJ>
; DI void b1_select(const float* sc, int nj, unsigned* mo) {
;     ...
; #pragma unroll
;   for (int j = 0; j < NJ; ++j) {
;     unsigned k = 0u;
;     if (j < nj) {
;       unsigned u = __float_as_uint(sc[64 * j + lane]);
;       u = (u == 0x80000000u) ? 0u : u;
;       k = (u & 0x80000000u) ? ~u : (u | 0x80000000u);
;     }
;     key[j] = k;
;   }
.LBB0_747:
	s_or_b64 exec, exec, s[44:45]
	v_mov_b32_e32 v0, v158
	v_readlane_b32 s0, v238, 63
	v_and_b32_e32 v0, 63, v0
	v_mov_b32_e32 v2, 0
	v_lshl_add_u32 v22, v0, 2, s0
	ds_read_b32 v104, v22 offset:8448
	ds_read_b32 v105, v22 offset:8704
	ds_read_b32 v106, v22 offset:8960
	ds_read_b32 v107, v22 offset:9216
	ds_read_b32 v108, v22 offset:9728
	ds_read_b32 v109, v22 offset:10240
	ds_read_b32 v110, v22 offset:10496
	ds_read_b32 v111, v22 offset:10752
	ds_read_b32 v112, v22 offset:11008
	ds_read_b32 v113, v22 offset:11264
	ds_read_b32 v114, v22 offset:11520
	ds_read_b32 v115, v22 offset:11776
	ds_read_b32 v116, v22 offset:12032
	ds_read_b32 v117, v22 offset:12288
	ds_read_b32 v118, v22 offset:12544
	ds_read_b32 v119, v22 offset:12800
	ds_read_b32 v120, v22 offset:13056
	ds_read_b32 v21, v22 offset:8192
	v_readlane_b32 s0, v236, 5
	v_readlane_b32 s1, v236, 6
	s_and_b64 vcc, exec, s[0:1]
	v_mov_b32_e32 v4, 0
	v_readlane_b32 s97, v238, 42
	s_cbranch_vccnz .LBB0_749
	s_waitcnt lgkmcnt(0)
	v_mov_b32_e32 v3, v104
	v_cmp_ne_u32_e32 vcc, s56, v3
	s_nop 1
	v_cndmask_b32_e32 v3, 0, v3, vcc
	v_not_b32_e32 v4, v3
	v_cmp_gt_i32_e32 vcc, 0, v3
	s_nop 1
	v_cndmask_b32_e64 v4, -|v3|, v4, vcc
.LBB0_749:
	v_readlane_b32 s0, v236, 3
	v_readlane_b32 s1, v236, 4
	s_andn2_b64 vcc, exec, s[0:1]
	s_mov_b32 s72, s57
	s_cbranch_vccnz .LBB0_751
	s_waitcnt lgkmcnt(0)
	v_mov_b32_e32 v2, v105
	v_cmp_ne_u32_e32 vcc, s56, v2
	s_nop 1
	v_cndmask_b32_e32 v2, 0, v2, vcc
	v_not_b32_e32 v3, v2
	v_cmp_gt_i32_e32 vcc, 0, v2
	s_nop 1
	v_cndmask_b32_e64 v2, -|v2|, v3, vcc
.LBB0_751:
	v_readlane_b32 s0, v236, 1
	v_readlane_b32 s1, v236, 2
	v_mov_b32_e32 v3, 0
	s_andn2_b64 vcc, exec, s[0:1]
	v_mov_b32_e32 v8, 0
	s_cbranch_vccnz .LBB0_753
	s_waitcnt lgkmcnt(0)
	v_mov_b32_e32 v5, v106
	v_cmp_ne_u32_e32 vcc, s56, v5
	s_nop 1
	v_cndmask_b32_e32 v5, 0, v5, vcc
	v_not_b32_e32 v6, v5
	v_cmp_gt_i32_e32 vcc, 0, v5
	s_nop 1
	v_cndmask_b32_e64 v8, -|v5|, v6, vcc
.LBB0_753:
	v_readlane_b32 s0, v237, 63
	v_readlane_b32 s1, v236, 0
	s_andn2_b64 vcc, exec, s[0:1]
	s_cbranch_vccnz .LBB0_788
	s_waitcnt lgkmcnt(0)
	v_mov_b32_e32 v3, v107
	v_cmp_ne_u32_e32 vcc, s56, v3
	s_nop 1
	v_cndmask_b32_e32 v3, 0, v3, vcc
	v_not_b32_e32 v5, v3
	v_cmp_gt_i32_e32 vcc, 0, v3
	s_nop 1
	v_cndmask_b32_e64 v3, -|v3|, v5, vcc
	v_mov_b32_e32 v5, 0
	s_andn2_b64 vcc, exec, s[70:71]
	v_mov_b32_e32 v9, 0
	s_cbranch_vccz .LBB0_789

; template <int NJ>
; DI void b1_select(const float* sc, int nj, unsigned* mo) {
;     ...
; #pragma unroll
;   for (int j = 0; j < NJ; ++j) {
;     unsigned k = 0u;
;     if (j < nj) {
;       unsigned u = __float_as_uint(sc[64 * j + lane]);
;       u = (u == 0x80000000u) ? 0u : u;
;       k = (u & 0x80000000u) ? ~u : (u | 0x80000000u);
;     }
;     key[j] = k;
;   }
.LBB0_756:
	s_waitcnt lgkmcnt(0)
	v_mov_b32_e32 v5, v108
	v_cmp_ne_u32_e32 vcc, s56, v5
	s_nop 1
	v_cndmask_b32_e32 v5, 0, v5, vcc
	v_not_b32_e32 v6, v5
	v_cmp_gt_i32_e32 vcc, 0, v5
	s_nop 1
	v_cndmask_b32_e64 v5, -|v5|, v6, vcc
	v_mov_b32_e32 v6, 0
	s_andn2_b64 vcc, exec, s[60:61]
	v_mov_b32_e32 v11, 0
	s_cbranch_vccz .LBB0_791

; template <int NJ>
; DI void b1_select(const float* sc, int nj, unsigned* mo) {
;     ...
; #pragma unroll
;   for (int j = 0; j < NJ; ++j) {
;     unsigned k = 0u;
;     if (j < nj) {
;       unsigned u = __float_as_uint(sc[64 * j + lane]);
;       u = (u == 0x80000000u) ? 0u : u;
;       k = (u & 0x80000000u) ? ~u : (u | 0x80000000u);
;     }
;     key[j] = k;
;   }
.LBB0_758:
	s_waitcnt lgkmcnt(0)
	v_mov_b32_e32 v6, v109
	v_cmp_ne_u32_e32 vcc, s56, v6
	s_nop 1
	v_cndmask_b32_e32 v6, 0, v6, vcc
	v_not_b32_e32 v7, v6
	v_cmp_gt_i32_e32 vcc, 0, v6
	s_nop 1
	v_cndmask_b32_e64 v6, -|v6|, v7, vcc
.LBB0_759:
	v_readlane_b32 s66, v238, 33
	v_mov_b32_e32 v7, 0
	s_andn2_b64 vcc, exec, s[68:69]
	v_mov_b32_e32 v12, 0
	v_readlane_b32 s67, v238, 34
	s_cbranch_vccnz .LBB0_761
	s_waitcnt lgkmcnt(0)
	v_mov_b32_e32 v10, v110
	v_cmp_ne_u32_e32 vcc, s56, v10
	s_nop 1
	v_cndmask_b32_e32 v10, 0, v10, vcc
	v_not_b32_e32 v12, v10
	v_cmp_gt_i32_e32 vcc, 0, v10
	s_nop 1
	v_cndmask_b32_e64 v12, -|v10|, v12, vcc
.LBB0_761:
	v_readlane_b32 s0, v237, 61
	v_readlane_b32 s1, v237, 62
	s_andn2_b64 vcc, exec, s[0:1]
	v_readlane_b32 s68, v238, 30
	s_cbranch_vccnz .LBB0_763
	s_waitcnt lgkmcnt(0)
	v_mov_b32_e32 v7, v111
	v_cmp_ne_u32_e32 vcc, s56, v7
	s_nop 1
	v_cndmask_b32_e32 v7, 0, v7, vcc
	v_not_b32_e32 v10, v7
	v_cmp_gt_i32_e32 vcc, 0, v7
	s_nop 1
	v_cndmask_b32_e64 v7, -|v7|, v10, vcc
.LBB0_763:
	v_mov_b32_e32 v10, 0
	s_andn2_b64 vcc, exec, s[74:75]
	v_mov_b32_e32 v14, 0
	s_cbranch_vccnz .LBB0_765
	s_waitcnt lgkmcnt(0)
	v_mov_b32_e32 v13, v112
	v_cmp_ne_u32_e32 vcc, s56, v13
	s_nop 1
	v_cndmask_b32_e32 v13, 0, v13, vcc
	v_not_b32_e32 v14, v13
	v_cmp_gt_i32_e32 vcc, 0, v13
	s_nop 1
	v_cndmask_b32_e64 v14, -|v13|, v14, vcc
.LBB0_765:
	v_readlane_b32 s74, v238, 37
	s_andn2_b64 vcc, exec, s[94:95]
	v_readlane_b32 s75, v238, 38
	s_cbranch_vccnz .LBB0_767
	s_waitcnt lgkmcnt(0)
	v_mov_b32_e32 v10, v113
	v_cmp_ne_u32_e32 vcc, s56, v10
	s_nop 1
	v_cndmask_b32_e32 v10, 0, v10, vcc
	v_not_b32_e32 v13, v10
	v_cmp_gt_i32_e32 vcc, 0, v10
	s_nop 1
	v_cndmask_b32_e64 v10, -|v10|, v13, vcc
.LBB0_767:
	v_readlane_b32 s0, v237, 59
	v_readlane_b32 s1, v237, 60
	v_readlane_b32 s12, v238, 40
	v_mov_b32_e32 v13, 0
	s_andn2_b64 vcc, exec, s[0:1]
	v_mov_b32_e32 v16, 0
	v_readlane_b32 s13, v238, 41
	s_mov_b32 s70, 0x10000
	s_mov_b32 s71, 0x18000
	s_movk_i32 s92, 0x80
	s_movk_i32 s93, 0x300
	s_movk_i32 s94, 0x2080
	s_movk_i32 s95, 0x104
	s_cbranch_vccnz .LBB0_769
	s_waitcnt lgkmcnt(0)
	v_mov_b32_e32 v15, v114
	v_cmp_ne_u32_e32 vcc, s56, v15
	s_nop 1
	v_cndmask_b32_e32 v15, 0, v15, vcc
	v_not_b32_e32 v16, v15
	v_cmp_gt_i32_e32 vcc, 0, v15
	s_nop 1
	v_cndmask_b32_e64 v16, -|v15|, v16, vcc
.LBB0_769:
	s_andn2_b64 vcc, exec, s[62:63]
	s_cbranch_vccnz .LBB0_771
	s_waitcnt lgkmcnt(0)
	v_mov_b32_e32 v13, v115
	v_cmp_ne_u32_e32 vcc, s56, v13
	s_nop 1
	v_cndmask_b32_e32 v13, 0, v13, vcc
	v_not_b32_e32 v15, v13
	v_cmp_gt_i32_e32 vcc, 0, v13
	s_nop 1
	v_cndmask_b32_e64 v13, -|v13|, v15, vcc
.LBB0_771:
	v_readlane_b32 s0, v237, 57
	v_readlane_b32 s1, v237, 58
	v_mov_b32_e32 v15, 0
	s_andn2_b64 vcc, exec, s[0:1]
	v_mov_b32_e32 v18, 0
	s_cbranch_vccnz .LBB0_773
	s_waitcnt lgkmcnt(0)
	v_mov_b32_e32 v17, v116
	v_cmp_ne_u32_e32 vcc, s56, v17
	s_nop 1
	v_cndmask_b32_e32 v17, 0, v17, vcc
	v_not_b32_e32 v18, v17
	v_cmp_gt_i32_e32 vcc, 0, v17
	s_nop 1
	v_cndmask_b32_e64 v18, -|v17|, v18, vcc
.LBB0_773:
	s_andn2_b64 vcc, exec, s[64:65]
	s_brev_b32 s65, 1
	s_cbranch_vccnz .LBB0_775
	s_waitcnt lgkmcnt(0)
	v_mov_b32_e32 v15, v117
	v_cmp_ne_u32_e32 vcc, s65, v15
	s_nop 1
	v_cndmask_b32_e32 v15, 0, v15, vcc
	v_not_b32_e32 v17, v15
	v_cmp_gt_i32_e32 vcc, 0, v15
	s_nop 1
	v_cndmask_b32_e64 v15, -|v15|, v17, vcc
.LBB0_775:
	v_readlane_b32 s0, v237, 55
	v_readlane_b32 s1, v237, 56
	v_mov_b32_e32 v17, 0
	s_andn2_b64 vcc, exec, s[0:1]
	v_mov_b32_e32 v19, 0
	s_mov_b64 s[60:61], 0x20000
	s_movk_i32 s69, 0x1040
	s_movk_i32 s64, 0x54a0
	s_cbranch_vccnz .LBB0_777
	s_waitcnt lgkmcnt(0)
	v_mov_b32_e32 v19, v118
	v_cmp_ne_u32_e32 vcc, s65, v19
	s_nop 1
	v_cndmask_b32_e32 v19, 0, v19, vcc
	v_not_b32_e32 v20, v19
	v_cmp_gt_i32_e32 vcc, 0, v19
	s_nop 1
	v_cndmask_b32_e64 v19, -|v19|, v20, vcc
.LBB0_777:
	v_readlane_b32 s0, v237, 53
	v_readlane_b32 s1, v237, 54
	s_andn2_b64 vcc, exec, s[0:1]
	s_cbranch_vccnz .LBB0_779
	s_waitcnt lgkmcnt(0)
	v_mov_b32_e32 v17, v119
	v_cmp_ne_u32_e32 vcc, s65, v17
	s_nop 1
	v_cndmask_b32_e32 v17, 0, v17, vcc
	v_not_b32_e32 v20, v17
	v_cmp_gt_i32_e32 vcc, 0, v17
	s_nop 1
	v_cndmask_b32_e64 v17, -|v17|, v20, vcc
.LBB0_779:
	v_readlane_b32 s0, v236, 7
	v_readlane_b32 s1, v236, 8
	v_mov_b32_e32 v20, 0
	s_andn2_b64 vcc, exec, s[0:1]
	s_cbranch_vccnz .LBB0_781
	s_waitcnt lgkmcnt(0)
	v_mov_b32_e32 v20, v120
	v_cmp_ne_u32_e32 vcc, s65, v20
	s_nop 1
	v_cndmask_b32_e32 v20, 0, v20, vcc
	v_not_b32_e32 v22, v20
	v_cmp_gt_i32_e32 vcc, 0, v20
	s_nop 1
	v_cndmask_b32_e64 v20, -|v20|, v22, vcc

; template <int NJ>
; DI void b1_select(const float* sc, int nj, unsigned* mo) {
;     ...
; #pragma unroll
;   for (int j = 0; j < NJ; ++j) {
;     unsigned k = 0u;
;     if (j < nj) {
;       unsigned u = __float_as_uint(sc[64 * j + lane]);
;       u = (u == 0x80000000u) ? 0u : u;
;       k = (u & 0x80000000u) ? ~u : (u | 0x80000000u);
;     }
;     key[j] = k;
;   }
.LBB0_798:
	s_and_b64 vcc, exec, s[0:1]
	s_cbranch_vccz .LBB0_955
	s_cmp_gt_i32 s4, 2
	s_mov_b64 s[0:1], -1
	s_cbranch_scc0 .LBB0_953
	v_writelane_b32 v237, s4, 19
	s_cmp_gt_i32 s4, 3
	v_writelane_b32 v237, s10, 21
	s_nop 1
	v_writelane_b32 v237, s11, 22
	s_cbranch_scc0 .LBB0_884
	v_mov_b32_e32 v0, v158
	v_readlane_b32 s0, v238, 63
	v_and_b32_e32 v0, 63, v0
	v_cndmask_b32_e64 v3, 0, 1, s[6:7]
	v_lshl_add_u32 v18, v0, 2, s0
	ds_read_b32 v104, v18 offset:256
	ds_read_b32 v105, v18 offset:512
	ds_read_b32 v106, v18 offset:768
	ds_read_b32 v107, v18 offset:1024
	ds_read_b32 v108, v18 offset:1280
	ds_read_b32 v109, v18 offset:1536
	ds_read_b32 v110, v18 offset:1792
	ds_read_b32 v111, v18 offset:2048
	ds_read_b32 v112, v18 offset:2304
	ds_read_b32 v113, v18 offset:2560
	ds_read_b32 v114, v18 offset:2816
	ds_read_b32 v115, v18 offset:3072
	ds_read_b32 v116, v18 offset:3328
	ds_read_b32 v117, v18 offset:3584
	ds_read_b32 v118, v18 offset:3840
	ds_read_b32 v17, v18
	v_mov_b32_e32 v2, 0
	v_cmp_ne_u32_e64 s[70:71], 1, v3
	s_andn2_b64 vcc, exec, s[6:7]
	v_mov_b32_e32 v5, 0
	s_cbranch_vccnz .LBB0_803
	s_waitcnt lgkmcnt(0)
	v_mov_b32_e32 v3, v104
	v_cmp_ne_u32_e32 vcc, s65, v3
	s_nop 1
	v_cndmask_b32_e32 v3, 0, v3, vcc
	v_not_b32_e32 v4, v3
	v_cmp_gt_i32_e32 vcc, 0, v3
	s_nop 1
	v_cndmask_b32_e64 v5, -|v3|, v4, vcc
.LBB0_803:
	s_cmp_gt_u32 s8, 4
	s_cselect_b64 s[40:41], -1, 0
	s_cmp_lt_u32 s8, 5
	s_cbranch_scc1 .LBB0_805
	s_waitcnt lgkmcnt(0)
	v_mov_b32_e32 v2, v105
	v_cmp_ne_u32_e32 vcc, s65, v2
	s_nop 1
	v_cndmask_b32_e32 v2, 0, v2, vcc
	v_not_b32_e32 v3, v2
	v_cmp_gt_i32_e32 vcc, 0, v2
	s_nop 1
	v_cndmask_b32_e64 v2, -|v2|, v3, vcc
.LBB0_805:
	s_cmp_gt_u32 s8, 6
	v_mov_b32_e32 v3, 0
	s_cselect_b64 s[42:43], -1, 0
	s_cmp_lt_u32 s8, 7
	v_mov_b32_e32 v7, 0
	s_cbranch_scc1 .LBB0_807
	s_waitcnt lgkmcnt(0)
	v_mov_b32_e32 v4, v106
	v_cmp_ne_u32_e32 vcc, s65, v4
	s_nop 1
	v_cndmask_b32_e32 v4, 0, v4, vcc
	v_not_b32_e32 v6, v4
	v_cmp_gt_i32_e32 vcc, 0, v4
	s_nop 1
	v_cndmask_b32_e64 v7, -|v4|, v6, vcc
.LBB0_807:
	s_cmp_gt_u32 s8, 8
	s_cselect_b64 s[44:45], -1, 0
	s_cmp_lt_u32 s8, 9
	s_cbranch_scc1 .LBB0_809
	s_waitcnt lgkmcnt(0)
	v_mov_b32_e32 v3, v107
	v_cmp_ne_u32_e32 vcc, s65, v3
	s_nop 1
	v_cndmask_b32_e32 v3, 0, v3, vcc
	v_not_b32_e32 v4, v3
	v_cmp_gt_i32_e32 vcc, 0, v3
	s_nop 1
	v_cndmask_b32_e64 v3, -|v3|, v4, vcc
.LBB0_809:
	s_cmp_gt_u32 s8, 10
	v_mov_b32_e32 v4, 0
	s_cselect_b64 s[46:47], -1, 0
	s_cmp_lt_u32 s8, 11
	v_mov_b32_e32 v9, 0
	s_cbranch_scc1 .LBB0_811
	s_waitcnt lgkmcnt(0)
	v_mov_b32_e32 v6, v108
	v_cmp_ne_u32_e32 vcc, s65, v6
	s_nop 1
	v_cndmask_b32_e32 v6, 0, v6, vcc
	v_not_b32_e32 v8, v6
	v_cmp_gt_i32_e32 vcc, 0, v6
	s_nop 1
	v_cndmask_b32_e64 v9, -|v6|, v8, vcc
.LBB0_811:
	s_cmp_gt_u32 s8, 12
	s_cselect_b64 s[48:49], -1, 0
	s_cmp_lt_u32 s8, 13
	s_cbranch_scc1 .LBB0_813
	s_waitcnt lgkmcnt(0)
	v_mov_b32_e32 v4, v109
	v_cmp_ne_u32_e32 vcc, s65, v4
	s_nop 1
	v_cndmask_b32_e32 v4, 0, v4, vcc
	v_not_b32_e32 v6, v4
	v_cmp_gt_i32_e32 vcc, 0, v4
	s_nop 1
	v_cndmask_b32_e64 v4, -|v4|, v6, vcc
.LBB0_813:
	s_cmp_gt_u32 s8, 14
	v_mov_b32_e32 v6, 0
	s_cselect_b64 s[50:51], -1, 0
	s_cmp_lt_u32 s8, 15
	v_mov_b32_e32 v11, 0
	s_cbranch_scc1 .LBB0_815
	s_waitcnt lgkmcnt(0)
	v_mov_b32_e32 v8, v110
	v_cmp_ne_u32_e32 vcc, s65, v8
	s_nop 1
	v_cndmask_b32_e32 v8, 0, v8, vcc
	v_not_b32_e32 v10, v8
	v_cmp_gt_i32_e32 vcc, 0, v8
	s_nop 1
	v_cndmask_b32_e64 v11, -|v8|, v10, vcc
.LBB0_815:
	s_cmp_gt_u32 s8, 16
	s_cselect_b64 s[52:53], -1, 0
	s_cmp_lt_u32 s8, 17
	s_cbranch_scc1 .LBB0_817
	s_waitcnt lgkmcnt(0)
	v_mov_b32_e32 v6, v111
	v_cmp_ne_u32_e32 vcc, s65, v6
	s_nop 1
	v_cndmask_b32_e32 v6, 0, v6, vcc
	v_not_b32_e32 v8, v6
	v_cmp_gt_i32_e32 vcc, 0, v6
	s_nop 1
	v_cndmask_b32_e64 v6, -|v6|, v8, vcc
.LBB0_817:
	s_cmp_gt_u32 s8, 18
	v_mov_b32_e32 v8, 0
	s_cselect_b64 s[54:55], -1, 0
	s_cmp_lt_u32 s8, 19
	v_mov_b32_e32 v13, 0
	s_cbranch_scc1 .LBB0_819
	s_waitcnt lgkmcnt(0)
	v_mov_b32_e32 v10, v112
	v_cmp_ne_u32_e32 vcc, s65, v10
	s_nop 1
	v_cndmask_b32_e32 v10, 0, v10, vcc
	v_not_b32_e32 v12, v10
	v_cmp_gt_i32_e32 vcc, 0, v10
	s_nop 1
	v_cndmask_b32_e64 v13, -|v10|, v12, vcc
.LBB0_819:
	s_cmp_gt_u32 s8, 20
	s_cselect_b64 s[56:57], -1, 0
	s_cmp_lt_u32 s8, 21
	s_cbranch_scc1 .LBB0_821
	s_waitcnt lgkmcnt(0)
	v_mov_b32_e32 v8, v113
	v_cmp_ne_u32_e32 vcc, s65, v8
	s_nop 1
	v_cndmask_b32_e32 v8, 0, v8, vcc
	v_not_b32_e32 v10, v8
	v_cmp_gt_i32_e32 vcc, 0, v8
	s_nop 1
	v_cndmask_b32_e64 v8, -|v8|, v10, vcc
.LBB0_821:
	s_cmp_gt_u32 s8, 22
	v_mov_b32_e32 v10, 0
	s_cselect_b64 s[58:59], -1, 0
	s_cmp_lt_u32 s8, 23
	v_mov_b32_e32 v14, 0
	s_cbranch_scc1 .LBB0_823
	s_waitcnt lgkmcnt(0)
	v_mov_b32_e32 v12, v114
	v_cmp_ne_u32_e32 vcc, s65, v12
	s_nop 1
	v_cndmask_b32_e32 v12, 0, v12, vcc
	v_not_b32_e32 v14, v12
	v_cmp_gt_i32_e32 vcc, 0, v12
	s_nop 1
	v_cndmask_b32_e64 v14, -|v12|, v14, vcc
.LBB0_823:
	s_cmp_gt_u32 s8, 24
	s_cselect_b64 s[60:61], -1, 0
	s_cmp_lt_u32 s8, 25
	s_cbranch_scc1 .LBB0_825
	s_waitcnt lgkmcnt(0)
	v_mov_b32_e32 v10, v115
	v_cmp_ne_u32_e32 vcc, s65, v10
	s_nop 1
	v_cndmask_b32_e32 v10, 0, v10, vcc
	v_not_b32_e32 v12, v10
	v_cmp_gt_i32_e32 vcc, 0, v10
	s_nop 1
	v_cndmask_b32_e64 v10, -|v10|, v12, vcc
.LBB0_825:
	s_cmp_gt_u32 s8, 26
	v_mov_b32_e32 v12, 0
	s_cselect_b64 s[62:63], -1, 0
	s_cmp_lt_u32 s8, 27
	v_mov_b32_e32 v15, 0
	s_cbranch_scc1 .LBB0_827
	s_waitcnt lgkmcnt(0)
	v_mov_b32_e32 v15, v116
	v_cmp_ne_u32_e32 vcc, s65, v15
	s_nop 1
	v_cndmask_b32_e32 v15, 0, v15, vcc
	v_not_b32_e32 v16, v15
	v_cmp_gt_i32_e32 vcc, 0, v15
	s_nop 1
	v_cndmask_b32_e64 v15, -|v15|, v16, vcc
.LBB0_827:
	s_cmp_gt_u32 s8, 28
	s_brev_b32 s38, 1
	s_cselect_b64 s[64:65], -1, 0
	s_cmp_lt_u32 s8, 29
	s_cbranch_scc1 .LBB0_829
	s_waitcnt lgkmcnt(0)
	v_mov_b32_e32 v12, v117
	v_cmp_ne_u32_e32 vcc, s38, v12
	s_nop 1
	v_cndmask_b32_e32 v12, 0, v12, vcc
	v_not_b32_e32 v16, v12
	v_cmp_gt_i32_e32 vcc, 0, v12
	s_nop 1
	v_cndmask_b32_e64 v12, -|v12|, v16, vcc
.LBB0_829:
	s_cmp_gt_u32 s8, 30
	s_cselect_b64 s[0:1], -1, 0
	v_writelane_b32 v236, s0, 7
	s_cmp_lt_u32 s8, 31
	v_mov_b32_e32 v16, 0
	v_writelane_b32 v236, s1, 8
	s_cbranch_scc1 .LBB0_831
	s_waitcnt lgkmcnt(0)
	v_mov_b32_e32 v16, v118
	v_cmp_ne_u32_e32 vcc, s38, v16
	s_nop 1
	v_cndmask_b32_e32 v16, 0, v16, vcc
	v_not_b32_e32 v18, v16
	v_cmp_gt_i32_e32 vcc, 0, v16
	s_nop 1
	v_cndmask_b32_e64 v16, -|v16|, v18, vcc

; template <int NJ>
; DI void b1_select(const float* sc, int nj, unsigned* mo) {
;     ...
; #pragma unroll
;   for (int j = 0; j < NJ; ++j) {
;     unsigned k = 0u;
;     if (j < nj) {
;       unsigned u = __float_as_uint(sc[64 * j + lane]);
;       u = (u == 0x80000000u) ? 0u : u;
;       k = (u & 0x80000000u) ? ~u : (u | 0x80000000u);
;     }
;     key[j] = k;
;   }
.LBB0_842:
	s_or_b64 exec, exec, s[36:37]
	v_mov_b32_e32 v0, v158
	v_readlane_b32 s0, v238, 63
	v_and_b32_e32 v0, 63, v0
	v_readlane_b32 s66, v238, 33
	v_lshl_add_u32 v18, v0, 2, s0
	ds_read_b32 v104, v18 offset:8448
	ds_read_b32 v105, v18 offset:8704
	ds_read_b32 v106, v18 offset:9216
	ds_read_b32 v107, v18 offset:9728
	ds_read_b32 v108, v18 offset:9984
	ds_read_b32 v109, v18 offset:10240
	ds_read_b32 v110, v18 offset:10496
	ds_read_b32 v111, v18 offset:10752
	ds_read_b32 v112, v18 offset:11008
	ds_read_b32 v113, v18 offset:11520
	ds_read_b32 v114, v18 offset:8960
	ds_read_b32 v115, v18 offset:9472
	ds_read_b32 v116, v18 offset:11264
	ds_read_b32 v117, v18 offset:11776
	ds_read_b32 v118, v18 offset:12032
	ds_read_b32 v17, v18 offset:8192
	v_mov_b32_e32 v2, 0
	s_and_b64 vcc, exec, s[70:71]
	v_mov_b32_e32 v3, 0
	v_readlane_b32 s67, v238, 34
	s_cbranch_vccnz .LBB0_844
	s_waitcnt lgkmcnt(0)
	v_mov_b32_e32 v3, v104
	v_cmp_ne_u32_e32 vcc, s38, v3
	s_nop 1
	v_cndmask_b32_e32 v3, 0, v3, vcc
	v_not_b32_e32 v4, v3
	v_cmp_gt_i32_e32 vcc, 0, v3
	s_nop 1
	v_cndmask_b32_e64 v3, -|v3|, v4, vcc
.LBB0_844:
	v_readlane_b32 s74, v238, 37
	v_readlane_b32 s0, v238, 40
	s_andn2_b64 vcc, exec, s[40:41]
	v_readlane_b32 s75, v238, 38
	v_readlane_b32 s1, v238, 41
	v_readlane_b32 s97, v238, 42
	s_mov_b32 s70, 0x10000
	s_mov_b32 s71, 0x18000
	s_movk_i32 s92, 0x80
	s_movk_i32 s93, 0x300
	s_movk_i32 s94, 0x2080
	s_movk_i32 s95, 0x104
	s_mov_b32 s68, s39
	s_mov_b32 s72, s4
	s_cbranch_vccnz .LBB0_862
	s_waitcnt lgkmcnt(0)
	v_mov_b32_e32 v2, v105
	v_cmp_ne_u32_e32 vcc, s38, v2
	s_nop 1
	v_cndmask_b32_e32 v2, 0, v2, vcc
	v_not_b32_e32 v4, v2
	v_cmp_gt_i32_e32 vcc, 0, v2
	s_nop 1
	v_cndmask_b32_e64 v2, -|v2|, v4, vcc
	v_mov_b32_e32 v4, 0
	s_andn2_b64 vcc, exec, s[42:43]
	v_mov_b32_e32 v8, 0
	s_cbranch_vccz .LBB0_863

; template <int NJ>
; DI void b1_select(const float* sc, int nj, unsigned* mo) {
;     ...
; #pragma unroll
;   for (int j = 0; j < NJ; ++j) {
;     unsigned k = 0u;
;     if (j < nj) {
;       unsigned u = __float_as_uint(sc[64 * j + lane]);
;       u = (u == 0x80000000u) ? 0u : u;
;       k = (u & 0x80000000u) ? ~u : (u | 0x80000000u);
;     }
;     key[j] = k;
;   }
.LBB0_847:
	s_waitcnt lgkmcnt(0)
	v_mov_b32_e32 v4, v106
	v_cmp_ne_u32_e32 vcc, s38, v4
	s_nop 1
	v_cndmask_b32_e32 v4, 0, v4, vcc
	v_not_b32_e32 v5, v4
	v_cmp_gt_i32_e32 vcc, 0, v4
	s_nop 1
	v_cndmask_b32_e64 v4, -|v4|, v5, vcc
	v_mov_b32_e32 v5, 0
	s_andn2_b64 vcc, exec, s[46:47]
	v_mov_b32_e32 v9, 0
	s_cbranch_vccz .LBB0_865

; template <int NJ>
; DI void b1_select(const float* sc, int nj, unsigned* mo) {
;     ...
; #pragma unroll
;   for (int j = 0; j < NJ; ++j) {
;     unsigned k = 0u;
;     if (j < nj) {
;       unsigned u = __float_as_uint(sc[64 * j + lane]);
;       u = (u == 0x80000000u) ? 0u : u;
;       k = (u & 0x80000000u) ? ~u : (u | 0x80000000u);
;     }
;     key[j] = k;
;   }
.LBB0_849:
	s_waitcnt lgkmcnt(0)
	v_mov_b32_e32 v5, v107
	v_cmp_ne_u32_e32 vcc, s38, v5
	s_nop 1
	v_cndmask_b32_e32 v5, 0, v5, vcc
	v_not_b32_e32 v6, v5
	v_cmp_gt_i32_e32 vcc, 0, v5
	s_nop 1
	v_cndmask_b32_e64 v5, -|v5|, v6, vcc
.LBB0_850:
	v_readlane_b32 s48, v238, 45
	v_mov_b32_e32 v6, 0
	s_andn2_b64 vcc, exec, s[50:51]
	v_mov_b32_e32 v11, 0
	v_readlane_b32 s49, v238, 46
	s_cbranch_vccnz .LBB0_852
	s_waitcnt lgkmcnt(0)
	v_mov_b32_e32 v7, v108
	v_cmp_ne_u32_e32 vcc, s38, v7
	s_nop 1
	v_cndmask_b32_e32 v7, 0, v7, vcc
	v_not_b32_e32 v10, v7
	v_cmp_gt_i32_e32 vcc, 0, v7
	s_nop 1
	v_cndmask_b32_e64 v11, -|v7|, v10, vcc
.LBB0_852:
	s_andn2_b64 vcc, exec, s[52:53]
	s_cbranch_vccnz .LBB0_854
	s_waitcnt lgkmcnt(0)
	v_mov_b32_e32 v6, v109
	v_cmp_ne_u32_e32 vcc, s38, v6
	s_nop 1
	v_cndmask_b32_e32 v6, 0, v6, vcc
	v_not_b32_e32 v7, v6
	v_cmp_gt_i32_e32 vcc, 0, v6
	s_nop 1
	v_cndmask_b32_e64 v6, -|v6|, v7, vcc
.LBB0_854:
	v_readlane_b32 s52, v238, 54
	v_mov_b32_e32 v7, 0
	s_andn2_b64 vcc, exec, s[54:55]
	v_mov_b32_e32 v13, 0
	v_readlane_b32 s53, v238, 55
	s_cbranch_vccnz .LBB0_856
	s_waitcnt lgkmcnt(0)
	v_mov_b32_e32 v10, v110
	v_cmp_ne_u32_e32 vcc, s38, v10
	s_nop 1
	v_cndmask_b32_e32 v10, 0, v10, vcc
	v_not_b32_e32 v12, v10
	v_cmp_gt_i32_e32 vcc, 0, v10
	s_nop 1
	v_cndmask_b32_e64 v13, -|v10|, v12, vcc
.LBB0_856:
	v_readlane_b32 s54, v238, 43
	s_andn2_b64 vcc, exec, s[56:57]
	v_readlane_b32 s55, v238, 44
	s_cbranch_vccnz .LBB0_858
	s_waitcnt lgkmcnt(0)
	v_mov_b32_e32 v7, v111
	v_cmp_ne_u32_e32 vcc, s38, v7
	s_nop 1
	v_cndmask_b32_e32 v7, 0, v7, vcc
	v_not_b32_e32 v10, v7
	v_cmp_gt_i32_e32 vcc, 0, v7
	s_nop 1
	v_cndmask_b32_e64 v7, -|v7|, v10, vcc
.LBB0_858:
	v_mov_b32_e32 v10, 0
	s_andn2_b64 vcc, exec, s[58:59]
	v_mov_b32_e32 v14, 0
	s_movk_i32 s56, 0x210
	s_cbranch_vccnz .LBB0_866
	s_waitcnt lgkmcnt(0)
	v_mov_b32_e32 v12, v112
	v_cmp_ne_u32_e32 vcc, s38, v12
	s_nop 1
	v_cndmask_b32_e32 v12, 0, v12, vcc
	v_not_b32_e32 v14, v12
	v_cmp_gt_i32_e32 vcc, 0, v12
	s_nop 1
	v_cndmask_b32_e64 v14, -|v12|, v14, vcc
	s_andn2_b64 vcc, exec, s[60:61]
	s_mov_b64 s[58:59], s[0:1]
	s_cbranch_vccz .LBB0_867

; template <int NJ>
; DI void b1_select(const float* sc, int nj, unsigned* mo) {
;     ...
; #pragma unroll
;   for (int j = 0; j < NJ; ++j) {
;     unsigned k = 0u;
;     if (j < nj) {
;       unsigned u = __float_as_uint(sc[64 * j + lane]);
;       u = (u == 0x80000000u) ? 0u : u;
;       k = (u & 0x80000000u) ? ~u : (u | 0x80000000u);
;     }
;     key[j] = k;
;   }
.LBB0_861:
	s_waitcnt lgkmcnt(0)
	v_mov_b32_e32 v15, v113
	v_cmp_ne_u32_e32 vcc, s38, v15
	s_nop 1
	v_cndmask_b32_e32 v15, 0, v15, vcc
	v_not_b32_e32 v16, v15
	v_cmp_gt_i32_e32 vcc, 0, v15
	s_nop 1
	v_cndmask_b32_e64 v15, -|v15|, v16, vcc
	s_andn2_b64 vcc, exec, s[64:65]
	s_brev_b32 s65, 1
	s_cbranch_vccz .LBB0_869
	s_branch .LBB0_870

; template <int NJ>
; DI void b1_select(const float* sc, int nj, unsigned* mo) {
;     ...
; #pragma unroll
;   for (int j = 0; j < NJ; ++j) {
;     unsigned k = 0u;
;     if (j < nj) {
;       unsigned u = __float_as_uint(sc[64 * j + lane]);
;       u = (u == 0x80000000u) ? 0u : u;
;       k = (u & 0x80000000u) ? ~u : (u | 0x80000000u);
;     }
;     key[j] = k;
;   }
.LBB0_863:
	s_waitcnt lgkmcnt(0)
	v_mov_b32_e32 v5, v114
	v_cmp_ne_u32_e32 vcc, s38, v5
	s_nop 1
	v_cndmask_b32_e32 v5, 0, v5, vcc
	v_not_b32_e32 v6, v5
	v_cmp_gt_i32_e32 vcc, 0, v5
	s_nop 1
	v_cndmask_b32_e64 v8, -|v5|, v6, vcc
	s_andn2_b64 vcc, exec, s[44:45]
	s_cbranch_vccz .LBB0_847

; template <int NJ>
; DI void b1_select(const float* sc, int nj, unsigned* mo) {
;     ...
; #pragma unroll
;   for (int j = 0; j < NJ; ++j) {
;     unsigned k = 0u;
;     if (j < nj) {
;       unsigned u = __float_as_uint(sc[64 * j + lane]);
;       u = (u == 0x80000000u) ? 0u : u;
;       k = (u & 0x80000000u) ? ~u : (u | 0x80000000u);
;     }
;     key[j] = k;
;   }
.LBB0_865:
	s_waitcnt lgkmcnt(0)
	v_mov_b32_e32 v6, v115
	v_cmp_ne_u32_e32 vcc, s38, v6
	s_nop 1
	v_cndmask_b32_e32 v6, 0, v6, vcc
	v_not_b32_e32 v7, v6
	v_cmp_gt_i32_e32 vcc, 0, v6
	s_nop 1
	v_cndmask_b32_e64 v9, -|v6|, v7, vcc
	s_andn2_b64 vcc, exec, s[48:49]
	s_cbranch_vccz .LBB0_849
	s_branch .LBB0_850

; template <int NJ>
; DI void b1_select(const float* sc, int nj, unsigned* mo) {
;     ...
; #pragma unroll
;   for (int j = 0; j < NJ; ++j) {
;     unsigned k = 0u;
;     if (j < nj) {
;       unsigned u = __float_as_uint(sc[64 * j + lane]);
;       u = (u == 0x80000000u) ? 0u : u;
;       k = (u & 0x80000000u) ? ~u : (u | 0x80000000u);
;     }
;     key[j] = k;
;   }
.LBB0_867:
	s_waitcnt lgkmcnt(0)
	v_mov_b32_e32 v10, v116
	v_cmp_ne_u32_e32 vcc, s38, v10
	s_nop 1
	v_cndmask_b32_e32 v10, 0, v10, vcc
	v_not_b32_e32 v12, v10
	v_cmp_gt_i32_e32 vcc, 0, v10
	s_nop 1
	v_cndmask_b32_e64 v10, -|v10|, v12, vcc
	v_mov_b32_e32 v12, 0
	s_andn2_b64 vcc, exec, s[62:63]
	v_mov_b32_e32 v15, 0
	s_cbranch_vccz .LBB0_861

; template <int NJ>
; DI void b1_select(const float* sc, int nj, unsigned* mo) {
;     ...
; #pragma unroll
;   for (int j = 0; j < NJ; ++j) {
;     unsigned k = 0u;
;     if (j < nj) {
;       unsigned u = __float_as_uint(sc[64 * j + lane]);
;       u = (u == 0x80000000u) ? 0u : u;
;       k = (u & 0x80000000u) ? ~u : (u | 0x80000000u);
;     }
;     key[j] = k;
;   }
.LBB0_869:
	s_waitcnt lgkmcnt(0)
	v_mov_b32_e32 v12, v117
	v_cmp_ne_u32_e32 vcc, s65, v12
	s_nop 1
	v_cndmask_b32_e32 v12, 0, v12, vcc
	v_not_b32_e32 v16, v12
	v_cmp_gt_i32_e32 vcc, 0, v12
	s_nop 1
	v_cndmask_b32_e64 v12, -|v12|, v16, vcc
.LBB0_870:
	v_readlane_b32 s0, v236, 7
	v_readlane_b32 s1, v236, 8
	v_mov_b32_e32 v16, 0
	s_andn2_b64 vcc, exec, s[0:1]
	s_mov_b64 s[60:61], 0x20000
	s_movk_i32 s69, 0x1040
	s_movk_i32 s64, 0x54a0
	s_cbranch_vccnz .LBB0_872
	s_waitcnt lgkmcnt(0)
	v_mov_b32_e32 v16, v118
	v_cmp_ne_u32_e32 vcc, s65, v16
	s_nop 1
	v_cndmask_b32_e32 v16, 0, v16, vcc
	v_not_b32_e32 v18, v16
	v_cmp_gt_i32_e32 vcc, 0, v16
	s_nop 1
	v_cndmask_b32_e64 v16, -|v16|, v18, vcc

; template <int NJ>
; DI void b1_select(const float* sc, int nj, unsigned* mo) {
;     ...
; #pragma unroll
;   for (int j = 0; j < NJ; ++j) {
;     unsigned k = 0u;
;     if (j < nj) {
;       unsigned u = __float_as_uint(sc[64 * j + lane]);
;       u = (u == 0x80000000u) ? 0u : u;
;       k = (u & 0x80000000u) ? ~u : (u | 0x80000000u);
;     }
;     key[j] = k;
;   }
.LBB0_884:
	s_and_b64 vcc, exec, s[0:1]
	s_cbranch_vccz .LBB0_952
	v_mov_b32_e32 v0, v158
	v_readlane_b32 s0, v238, 63
	v_and_b32_e32 v0, 63, v0
	v_cndmask_b32_e64 v3, 0, 1, s[6:7]
	v_lshl_add_u32 v14, v0, 2, s0
	ds_read_b32 v104, v14 offset:256
	ds_read_b32 v105, v14 offset:512
	ds_read_b32 v106, v14 offset:768
	ds_read_b32 v107, v14 offset:1024
	ds_read_b32 v108, v14 offset:1280
	ds_read_b32 v109, v14 offset:1536
	ds_read_b32 v110, v14 offset:1792
	ds_read_b32 v111, v14 offset:2048
	ds_read_b32 v112, v14 offset:2304
	ds_read_b32 v113, v14 offset:2560
	ds_read_b32 v114, v14 offset:2816
	ds_read_b32 v13, v14
	v_mov_b32_e32 v2, 0
	v_cmp_ne_u32_e64 s[4:5], 1, v3
	s_andn2_b64 vcc, exec, s[6:7]
	v_mov_b32_e32 v5, 0
	s_cbranch_vccnz .LBB0_887
	s_waitcnt lgkmcnt(0)
	v_mov_b32_e32 v3, v104
	v_cmp_ne_u32_e32 vcc, s65, v3
	s_nop 1
	v_cndmask_b32_e32 v3, 0, v3, vcc
	v_not_b32_e32 v4, v3
	v_cmp_gt_i32_e32 vcc, 0, v3
	s_nop 1
	v_cndmask_b32_e64 v5, -|v3|, v4, vcc
.LBB0_887:
	s_cmp_gt_u32 s8, 4
	s_cselect_b64 s[30:31], -1, 0
	s_cmp_lt_u32 s8, 5
	s_cbranch_scc1 .LBB0_889
	s_waitcnt lgkmcnt(0)
	v_mov_b32_e32 v2, v105
	v_cmp_ne_u32_e32 vcc, s65, v2
	s_nop 1
	v_cndmask_b32_e32 v2, 0, v2, vcc
	v_not_b32_e32 v3, v2
	v_cmp_gt_i32_e32 vcc, 0, v2
	s_nop 1
	v_cndmask_b32_e64 v2, -|v2|, v3, vcc
.LBB0_889:
	s_cmp_gt_u32 s8, 6
	v_mov_b32_e32 v3, 0
	s_cselect_b64 s[34:35], -1, 0
	s_cmp_lt_u32 s8, 7
	v_mov_b32_e32 v7, 0
	s_cbranch_scc1 .LBB0_891
	s_waitcnt lgkmcnt(0)
	v_mov_b32_e32 v4, v106
	v_cmp_ne_u32_e32 vcc, s65, v4
	s_nop 1
	v_cndmask_b32_e32 v4, 0, v4, vcc
	v_not_b32_e32 v6, v4
	v_cmp_gt_i32_e32 vcc, 0, v4
	s_nop 1
	v_cndmask_b32_e64 v7, -|v4|, v6, vcc
.LBB0_891:
	s_cmp_gt_u32 s8, 8
	s_cselect_b64 s[36:37], -1, 0
	s_cmp_lt_u32 s8, 9
	s_cbranch_scc1 .LBB0_893
	s_waitcnt lgkmcnt(0)
	v_mov_b32_e32 v3, v107
	v_cmp_ne_u32_e32 vcc, s65, v3
	s_nop 1
	v_cndmask_b32_e32 v3, 0, v3, vcc
	v_not_b32_e32 v4, v3
	v_cmp_gt_i32_e32 vcc, 0, v3
	s_nop 1
	v_cndmask_b32_e64 v3, -|v3|, v4, vcc
.LBB0_893:
	s_cmp_gt_u32 s8, 10
	v_mov_b32_e32 v4, 0
	s_cselect_b64 s[38:39], -1, 0
	s_cmp_lt_u32 s8, 11
	v_mov_b32_e32 v9, 0
	s_cbranch_scc1 .LBB0_895
	s_waitcnt lgkmcnt(0)
	v_mov_b32_e32 v6, v108
	v_cmp_ne_u32_e32 vcc, s65, v6
	s_nop 1
	v_cndmask_b32_e32 v6, 0, v6, vcc
	v_not_b32_e32 v8, v6
	v_cmp_gt_i32_e32 vcc, 0, v6
	s_nop 1
	v_cndmask_b32_e64 v9, -|v6|, v8, vcc
.LBB0_895:
	s_cmp_gt_u32 s8, 12
	s_cselect_b64 s[40:41], -1, 0
	s_cmp_lt_u32 s8, 13
	s_cbranch_scc1 .LBB0_897
	s_waitcnt lgkmcnt(0)
	v_mov_b32_e32 v4, v109
	v_cmp_ne_u32_e32 vcc, s65, v4
	s_nop 1
	v_cndmask_b32_e32 v4, 0, v4, vcc
	v_not_b32_e32 v6, v4
	v_cmp_gt_i32_e32 vcc, 0, v4
	s_nop 1
	v_cndmask_b32_e64 v4, -|v4|, v6, vcc
.LBB0_897:
	s_cmp_gt_u32 s8, 14
	v_mov_b32_e32 v6, 0
	s_cselect_b64 s[42:43], -1, 0
	s_cmp_lt_u32 s8, 15
	v_mov_b32_e32 v10, 0
	s_cbranch_scc1 .LBB0_899
	s_waitcnt lgkmcnt(0)
	v_mov_b32_e32 v8, v110
	v_cmp_ne_u32_e32 vcc, s65, v8
	s_nop 1
	v_cndmask_b32_e32 v8, 0, v8, vcc
	v_not_b32_e32 v10, v8
	v_cmp_gt_i32_e32 vcc, 0, v8
	s_nop 1
	v_cndmask_b32_e64 v10, -|v8|, v10, vcc
.LBB0_899:
	s_cmp_gt_u32 s8, 16
	s_cselect_b64 s[44:45], -1, 0
	s_cmp_lt_u32 s8, 17
	s_cbranch_scc1 .LBB0_901
	s_waitcnt lgkmcnt(0)
	v_mov_b32_e32 v6, v111
	v_cmp_ne_u32_e32 vcc, s65, v6
	s_nop 1
	v_cndmask_b32_e32 v6, 0, v6, vcc
	v_not_b32_e32 v8, v6
	v_cmp_gt_i32_e32 vcc, 0, v6
	s_nop 1
	v_cndmask_b32_e64 v6, -|v6|, v8, vcc
.LBB0_901:
	s_cmp_gt_u32 s8, 18
	v_mov_b32_e32 v8, 0
	s_cselect_b64 s[46:47], -1, 0
	s_cmp_lt_u32 s8, 19
	v_mov_b32_e32 v11, 0
	s_cbranch_scc1 .LBB0_903
	s_waitcnt lgkmcnt(0)
	v_mov_b32_e32 v11, v112
	v_cmp_ne_u32_e32 vcc, s65, v11
	s_nop 1
	v_cndmask_b32_e32 v11, 0, v11, vcc
	v_not_b32_e32 v12, v11
	v_cmp_gt_i32_e32 vcc, 0, v11
	s_nop 1
	v_cndmask_b32_e64 v11, -|v11|, v12, vcc
.LBB0_903:
	s_cmp_gt_u32 s8, 20
	s_cselect_b64 s[48:49], -1, 0
	s_cmp_lt_u32 s8, 21
	s_cbranch_scc1 .LBB0_905
	s_waitcnt lgkmcnt(0)
	v_mov_b32_e32 v8, v113
	v_cmp_ne_u32_e32 vcc, s65, v8
	s_nop 1
	v_cndmask_b32_e32 v8, 0, v8, vcc
	v_not_b32_e32 v12, v8
	v_cmp_gt_i32_e32 vcc, 0, v8
	s_nop 1
	v_cndmask_b32_e64 v8, -|v8|, v12, vcc
.LBB0_905:
	s_cmp_gt_u32 s8, 22
	s_cselect_b64 s[28:29], -1, 0
	s_cmp_lt_u32 s8, 23
	v_mov_b32_e32 v12, 0
	s_cbranch_scc1 .LBB0_907
	s_waitcnt lgkmcnt(0)
	v_mov_b32_e32 v12, v114
	v_cmp_ne_u32_e32 vcc, s65, v12
	s_nop 1
	v_cndmask_b32_e32 v12, 0, v12, vcc
	v_not_b32_e32 v14, v12
	v_cmp_gt_i32_e32 vcc, 0, v12
	s_nop 1
	v_cndmask_b32_e64 v12, -|v12|, v14, vcc

; template <int NJ>
; DI void b1_select(const float* sc, int nj, unsigned* mo) {
;     ...
; #pragma unroll
;   for (int j = 0; j < NJ; ++j) {
;     unsigned k = 0u;
;     if (j < nj) {
;       unsigned u = __float_as_uint(sc[64 * j + lane]);
;       u = (u == 0x80000000u) ? 0u : u;
;       k = (u & 0x80000000u) ? ~u : (u | 0x80000000u);
;     }
;     key[j] = k;
;   }
.LBB0_918:
	s_or_b64 exec, exec, s[26:27]
	v_mov_b32_e32 v0, v158
	v_readlane_b32 s0, v238, 63
	v_and_b32_e32 v0, 63, v0
	v_mov_b32_e32 v2, 0
	v_lshl_add_u32 v14, v0, 2, s0
	ds_read_b32 v104, v14 offset:8448
	ds_read_b32 v105, v14 offset:8704
	ds_read_b32 v106, v14 offset:9216
	ds_read_b32 v107, v14 offset:9472
	ds_read_b32 v108, v14 offset:9728
	ds_read_b32 v109, v14 offset:10240
	ds_read_b32 v110, v14 offset:10496
	ds_read_b32 v111, v14 offset:10752
	ds_read_b32 v112, v14 offset:11008
	ds_read_b32 v13, v14 offset:8192
	s_and_b64 vcc, exec, s[4:5]
	v_mov_b32_e32 v5, 0
	s_cbranch_vccnz .LBB0_920
	s_waitcnt lgkmcnt(0)
	v_mov_b32_e32 v3, v104
	v_cmp_ne_u32_e32 vcc, s65, v3
	s_nop 1
	v_cndmask_b32_e32 v3, 0, v3, vcc
	v_not_b32_e32 v4, v3
	v_cmp_gt_i32_e32 vcc, 0, v3
	s_nop 1
	v_cndmask_b32_e64 v5, -|v3|, v4, vcc
.LBB0_920:
	v_readlane_b32 s52, v238, 54
	v_readlane_b32 s54, v238, 43
	s_andn2_b64 vcc, exec, s[30:31]
	v_readlane_b32 s53, v238, 55
	v_readlane_b32 s55, v238, 44
	s_movk_i32 s56, 0x210
	s_cbranch_vccnz .LBB0_943
	s_waitcnt lgkmcnt(0)
	v_mov_b32_e32 v2, v105
	v_cmp_ne_u32_e32 vcc, s65, v2
	s_nop 1
	v_cndmask_b32_e32 v2, 0, v2, vcc
	v_not_b32_e32 v3, v2
	v_cmp_gt_i32_e32 vcc, 0, v2
	s_nop 1
	v_cndmask_b32_e64 v2, -|v2|, v3, vcc
	v_mov_b32_e32 v3, 0
	s_andn2_b64 vcc, exec, s[34:35]
	v_mov_b32_e32 v7, 0
	s_cbranch_vccz .LBB0_944

; template <int NJ>
; DI void b1_select(const float* sc, int nj, unsigned* mo) {
;     ...
; #pragma unroll
;   for (int j = 0; j < NJ; ++j) {
;     unsigned k = 0u;
;     if (j < nj) {
;       unsigned u = __float_as_uint(sc[64 * j + lane]);
;       u = (u == 0x80000000u) ? 0u : u;
;       k = (u & 0x80000000u) ? ~u : (u | 0x80000000u);
;     }
;     key[j] = k;
;   }
.LBB0_923:
	s_waitcnt lgkmcnt(0)
	v_mov_b32_e32 v3, v106
	v_cmp_ne_u32_e32 vcc, s65, v3
	s_nop 1
	v_cndmask_b32_e32 v3, 0, v3, vcc
	v_not_b32_e32 v4, v3
	v_cmp_gt_i32_e32 vcc, 0, v3
	s_nop 1
	v_cndmask_b32_e64 v3, -|v3|, v4, vcc
.LBB0_924:
	v_mov_b32_e32 v4, 0
	s_andn2_b64 vcc, exec, s[38:39]
	v_mov_b32_e32 v9, 0
	v_readlane_b32 s36, v237, 9
	v_readlane_b32 s37, v237, 12
	s_cbranch_vccnz .LBB0_926
	s_waitcnt lgkmcnt(0)
	v_mov_b32_e32 v6, v107
	v_cmp_ne_u32_e32 vcc, s65, v6
	s_nop 1
	v_cndmask_b32_e32 v6, 0, v6, vcc
	v_not_b32_e32 v8, v6
	v_cmp_gt_i32_e32 vcc, 0, v6
	s_nop 1
	v_cndmask_b32_e64 v9, -|v6|, v8, vcc
.LBB0_926:
	s_andn2_b64 vcc, exec, s[40:41]
	v_readlane_b32 s38, v237, 10
	v_readlane_b32 s39, v237, 11
	s_cbranch_vccnz .LBB0_945
	s_waitcnt lgkmcnt(0)
	v_mov_b32_e32 v4, v108
	v_cmp_ne_u32_e32 vcc, s65, v4
	s_nop 1
	v_cndmask_b32_e32 v4, 0, v4, vcc
	v_not_b32_e32 v6, v4
	v_cmp_gt_i32_e32 vcc, 0, v4
	s_nop 1
	v_cndmask_b32_e64 v4, -|v4|, v6, vcc
	v_mov_b32_e32 v6, 0
	s_andn2_b64 vcc, exec, s[42:43]
	v_mov_b32_e32 v10, 0
	s_cbranch_vccz .LBB0_946

; template <int NJ>
; DI void b1_select(const float* sc, int nj, unsigned* mo) {
;     ...
; #pragma unroll
;   for (int j = 0; j < NJ; ++j) {
;     unsigned k = 0u;
;     if (j < nj) {
;       unsigned u = __float_as_uint(sc[64 * j + lane]);
;       u = (u == 0x80000000u) ? 0u : u;
;       k = (u & 0x80000000u) ? ~u : (u | 0x80000000u);
;     }
;     key[j] = k;
;   }
.LBB0_929:
	s_waitcnt lgkmcnt(0)
	v_mov_b32_e32 v6, v109
	v_cmp_ne_u32_e32 vcc, s65, v6
	s_nop 1
	v_cndmask_b32_e32 v6, 0, v6, vcc
	v_not_b32_e32 v8, v6
	v_cmp_gt_i32_e32 vcc, 0, v6
	s_nop 1
	v_cndmask_b32_e64 v6, -|v6|, v8, vcc
.LBB0_930:
	v_readlane_b32 s44, v238, 47
	v_mov_b32_e32 v8, 0
	s_andn2_b64 vcc, exec, s[46:47]
	v_mov_b32_e32 v11, 0
	v_readlane_b32 s45, v238, 48
	s_cbranch_vccnz .LBB0_932
	s_waitcnt lgkmcnt(0)
	v_mov_b32_e32 v11, v110
	v_cmp_ne_u32_e32 vcc, s65, v11
	s_nop 1
	v_cndmask_b32_e32 v11, 0, v11, vcc
	v_not_b32_e32 v12, v11
	v_cmp_gt_i32_e32 vcc, 0, v11
	s_nop 1
	v_cndmask_b32_e64 v11, -|v11|, v12, vcc
.LBB0_932:
	s_andn2_b64 vcc, exec, s[48:49]
	v_readlane_b32 s46, v238, 49
	v_readlane_b32 s47, v238, 50
	s_cbranch_vccnz .LBB0_934
	s_waitcnt lgkmcnt(0)
	v_mov_b32_e32 v8, v111
	v_cmp_ne_u32_e32 vcc, s65, v8
	s_nop 1
	v_cndmask_b32_e32 v8, 0, v8, vcc
	v_not_b32_e32 v12, v8
	v_cmp_gt_i32_e32 vcc, 0, v8
	s_nop 1
	v_cndmask_b32_e64 v8, -|v8|, v12, vcc
.LBB0_934:
	v_readlane_b32 s48, v238, 45
	v_mov_b32_e32 v12, 0
	s_andn2_b64 vcc, exec, s[28:29]
	v_readlane_b32 s49, v238, 46
	s_cbranch_vccnz .LBB0_936
	s_waitcnt lgkmcnt(0)
	v_mov_b32_e32 v12, v112
	v_cmp_ne_u32_e32 vcc, s65, v12
	s_nop 1
	v_cndmask_b32_e32 v12, 0, v12, vcc
	v_not_b32_e32 v14, v12
	v_cmp_gt_i32_e32 vcc, 0, v12
	s_nop 1
	v_cndmask_b32_e64 v12, -|v12|, v14, vcc

; template <int NJ>
; DI void b1_select(const float* sc, int nj, unsigned* mo) {
;     ...
; #pragma unroll
;   for (int j = 0; j < NJ; ++j) {
;     unsigned k = 0u;
;     if (j < nj) {
;       unsigned u = __float_as_uint(sc[64 * j + lane]);
;       u = (u == 0x80000000u) ? 0u : u;
;       k = (u & 0x80000000u) ? ~u : (u | 0x80000000u);
;     }
;     key[j] = k;
;   }
.LBB0_955:
	v_cndmask_b32_e64 v0, 0, 1, s[6:7]
	s_and_b64 vcc, exec, s[10:11]
	v_cmp_ne_u32_e64 s[40:41], 1, v0
	s_cbranch_vccz .LBB0_1103
	v_mov_b32_e32 v0, v158
	v_readlane_b32 s0, v238, 63
	v_and_b32_e32 v0, 63, v0
	v_mov_b32_e32 v2, 0
	v_lshl_add_u32 v34, v0, 2, s0
	ds_read_b32 v104, v34 offset:256
	ds_read_b32 v105, v34 offset:512
	ds_read_b32 v106, v34 offset:768
	ds_read_b32 v107, v34 offset:1024
	ds_read_b32 v108, v34 offset:1280
	ds_read_b32 v109, v34 offset:1536
	ds_read_b32 v110, v34 offset:1792
	ds_read_b32 v111, v34 offset:2048
	ds_read_b32 v112, v34 offset:2304
	ds_read_b32 v113, v34 offset:2560
	ds_read_b32 v114, v34 offset:2816
	ds_read_b32 v115, v34 offset:3072
	ds_read_b32 v116, v34 offset:3328
	ds_read_b32 v117, v34 offset:3584
	ds_read_b32 v118, v34 offset:3840
	ds_read_b32 v119, v34 offset:4096
	ds_read_b32 v120, v34 offset:4352
	ds_read_b32 v121, v34 offset:4608
	ds_read_b32 v122, v34 offset:4864
	ds_read_b32 v123, v34 offset:5120
	ds_read_b32 v124, v34 offset:5376
	ds_read_b32 v125, v34 offset:5632
	ds_read_b32 v126, v34 offset:5888
	ds_read_b32 v127, v34 offset:6144
	ds_read_b32 v128, v34 offset:6400
	ds_read_b32 v129, v34 offset:6656
	ds_read_b32 v130, v34 offset:6912
	ds_read_b32 v131, v34 offset:7168
	ds_read_b32 v132, v34 offset:7424
	ds_read_b32 v133, v34 offset:7680
	ds_read_b32 v134, v34 offset:7936
	ds_read_b32 v33, v34
	s_and_b64 vcc, exec, s[40:41]
	v_mov_b32_e32 v5, 0
	s_cbranch_vccnz .LBB0_958
	s_waitcnt lgkmcnt(0)
	v_mov_b32_e32 v3, v104
	v_cmp_ne_u32_e32 vcc, s65, v3
	s_nop 1
	v_cndmask_b32_e32 v3, 0, v3, vcc
	v_not_b32_e32 v4, v3
	v_cmp_gt_i32_e32 vcc, 0, v3
	s_nop 1
	v_cndmask_b32_e64 v5, -|v3|, v4, vcc
.LBB0_958:
	s_cmp_gt_u32 s8, 4
	s_cselect_b64 s[0:1], -1, 0
	v_writelane_b32 v237, s0, 17
	s_cmp_lt_u32 s8, 5
	s_nop 0
	v_writelane_b32 v237, s1, 18
	s_cbranch_scc1 .LBB0_960
	s_waitcnt lgkmcnt(0)
	v_mov_b32_e32 v2, v105
	v_cmp_ne_u32_e32 vcc, s65, v2
	s_nop 1
	v_cndmask_b32_e32 v2, 0, v2, vcc
	v_not_b32_e32 v3, v2
	v_cmp_gt_i32_e32 vcc, 0, v2
	s_nop 1
	v_cndmask_b32_e64 v2, -|v2|, v3, vcc
.LBB0_960:
	s_cmp_gt_u32 s8, 6
	s_cselect_b64 s[0:1], -1, 0
	v_mov_b32_e32 v3, 0
	v_writelane_b32 v236, s0, 7
	s_cmp_lt_u32 s8, 7
	v_mov_b32_e32 v7, 0
	v_writelane_b32 v236, s1, 8
	s_cbranch_scc1 .LBB0_962
	s_waitcnt lgkmcnt(0)
	v_mov_b32_e32 v4, v106
	v_cmp_ne_u32_e32 vcc, s65, v4
	s_nop 1
	v_cndmask_b32_e32 v4, 0, v4, vcc
	v_not_b32_e32 v6, v4
	v_cmp_gt_i32_e32 vcc, 0, v4
	s_nop 1
	v_cndmask_b32_e64 v7, -|v4|, v6, vcc
.LBB0_962:
	s_cmp_gt_u32 s8, 8
	s_cselect_b64 s[0:1], -1, 0
	v_writelane_b32 v236, s0, 5
	s_cmp_lt_u32 s8, 9
	s_nop 0
	v_writelane_b32 v236, s1, 6
	s_cbranch_scc1 .LBB0_964
	s_waitcnt lgkmcnt(0)
	v_mov_b32_e32 v3, v107
	v_cmp_ne_u32_e32 vcc, s65, v3
	s_nop 1
	v_cndmask_b32_e32 v3, 0, v3, vcc
	v_not_b32_e32 v4, v3
	v_cmp_gt_i32_e32 vcc, 0, v3
	s_nop 1
	v_cndmask_b32_e64 v3, -|v3|, v4, vcc
.LBB0_964:
	s_cmp_gt_u32 s8, 10
	s_cselect_b64 s[0:1], -1, 0
	v_mov_b32_e32 v4, 0
	v_writelane_b32 v236, s0, 3
	s_cmp_lt_u32 s8, 11
	v_mov_b32_e32 v9, 0
	v_writelane_b32 v236, s1, 4
	s_cbranch_scc1 .LBB0_966
	s_waitcnt lgkmcnt(0)
	v_mov_b32_e32 v6, v108
	v_cmp_ne_u32_e32 vcc, s65, v6
	s_nop 1
	v_cndmask_b32_e32 v6, 0, v6, vcc
	v_not_b32_e32 v8, v6
	v_cmp_gt_i32_e32 vcc, 0, v6
	s_nop 1
	v_cndmask_b32_e64 v9, -|v6|, v8, vcc

; template <int NJ>
; DI void b1_select(const float* sc, int nj, unsigned* mo) {
;     ...
; #pragma unroll
;   for (int j = 0; j < NJ; ++j) {
;     unsigned k = 0u;
;     if (j < nj) {
;       unsigned u = __float_as_uint(sc[64 * j + lane]);
;       u = (u == 0x80000000u) ? 0u : u;
;       k = (u & 0x80000000u) ? ~u : (u | 0x80000000u);
;     }
;     key[j] = k;
;   }
.LBB0_968:
	s_cmp_gt_u32 s8, 14
	v_mov_b32_e32 v6, 0
	s_cselect_b64 s[0:1], -1, 0
	s_cmp_lt_u32 s8, 15
	v_mov_b32_e32 v11, 0
	v_writelane_b32 v237, s0, 63
	s_nop 1
	v_writelane_b32 v236, s1, 0
	s_cbranch_scc1 .LBB0_970
	s_waitcnt lgkmcnt(0)
	v_mov_b32_e32 v8, v110
	v_cmp_ne_u32_e32 vcc, s65, v8
	s_nop 1
	v_cndmask_b32_e32 v8, 0, v8, vcc
	v_not_b32_e32 v10, v8
	v_cmp_gt_i32_e32 vcc, 0, v8
	s_nop 1
	v_cndmask_b32_e64 v11, -|v8|, v10, vcc
.LBB0_970:
	s_cmp_gt_u32 s8, 16
	s_cselect_b64 s[0:1], -1, 0
	v_writelane_b32 v237, s0, 61
	s_cmp_lt_u32 s8, 17
	s_nop 0
	v_writelane_b32 v237, s1, 62
	s_cbranch_scc1 .LBB0_972
	s_waitcnt lgkmcnt(0)
	v_mov_b32_e32 v6, v111
	v_cmp_ne_u32_e32 vcc, s65, v6
	s_nop 1
	v_cndmask_b32_e32 v6, 0, v6, vcc
	v_not_b32_e32 v8, v6
	v_cmp_gt_i32_e32 vcc, 0, v6
	s_nop 1
	v_cndmask_b32_e64 v6, -|v6|, v8, vcc
.LBB0_972:
	s_cmp_gt_u32 s8, 18
	s_cselect_b64 s[0:1], -1, 0
	v_mov_b32_e32 v8, 0
	v_writelane_b32 v237, s0, 59
	s_cmp_lt_u32 s8, 19
	v_mov_b32_e32 v13, 0
	v_writelane_b32 v237, s1, 60
	s_cbranch_scc1 .LBB0_974
	s_waitcnt lgkmcnt(0)
	v_mov_b32_e32 v10, v112
	v_cmp_ne_u32_e32 vcc, s65, v10
	s_nop 1
	v_cndmask_b32_e32 v10, 0, v10, vcc
	v_not_b32_e32 v12, v10
	v_cmp_gt_i32_e32 vcc, 0, v10
	s_nop 1
	v_cndmask_b32_e64 v13, -|v10|, v12, vcc
.LBB0_974:
	s_cmp_gt_u32 s8, 20
	s_cselect_b64 s[0:1], -1, 0
	v_writelane_b32 v237, s0, 57
	s_cmp_lt_u32 s8, 21
	s_nop 0
	v_writelane_b32 v237, s1, 58
	s_cbranch_scc1 .LBB0_976
	s_waitcnt lgkmcnt(0)
	v_mov_b32_e32 v8, v113
	v_cmp_ne_u32_e32 vcc, s65, v8
	s_nop 1
	v_cndmask_b32_e32 v8, 0, v8, vcc
	v_not_b32_e32 v10, v8
	v_cmp_gt_i32_e32 vcc, 0, v8
	s_nop 1
	v_cndmask_b32_e64 v8, -|v8|, v10, vcc
.LBB0_976:
	s_cmp_gt_u32 s8, 22
	s_cselect_b64 s[0:1], -1, 0
	v_mov_b32_e32 v10, 0
	v_writelane_b32 v237, s0, 55
	s_cmp_lt_u32 s8, 23
	v_mov_b32_e32 v15, 0
	v_writelane_b32 v237, s1, 56
	s_cbranch_scc1 .LBB0_978
	s_waitcnt lgkmcnt(0)
	v_mov_b32_e32 v12, v114
	v_cmp_ne_u32_e32 vcc, s65, v12
	s_nop 1
	v_cndmask_b32_e32 v12, 0, v12, vcc
	v_not_b32_e32 v14, v12
	v_cmp_gt_i32_e32 vcc, 0, v12
	s_nop 1
	v_cndmask_b32_e64 v15, -|v12|, v14, vcc
.LBB0_978:
	s_cmp_gt_u32 s8, 24
	s_cselect_b64 s[0:1], -1, 0
	v_writelane_b32 v237, s0, 53
	s_cmp_lt_u32 s8, 25
	s_nop 0
	v_writelane_b32 v237, s1, 54
	s_cbranch_scc1 .LBB0_980
	s_waitcnt lgkmcnt(0)
	v_mov_b32_e32 v10, v115
	v_cmp_ne_u32_e32 vcc, s65, v10
	s_nop 1
	v_cndmask_b32_e32 v10, 0, v10, vcc
	v_not_b32_e32 v12, v10
	v_cmp_gt_i32_e32 vcc, 0, v10
	s_nop 1
	v_cndmask_b32_e64 v10, -|v10|, v12, vcc
.LBB0_980:
	s_cmp_gt_u32 s8, 26
	s_cselect_b64 s[0:1], -1, 0
	v_mov_b32_e32 v12, 0
	v_writelane_b32 v237, s0, 51
	s_cmp_lt_u32 s8, 27
	v_mov_b32_e32 v17, 0
	v_writelane_b32 v237, s1, 52
	s_cbranch_scc1 .LBB0_982
	s_waitcnt lgkmcnt(0)
	v_mov_b32_e32 v14, v116
	v_cmp_ne_u32_e32 vcc, s65, v14
	s_nop 1
	v_cndmask_b32_e32 v14, 0, v14, vcc
	v_not_b32_e32 v16, v14
	v_cmp_gt_i32_e32 vcc, 0, v14
	s_nop 1
	v_cndmask_b32_e64 v17, -|v14|, v16, vcc
.LBB0_982:
	s_cmp_gt_u32 s8, 28
	s_cselect_b64 s[0:1], -1, 0
	v_writelane_b32 v237, s0, 49
	s_cmp_lt_u32 s8, 29
	s_nop 0
	v_writelane_b32 v237, s1, 50
	s_cbranch_scc1 .LBB0_984
	s_waitcnt lgkmcnt(0)
	v_mov_b32_e32 v12, v117
	v_cmp_ne_u32_e32 vcc, s65, v12
	s_nop 1
	v_cndmask_b32_e32 v12, 0, v12, vcc
	v_not_b32_e32 v14, v12
	v_cmp_gt_i32_e32 vcc, 0, v12
	s_nop 1
	v_cndmask_b32_e64 v12, -|v12|, v14, vcc
.LBB0_984:
	s_cmp_gt_u32 s8, 30
	s_cselect_b64 s[0:1], -1, 0
	v_mov_b32_e32 v14, 0
	v_writelane_b32 v237, s0, 23
	s_cmp_lt_u32 s8, 31
	v_mov_b32_e32 v19, 0
	v_writelane_b32 v237, s1, 24
	s_cbranch_scc1 .LBB0_986
	s_waitcnt lgkmcnt(0)
	v_mov_b32_e32 v16, v118
	v_cmp_ne_u32_e32 vcc, s65, v16
	s_nop 1
	v_cndmask_b32_e32 v16, 0, v16, vcc
	v_not_b32_e32 v18, v16
	v_cmp_gt_i32_e32 vcc, 0, v16
	s_nop 1
	v_cndmask_b32_e64 v19, -|v16|, v18, vcc
.LBB0_986:
	s_cmp_gt_u32 s8, 32
	s_cselect_b64 s[0:1], -1, 0
	v_writelane_b32 v237, s0, 47
	s_cmp_lt_u32 s8, 33
	s_nop 0
	v_writelane_b32 v237, s1, 48
	s_cbranch_scc1 .LBB0_988
	s_waitcnt lgkmcnt(0)
	v_mov_b32_e32 v14, v119
	v_cmp_ne_u32_e32 vcc, s65, v14
	s_nop 1
	v_cndmask_b32_e32 v14, 0, v14, vcc
	v_not_b32_e32 v16, v14
	v_cmp_gt_i32_e32 vcc, 0, v14
	s_nop 1
	v_cndmask_b32_e64 v14, -|v14|, v16, vcc
.LBB0_988:
	s_cmp_gt_u32 s8, 34
	s_cselect_b64 s[0:1], -1, 0
	v_mov_b32_e32 v16, 0
	v_writelane_b32 v237, s0, 45
	s_cmp_lt_u32 s8, 35
	v_mov_b32_e32 v21, 0
	v_writelane_b32 v237, s1, 46
	s_cbranch_scc1 .LBB0_990
	s_waitcnt lgkmcnt(0)
	v_mov_b32_e32 v18, v120
	v_cmp_ne_u32_e32 vcc, s65, v18
	s_nop 1
	v_cndmask_b32_e32 v18, 0, v18, vcc
	v_not_b32_e32 v20, v18
	v_cmp_gt_i32_e32 vcc, 0, v18
	s_nop 1
	v_cndmask_b32_e64 v21, -|v18|, v20, vcc
.LBB0_990:
	s_cmp_gt_u32 s8, 36
	s_cselect_b64 s[0:1], -1, 0
	v_writelane_b32 v237, s0, 43
	s_cmp_lt_u32 s8, 37
	s_nop 0
	v_writelane_b32 v237, s1, 44
	s_cbranch_scc1 .LBB0_992
	s_waitcnt lgkmcnt(0)
	v_mov_b32_e32 v16, v121
	v_cmp_ne_u32_e32 vcc, s65, v16
	s_nop 1
	v_cndmask_b32_e32 v16, 0, v16, vcc
	v_not_b32_e32 v18, v16
	v_cmp_gt_i32_e32 vcc, 0, v16
	s_nop 1
	v_cndmask_b32_e64 v16, -|v16|, v18, vcc
.LBB0_992:
	s_cmp_gt_u32 s8, 38
	s_cselect_b64 s[0:1], -1, 0
	v_mov_b32_e32 v18, 0
	v_writelane_b32 v237, s0, 41
	s_cmp_lt_u32 s8, 39
	v_mov_b32_e32 v23, 0
	v_writelane_b32 v237, s1, 42
	s_cbranch_scc1 .LBB0_994
	s_waitcnt lgkmcnt(0)
	v_mov_b32_e32 v20, v122
	v_cmp_ne_u32_e32 vcc, s65, v20
	s_nop 1
	v_cndmask_b32_e32 v20, 0, v20, vcc
	v_not_b32_e32 v22, v20
	v_cmp_gt_i32_e32 vcc, 0, v20
	s_nop 1
	v_cndmask_b32_e64 v23, -|v20|, v22, vcc
; template <int NJ>
; DI void b1_select(const float* sc, int nj, unsigned* mo) {
;     ...
; #pragma unroll
;   for (int j = 0; j < NJ; ++j) {
;     unsigned k = 0u;
;     if (j < nj) {
;       unsigned u = __float_as_uint(sc[64 * j + lane]);
;       u = (u == 0x80000000u) ? 0u : u;
;       k = (u & 0x80000000u) ? ~u : (u | 0x80000000u);
;     }
;     key[j] = k;
;   }
.LBB0_994:
	s_cmp_gt_u32 s8, 40
	s_cselect_b64 s[0:1], -1, 0
	v_writelane_b32 v237, s0, 39
	s_cmp_lt_u32 s8, 41
	s_nop 0
	v_writelane_b32 v237, s1, 40
	s_cbranch_scc1 .LBB0_996
	s_waitcnt lgkmcnt(0)
	v_mov_b32_e32 v18, v123
	v_cmp_ne_u32_e32 vcc, s65, v18
	s_nop 1
	v_cndmask_b32_e32 v18, 0, v18, vcc
	v_not_b32_e32 v20, v18
	v_cmp_gt_i32_e32 vcc, 0, v18
	s_nop 1
	v_cndmask_b32_e64 v18, -|v18|, v20, vcc
.LBB0_996:
	s_cmp_gt_u32 s8, 42
	s_cselect_b64 s[0:1], -1, 0
	v_mov_b32_e32 v20, 0
	v_writelane_b32 v237, s0, 35
	s_cmp_lt_u32 s8, 43
	v_mov_b32_e32 v26, 0
	v_writelane_b32 v237, s1, 36
	s_cbranch_scc1 .LBB0_998
	s_waitcnt lgkmcnt(0)
	v_mov_b32_e32 v22, v124
	v_cmp_ne_u32_e32 vcc, s65, v22
	s_nop 1
	v_cndmask_b32_e32 v22, 0, v22, vcc
	v_not_b32_e32 v24, v22
	v_cmp_gt_i32_e32 vcc, 0, v22
	s_nop 1
	v_cndmask_b32_e64 v26, -|v22|, v24, vcc
.LBB0_998:
	s_cmp_gt_u32 s8, 44
	s_cselect_b64 s[0:1], -1, 0
	v_writelane_b32 v237, s0, 33
	s_cmp_lt_u32 s8, 45
	s_nop 0
	v_writelane_b32 v237, s1, 34
	s_cbranch_scc1 .LBB0_1000
	s_waitcnt lgkmcnt(0)
	v_mov_b32_e32 v20, v125
	v_cmp_ne_u32_e32 vcc, s65, v20
	s_nop 1
	v_cndmask_b32_e32 v20, 0, v20, vcc
	v_not_b32_e32 v22, v20
	v_cmp_gt_i32_e32 vcc, 0, v20
	s_nop 1
	v_cndmask_b32_e64 v20, -|v20|, v22, vcc
.LBB0_1000:
	s_cmp_gt_u32 s8, 46
	s_cselect_b64 s[0:1], -1, 0
	v_mov_b32_e32 v22, 0
	v_writelane_b32 v237, s0, 31
	s_cmp_lt_u32 s8, 47
	v_mov_b32_e32 v28, 0
	v_writelane_b32 v237, s1, 32
	s_cbranch_scc1 .LBB0_1002
	s_waitcnt lgkmcnt(0)
	v_mov_b32_e32 v24, v126
	v_cmp_ne_u32_e32 vcc, s65, v24
	s_nop 1
	v_cndmask_b32_e32 v24, 0, v24, vcc
	v_not_b32_e32 v25, v24
	v_cmp_gt_i32_e32 vcc, 0, v24
	s_nop 1
	v_cndmask_b32_e64 v28, -|v24|, v25, vcc
.LBB0_1002:
	s_cmp_gt_u32 s8, 48
	s_cselect_b64 s[0:1], -1, 0
	v_writelane_b32 v237, s0, 37
	s_cmp_lt_u32 s8, 49
	s_nop 0
	v_writelane_b32 v237, s1, 38
	s_cbranch_scc1 .LBB0_1004
	s_waitcnt lgkmcnt(0)
	v_mov_b32_e32 v22, v127
	v_cmp_ne_u32_e32 vcc, s65, v22
	s_nop 1
	v_cndmask_b32_e32 v22, 0, v22, vcc
	v_not_b32_e32 v24, v22
	v_cmp_gt_i32_e32 vcc, 0, v22
	s_nop 1
	v_cndmask_b32_e64 v22, -|v22|, v24, vcc
.LBB0_1004:
	s_cmp_gt_u32 s8, 50
	s_cselect_b64 s[0:1], -1, 0
	v_mov_b32_e32 v24, 0
	v_writelane_b32 v237, s0, 29
	s_cmp_lt_u32 s8, 51
	v_mov_b32_e32 v29, 0
	v_writelane_b32 v237, s1, 30
	s_cbranch_scc1 .LBB0_1006
	s_waitcnt lgkmcnt(0)
	v_mov_b32_e32 v25, v128
	v_cmp_ne_u32_e32 vcc, s65, v25
	s_nop 1
	v_cndmask_b32_e32 v25, 0, v25, vcc
	v_not_b32_e32 v27, v25
	v_cmp_gt_i32_e32 vcc, 0, v25
	s_nop 1
	v_cndmask_b32_e64 v29, -|v25|, v27, vcc
.LBB0_1006:
	s_cmp_gt_u32 s8, 52
	s_cselect_b64 s[0:1], -1, 0
	v_writelane_b32 v237, s0, 27
	s_cmp_lt_u32 s8, 53
	s_nop 0
	v_writelane_b32 v237, s1, 28
	s_cbranch_scc1 .LBB0_1008
	s_waitcnt lgkmcnt(0)
	v_mov_b32_e32 v24, v129
	v_cmp_ne_u32_e32 vcc, s65, v24
	s_nop 1
	v_cndmask_b32_e32 v24, 0, v24, vcc
	v_not_b32_e32 v25, v24
	v_cmp_gt_i32_e32 vcc, 0, v24
	s_nop 1
	v_cndmask_b32_e64 v24, -|v24|, v25, vcc
.LBB0_1008:
	s_cmp_gt_u32 s8, 54
	s_cselect_b64 s[0:1], -1, 0
	v_mov_b32_e32 v25, 0
	v_writelane_b32 v237, s0, 25
	s_cmp_lt_u32 s8, 55
	v_mov_b32_e32 v30, 0
	v_writelane_b32 v237, s1, 26
	s_cbranch_scc1 .LBB0_1010
	s_waitcnt lgkmcnt(0)
	v_mov_b32_e32 v27, v130
	v_cmp_ne_u32_e32 vcc, s65, v27
	s_nop 1
	v_cndmask_b32_e32 v27, 0, v27, vcc
	v_not_b32_e32 v30, v27
	v_cmp_gt_i32_e32 vcc, 0, v27
	s_nop 1
	v_cndmask_b32_e64 v30, -|v27|, v30, vcc
.LBB0_1010:
	s_cmp_gt_u32 s8, 56
	s_cselect_b64 s[0:1], -1, 0
	v_writelane_b32 v236, s0, 11
	s_cmp_lt_u32 s8, 57
	s_nop 0
	v_writelane_b32 v236, s1, 12
	s_cbranch_scc1 .LBB0_1012
	s_waitcnt lgkmcnt(0)
	v_mov_b32_e32 v25, v131
	v_cmp_ne_u32_e32 vcc, s65, v25
	s_nop 1
	v_cndmask_b32_e32 v25, 0, v25, vcc
	v_not_b32_e32 v27, v25
	v_cmp_gt_i32_e32 vcc, 0, v25
	s_nop 1
	v_cndmask_b32_e64 v25, -|v25|, v27, vcc
.LBB0_1012:
	s_cmp_gt_u32 s8, 58
	s_cselect_b64 s[0:1], -1, 0
	v_mov_b32_e32 v27, 0
	v_writelane_b32 v236, s0, 17
	s_cmp_lt_u32 s8, 59
	v_mov_b32_e32 v31, 0
	v_writelane_b32 v236, s1, 18
	s_cbranch_scc1 .LBB0_1014
	s_waitcnt lgkmcnt(0)
	v_mov_b32_e32 v31, v132
	v_cmp_ne_u32_e32 vcc, s65, v31
	s_nop 1
	v_cndmask_b32_e32 v31, 0, v31, vcc
	v_not_b32_e32 v32, v31
	v_cmp_gt_i32_e32 vcc, 0, v31
	s_nop 1
	v_cndmask_b32_e64 v31, -|v31|, v32, vcc
.LBB0_1014:
	s_cmp_gt_u32 s8, 60
	s_cselect_b64 s[0:1], -1, 0
	v_writelane_b32 v236, s0, 15
	s_cmp_lt_u32 s8, 61
	s_nop 0
	v_writelane_b32 v236, s1, 16
	s_cbranch_scc1 .LBB0_1016
	s_waitcnt lgkmcnt(0)
	v_mov_b32_e32 v27, v133
	v_cmp_ne_u32_e32 vcc, s65, v27
	s_nop 1
	v_cndmask_b32_e32 v27, 0, v27, vcc
	v_not_b32_e32 v32, v27
	v_cmp_gt_i32_e32 vcc, 0, v27
	s_nop 1
	v_cndmask_b32_e64 v27, -|v27|, v32, vcc
.LBB0_1016:
	s_cmp_gt_u32 s8, 62
	s_cselect_b64 s[0:1], -1, 0
	v_writelane_b32 v237, s0, 21
	s_cmp_lt_u32 s8, 63
	v_mov_b32_e32 v32, 0
	v_writelane_b32 v237, s1, 22
	s_cbranch_scc1 .LBB0_1018
	s_waitcnt lgkmcnt(0)
	v_mov_b32_e32 v32, v134
	v_cmp_ne_u32_e32 vcc, s65, v32
	s_nop 1
	v_cndmask_b32_e32 v32, 0, v32, vcc
	v_not_b32_e32 v34, v32
	v_cmp_gt_i32_e32 vcc, 0, v32
	s_nop 1
	v_cndmask_b32_e64 v32, -|v32|, v34, vcc

; template <int NJ>
; DI void b1_select(const float* sc, int nj, unsigned* mo) {
;     ...
; #pragma unroll
;   for (int j = 0; j < NJ; ++j) {
;     unsigned k = 0u;
;     if (j < nj) {
;       unsigned u = __float_as_uint(sc[64 * j + lane]);
;       u = (u == 0x80000000u) ? 0u : u;
;       k = (u & 0x80000000u) ? ~u : (u | 0x80000000u);
;     }
;     key[j] = k;
;   }
.LBB0_1029:
	s_or_b64 exec, exec, s[68:69]
	v_mov_b32_e32 v0, v158
	v_readlane_b32 s0, v238, 63
	v_and_b32_e32 v0, 63, v0
	v_mov_b32_e32 v2, 0
	v_lshl_add_u32 v34, v0, 2, s0
	ds_read_b32 v104, v34 offset:8448
	ds_read_b32 v105, v34 offset:8704
	ds_read_b32 v106, v34 offset:8960
	ds_read_b32 v107, v34 offset:9216
	ds_read_b32 v108, v34 offset:9472
	ds_read_b32 v109, v34 offset:9728
	ds_read_b32 v110, v34 offset:9984
	ds_read_b32 v111, v34 offset:10240
	ds_read_b32 v112, v34 offset:10496
	ds_read_b32 v113, v34 offset:10752
	ds_read_b32 v114, v34 offset:11008
	ds_read_b32 v115, v34 offset:11264
	ds_read_b32 v116, v34 offset:11520
	ds_read_b32 v117, v34 offset:11776
	ds_read_b32 v118, v34 offset:12032
	ds_read_b32 v119, v34 offset:12288
	ds_read_b32 v120, v34 offset:12544
	ds_read_b32 v121, v34 offset:12800
	ds_read_b32 v122, v34 offset:13056
	ds_read_b32 v123, v34 offset:13312
	ds_read_b32 v124, v34 offset:13568
	ds_read_b32 v125, v34 offset:13824
	ds_read_b32 v126, v34 offset:14080
	ds_read_b32 v127, v34 offset:14336
	ds_read_b32 v128, v34 offset:14592
	ds_read_b32 v129, v34 offset:14848
	ds_read_b32 v130, v34 offset:15104
	ds_read_b32 v131, v34 offset:15360
	ds_read_b32 v132, v34 offset:15616
	ds_read_b32 v133, v34 offset:15872
	ds_read_b32 v134, v34 offset:16128
	ds_read_b32 v33, v34 offset:8192
	v_readlane_b32 s0, v237, 19
	v_readlane_b32 s1, v237, 20
	s_and_b64 vcc, exec, s[0:1]
	v_mov_b32_e32 v5, 0
	s_brev_b32 s0, 1
	s_cbranch_vccnz .LBB0_1031
	s_waitcnt lgkmcnt(0)
	v_mov_b32_e32 v3, v104
	v_cmp_ne_u32_e32 vcc, s0, v3
	s_nop 1
	v_cndmask_b32_e32 v3, 0, v3, vcc
	v_not_b32_e32 v4, v3
	v_cmp_gt_i32_e32 vcc, 0, v3
	s_nop 1
	v_cndmask_b32_e64 v5, -|v3|, v4, vcc
.LBB0_1031:
	v_readlane_b32 s2, v237, 17
	v_readlane_b32 s3, v237, 18
	s_andn2_b64 vcc, exec, s[2:3]
	s_cbranch_vccnz .LBB0_1033
	s_waitcnt lgkmcnt(0)
	v_mov_b32_e32 v2, v105
	v_cmp_ne_u32_e32 vcc, s0, v2
	s_nop 1
	v_cndmask_b32_e32 v2, 0, v2, vcc
	v_not_b32_e32 v3, v2
	v_cmp_gt_i32_e32 vcc, 0, v2
	s_nop 1
	v_cndmask_b32_e64 v2, -|v2|, v3, vcc
.LBB0_1033:
	v_readlane_b32 s2, v236, 7
	v_readlane_b32 s3, v236, 8
	v_mov_b32_e32 v3, 0
	s_andn2_b64 vcc, exec, s[2:3]
	v_mov_b32_e32 v7, 0
	s_cbranch_vccnz .LBB0_1035
	s_waitcnt lgkmcnt(0)
	v_mov_b32_e32 v4, v106
	v_cmp_ne_u32_e32 vcc, s0, v4
	s_nop 1
	v_cndmask_b32_e32 v4, 0, v4, vcc
	v_not_b32_e32 v6, v4
	v_cmp_gt_i32_e32 vcc, 0, v4
	s_nop 1
	v_cndmask_b32_e64 v7, -|v4|, v6, vcc
.LBB0_1035:
	v_readlane_b32 s2, v236, 5
	v_readlane_b32 s3, v236, 6
	s_andn2_b64 vcc, exec, s[2:3]
	s_cbranch_vccnz .LBB0_1037
	s_waitcnt lgkmcnt(0)
	v_mov_b32_e32 v3, v107
	v_cmp_ne_u32_e32 vcc, s0, v3
	s_nop 1
	v_cndmask_b32_e32 v3, 0, v3, vcc
	v_not_b32_e32 v4, v3
	v_cmp_gt_i32_e32 vcc, 0, v3
	s_nop 1
	v_cndmask_b32_e64 v3, -|v3|, v4, vcc
.LBB0_1037:
	v_readlane_b32 s2, v236, 3
	v_readlane_b32 s3, v236, 4
	v_mov_b32_e32 v4, 0
	s_andn2_b64 vcc, exec, s[2:3]
	v_mov_b32_e32 v9, 0
	s_cbranch_vccnz .LBB0_1039
	s_waitcnt lgkmcnt(0)
	v_mov_b32_e32 v6, v108
	v_cmp_ne_u32_e32 vcc, s0, v6
	s_nop 1
	v_cndmask_b32_e32 v6, 0, v6, vcc
	v_not_b32_e32 v8, v6
	v_cmp_gt_i32_e32 vcc, 0, v6
	s_nop 1
	v_cndmask_b32_e64 v9, -|v6|, v8, vcc
.LBB0_1039:
	v_readlane_b32 s2, v236, 1
	v_readlane_b32 s3, v236, 2
	s_andn2_b64 vcc, exec, s[2:3]
	s_cbranch_vccnz .LBB0_1041
	s_waitcnt lgkmcnt(0)
	v_mov_b32_e32 v4, v109
	v_cmp_ne_u32_e32 vcc, s0, v4
	s_nop 1
	v_cndmask_b32_e32 v4, 0, v4, vcc
	v_not_b32_e32 v6, v4
	v_cmp_gt_i32_e32 vcc, 0, v4
	s_nop 1
	v_cndmask_b32_e64 v4, -|v4|, v6, vcc
.LBB0_1041:
	v_readlane_b32 s2, v237, 63
	v_readlane_b32 s3, v236, 0
	v_mov_b32_e32 v6, 0
	s_andn2_b64 vcc, exec, s[2:3]
	v_mov_b32_e32 v11, 0
	s_cbranch_vccnz .LBB0_1043
	s_waitcnt lgkmcnt(0)
	v_mov_b32_e32 v8, v110
	v_cmp_ne_u32_e32 vcc, s0, v8
	s_nop 1
	v_cndmask_b32_e32 v8, 0, v8, vcc
	v_not_b32_e32 v10, v8
	v_cmp_gt_i32_e32 vcc, 0, v8
	s_nop 1
	v_cndmask_b32_e64 v11, -|v8|, v10, vcc
.LBB0_1043:
	v_readlane_b32 s2, v237, 61
	v_readlane_b32 s3, v237, 62
	s_andn2_b64 vcc, exec, s[2:3]
	s_cbranch_vccnz .LBB0_1045
	s_waitcnt lgkmcnt(0)
	v_mov_b32_e32 v6, v111
	v_cmp_ne_u32_e32 vcc, s0, v6
	s_nop 1
	v_cndmask_b32_e32 v6, 0, v6, vcc
	v_not_b32_e32 v8, v6
	v_cmp_gt_i32_e32 vcc, 0, v6
	s_nop 1
	v_cndmask_b32_e64 v6, -|v6|, v8, vcc
.LBB0_1045:
	v_readlane_b32 s2, v237, 59
	v_readlane_b32 s3, v237, 60
	v_mov_b32_e32 v8, 0
	s_andn2_b64 vcc, exec, s[2:3]
	v_mov_b32_e32 v13, 0
	s_cbranch_vccnz .LBB0_1047
	s_waitcnt lgkmcnt(0)
	v_mov_b32_e32 v10, v112
	v_cmp_ne_u32_e32 vcc, s0, v10
	s_nop 1
	v_cndmask_b32_e32 v10, 0, v10, vcc
	v_not_b32_e32 v12, v10
	v_cmp_gt_i32_e32 vcc, 0, v10
	s_nop 1
	v_cndmask_b32_e64 v13, -|v10|, v12, vcc
.LBB0_1047:
	v_readlane_b32 s2, v237, 57
	v_readlane_b32 s3, v237, 58
	s_andn2_b64 vcc, exec, s[2:3]
	s_cbranch_vccnz .LBB0_1049
	s_waitcnt lgkmcnt(0)
	v_mov_b32_e32 v8, v113
	v_cmp_ne_u32_e32 vcc, s0, v8
	s_nop 1
	v_cndmask_b32_e32 v8, 0, v8, vcc
	v_not_b32_e32 v10, v8
	v_cmp_gt_i32_e32 vcc, 0, v8
	s_nop 1
	v_cndmask_b32_e64 v8, -|v8|, v10, vcc
.LBB0_1049:
	v_readlane_b32 s2, v237, 55
	v_readlane_b32 s3, v237, 56
	v_mov_b32_e32 v10, 0
	s_andn2_b64 vcc, exec, s[2:3]
	v_mov_b32_e32 v15, 0
	s_cbranch_vccnz .LBB0_1051
	s_waitcnt lgkmcnt(0)
	v_mov_b32_e32 v12, v114
	v_cmp_ne_u32_e32 vcc, s0, v12
	s_nop 1
	v_cndmask_b32_e32 v12, 0, v12, vcc
	v_not_b32_e32 v14, v12
	v_cmp_gt_i32_e32 vcc, 0, v12
	s_nop 1
	v_cndmask_b32_e64 v15, -|v12|, v14, vcc
.LBB0_1051:
	v_readlane_b32 s2, v237, 53
	v_readlane_b32 s3, v237, 54
	s_andn2_b64 vcc, exec, s[2:3]
	s_cbranch_vccnz .LBB0_1053
	s_waitcnt lgkmcnt(0)
	v_mov_b32_e32 v10, v115
	v_cmp_ne_u32_e32 vcc, s0, v10
	s_nop 1
	v_cndmask_b32_e32 v10, 0, v10, vcc
	v_not_b32_e32 v12, v10
	v_cmp_gt_i32_e32 vcc, 0, v10
	s_nop 1
	v_cndmask_b32_e64 v10, -|v10|, v12, vcc
; template <int NJ>
; DI void b1_select(const float* sc, int nj, unsigned* mo) {
;     ...
; #pragma unroll
;   for (int j = 0; j < NJ; ++j) {
;     unsigned k = 0u;
;     if (j < nj) {
;       unsigned u = __float_as_uint(sc[64 * j + lane]);
;       u = (u == 0x80000000u) ? 0u : u;
;       k = (u & 0x80000000u) ? ~u : (u | 0x80000000u);
;     }
;     key[j] = k;
;   }
.LBB0_1053:
	v_readlane_b32 s2, v237, 51
	v_readlane_b32 s3, v237, 52
	v_mov_b32_e32 v12, 0
	s_andn2_b64 vcc, exec, s[2:3]
	v_mov_b32_e32 v17, 0
	s_cbranch_vccnz .LBB0_1055
	s_waitcnt lgkmcnt(0)
	v_mov_b32_e32 v14, v116
	v_cmp_ne_u32_e32 vcc, s0, v14
	s_nop 1
	v_cndmask_b32_e32 v14, 0, v14, vcc
	v_not_b32_e32 v16, v14
	v_cmp_gt_i32_e32 vcc, 0, v14
	s_nop 1
	v_cndmask_b32_e64 v17, -|v14|, v16, vcc
.LBB0_1055:
	v_readlane_b32 s2, v237, 49
	v_readlane_b32 s3, v237, 50
	s_andn2_b64 vcc, exec, s[2:3]
	s_cbranch_vccnz .LBB0_1057
	s_waitcnt lgkmcnt(0)
	v_mov_b32_e32 v12, v117
	v_cmp_ne_u32_e32 vcc, s0, v12
	s_nop 1
	v_cndmask_b32_e32 v12, 0, v12, vcc
	v_not_b32_e32 v14, v12
	v_cmp_gt_i32_e32 vcc, 0, v12
	s_nop 1
	v_cndmask_b32_e64 v12, -|v12|, v14, vcc
.LBB0_1057:
	v_readlane_b32 s2, v237, 23
	v_readlane_b32 s3, v237, 24
	v_mov_b32_e32 v14, 0
	s_andn2_b64 vcc, exec, s[2:3]
	v_mov_b32_e32 v19, 0
	s_cbranch_vccnz .LBB0_1059
	s_waitcnt lgkmcnt(0)
	v_mov_b32_e32 v16, v118
	v_cmp_ne_u32_e32 vcc, s0, v16
	s_nop 1
	v_cndmask_b32_e32 v16, 0, v16, vcc
	v_not_b32_e32 v18, v16
	v_cmp_gt_i32_e32 vcc, 0, v16
	s_nop 1
	v_cndmask_b32_e64 v19, -|v16|, v18, vcc
.LBB0_1059:
	v_readlane_b32 s2, v237, 47
	v_readlane_b32 s3, v237, 48
	s_andn2_b64 vcc, exec, s[2:3]
	s_cbranch_vccnz .LBB0_1061
	s_waitcnt lgkmcnt(0)
	v_mov_b32_e32 v14, v119
	v_cmp_ne_u32_e32 vcc, s0, v14
	s_nop 1
	v_cndmask_b32_e32 v14, 0, v14, vcc
	v_not_b32_e32 v16, v14
	v_cmp_gt_i32_e32 vcc, 0, v14
	s_nop 1
	v_cndmask_b32_e64 v14, -|v14|, v16, vcc
.LBB0_1061:
	v_readlane_b32 s2, v237, 45
	v_readlane_b32 s3, v237, 46
	v_mov_b32_e32 v16, 0
	s_andn2_b64 vcc, exec, s[2:3]
	v_mov_b32_e32 v21, 0
	s_cbranch_vccnz .LBB0_1063
	s_waitcnt lgkmcnt(0)
	v_mov_b32_e32 v18, v120
	v_cmp_ne_u32_e32 vcc, s0, v18
	s_nop 1
	v_cndmask_b32_e32 v18, 0, v18, vcc
	v_not_b32_e32 v20, v18
	v_cmp_gt_i32_e32 vcc, 0, v18
	s_nop 1
	v_cndmask_b32_e64 v21, -|v18|, v20, vcc
.LBB0_1063:
	v_readlane_b32 s2, v237, 43
	v_readlane_b32 s3, v237, 44
	s_andn2_b64 vcc, exec, s[2:3]
	s_cbranch_vccnz .LBB0_1065
	s_waitcnt lgkmcnt(0)
	v_mov_b32_e32 v16, v121
	v_cmp_ne_u32_e32 vcc, s0, v16
	s_nop 1
	v_cndmask_b32_e32 v16, 0, v16, vcc
	v_not_b32_e32 v18, v16
	v_cmp_gt_i32_e32 vcc, 0, v16
	s_nop 1
	v_cndmask_b32_e64 v16, -|v16|, v18, vcc
.LBB0_1065:
	v_readlane_b32 s2, v237, 41
	v_readlane_b32 s3, v237, 42
	v_mov_b32_e32 v18, 0
	s_andn2_b64 vcc, exec, s[2:3]
	v_mov_b32_e32 v23, 0
	s_cbranch_vccnz .LBB0_1067
	s_waitcnt lgkmcnt(0)
	v_mov_b32_e32 v20, v122
	v_cmp_ne_u32_e32 vcc, s0, v20
	s_nop 1
	v_cndmask_b32_e32 v20, 0, v20, vcc
	v_not_b32_e32 v22, v20
	v_cmp_gt_i32_e32 vcc, 0, v20
	s_nop 1
	v_cndmask_b32_e64 v23, -|v20|, v22, vcc
.LBB0_1067:
	v_readlane_b32 s2, v237, 39
	v_readlane_b32 s3, v237, 40
	s_andn2_b64 vcc, exec, s[2:3]
	s_cbranch_vccnz .LBB0_1069
	s_waitcnt lgkmcnt(0)
	v_mov_b32_e32 v18, v123
	v_cmp_ne_u32_e32 vcc, s0, v18
	s_nop 1
	v_cndmask_b32_e32 v18, 0, v18, vcc
	v_not_b32_e32 v20, v18
	v_cmp_gt_i32_e32 vcc, 0, v18
	s_nop 1
	v_cndmask_b32_e64 v18, -|v18|, v20, vcc
.LBB0_1069:
	v_readlane_b32 s2, v237, 35
	v_readlane_b32 s3, v237, 36
	v_mov_b32_e32 v20, 0
	s_andn2_b64 vcc, exec, s[2:3]
	v_mov_b32_e32 v26, 0
	s_cbranch_vccnz .LBB0_1071
	s_waitcnt lgkmcnt(0)
	v_mov_b32_e32 v22, v124
	v_cmp_ne_u32_e32 vcc, s0, v22
	s_nop 1
	v_cndmask_b32_e32 v22, 0, v22, vcc
	v_not_b32_e32 v24, v22
	v_cmp_gt_i32_e32 vcc, 0, v22
	s_nop 1
	v_cndmask_b32_e64 v26, -|v22|, v24, vcc
; template <int NJ>
; DI void b1_select(const float* sc, int nj, unsigned* mo) {
;     ...
; #pragma unroll
;   for (int j = 0; j < NJ; ++j) {
;     unsigned k = 0u;
;     if (j < nj) {
;       unsigned u = __float_as_uint(sc[64 * j + lane]);
;       u = (u == 0x80000000u) ? 0u : u;
;       k = (u & 0x80000000u) ? ~u : (u | 0x80000000u);
;     }
;     key[j] = k;
;   }
.LBB0_1071:
	v_readlane_b32 s2, v237, 33
	v_readlane_b32 s3, v237, 34
	s_andn2_b64 vcc, exec, s[2:3]
	s_cbranch_vccnz .LBB0_1073
	s_waitcnt lgkmcnt(0)
	v_mov_b32_e32 v20, v125
	v_cmp_ne_u32_e32 vcc, s0, v20
	s_nop 1
	v_cndmask_b32_e32 v20, 0, v20, vcc
	v_not_b32_e32 v22, v20
	v_cmp_gt_i32_e32 vcc, 0, v20
	s_nop 1
	v_cndmask_b32_e64 v20, -|v20|, v22, vcc
.LBB0_1073:
	v_readlane_b32 s2, v237, 31
	v_readlane_b32 s3, v237, 32
	v_mov_b32_e32 v22, 0
	s_andn2_b64 vcc, exec, s[2:3]
	v_mov_b32_e32 v28, 0
	s_cbranch_vccnz .LBB0_1075
	s_waitcnt lgkmcnt(0)
	v_mov_b32_e32 v24, v126
	v_cmp_ne_u32_e32 vcc, s0, v24
	s_nop 1
	v_cndmask_b32_e32 v24, 0, v24, vcc
	v_not_b32_e32 v25, v24
	v_cmp_gt_i32_e32 vcc, 0, v24
	s_nop 1
	v_cndmask_b32_e64 v28, -|v24|, v25, vcc
.LBB0_1075:
	v_readlane_b32 s2, v237, 37
	v_readlane_b32 s3, v237, 38
	s_andn2_b64 vcc, exec, s[2:3]
	s_cbranch_vccnz .LBB0_1077
	s_waitcnt lgkmcnt(0)
	v_mov_b32_e32 v22, v127
	v_cmp_ne_u32_e32 vcc, s0, v22
	s_nop 1
	v_cndmask_b32_e32 v22, 0, v22, vcc
	v_not_b32_e32 v24, v22
	v_cmp_gt_i32_e32 vcc, 0, v22
	s_nop 1
	v_cndmask_b32_e64 v22, -|v22|, v24, vcc
.LBB0_1077:
	v_readlane_b32 s2, v237, 29
	v_readlane_b32 s3, v237, 30
	v_mov_b32_e32 v24, 0
	s_andn2_b64 vcc, exec, s[2:3]
	v_mov_b32_e32 v29, 0
	s_cbranch_vccnz .LBB0_1079
	s_waitcnt lgkmcnt(0)
	v_mov_b32_e32 v25, v128
	v_cmp_ne_u32_e32 vcc, s0, v25
	s_nop 1
	v_cndmask_b32_e32 v25, 0, v25, vcc
	v_not_b32_e32 v27, v25
	v_cmp_gt_i32_e32 vcc, 0, v25
	s_nop 1
	v_cndmask_b32_e64 v29, -|v25|, v27, vcc
.LBB0_1079:
	v_readlane_b32 s2, v237, 27
	v_readlane_b32 s3, v237, 28
	s_andn2_b64 vcc, exec, s[2:3]
	s_cbranch_vccnz .LBB0_1081
	s_waitcnt lgkmcnt(0)
	v_mov_b32_e32 v24, v129
	v_cmp_ne_u32_e32 vcc, s0, v24
	s_nop 1
	v_cndmask_b32_e32 v24, 0, v24, vcc
	v_not_b32_e32 v25, v24
	v_cmp_gt_i32_e32 vcc, 0, v24
	s_nop 1
	v_cndmask_b32_e64 v24, -|v24|, v25, vcc
.LBB0_1081:
	v_readlane_b32 s2, v237, 25
	v_readlane_b32 s3, v237, 26
	v_mov_b32_e32 v25, 0
	s_andn2_b64 vcc, exec, s[2:3]
	v_mov_b32_e32 v30, 0
	s_cbranch_vccnz .LBB0_1083
	s_waitcnt lgkmcnt(0)
	v_mov_b32_e32 v27, v130
	v_cmp_ne_u32_e32 vcc, s0, v27
	s_nop 1
	v_cndmask_b32_e32 v27, 0, v27, vcc
	v_not_b32_e32 v30, v27
	v_cmp_gt_i32_e32 vcc, 0, v27
	s_nop 1
	v_cndmask_b32_e64 v30, -|v27|, v30, vcc
.LBB0_1083:
	v_readlane_b32 s2, v236, 11
	v_readlane_b32 s3, v236, 12
	s_andn2_b64 vcc, exec, s[2:3]
	s_cbranch_vccnz .LBB0_1085
	s_waitcnt lgkmcnt(0)
	v_mov_b32_e32 v25, v131
	v_cmp_ne_u32_e32 vcc, s0, v25
	s_nop 1
	v_cndmask_b32_e32 v25, 0, v25, vcc
	v_not_b32_e32 v27, v25
	v_cmp_gt_i32_e32 vcc, 0, v25
	s_nop 1
	v_cndmask_b32_e64 v25, -|v25|, v27, vcc
.LBB0_1085:
	v_readlane_b32 s2, v236, 17
	v_readlane_b32 s3, v236, 18
	v_mov_b32_e32 v27, 0
	s_andn2_b64 vcc, exec, s[2:3]
	v_mov_b32_e32 v32, 0
	s_cbranch_vccnz .LBB0_1087
	s_waitcnt lgkmcnt(0)
	v_mov_b32_e32 v31, v132
	v_cmp_ne_u32_e32 vcc, s0, v31
	s_nop 1
	v_cndmask_b32_e32 v31, 0, v31, vcc
	v_not_b32_e32 v32, v31
	v_cmp_gt_i32_e32 vcc, 0, v31
	s_nop 1
	v_cndmask_b32_e64 v32, -|v31|, v32, vcc
.LBB0_1087:
	v_readlane_b32 s2, v236, 15
	v_readlane_b32 s3, v236, 16
	s_andn2_b64 vcc, exec, s[2:3]
	s_cbranch_vccnz .LBB0_1089
	s_waitcnt lgkmcnt(0)
	v_mov_b32_e32 v27, v133
	v_cmp_ne_u32_e32 vcc, s0, v27
	s_nop 1
	v_cndmask_b32_e32 v27, 0, v27, vcc
	v_not_b32_e32 v31, v27
	v_cmp_gt_i32_e32 vcc, 0, v27
	s_nop 1
	v_cndmask_b32_e64 v27, -|v27|, v31, vcc
.LBB0_1089:
	v_readlane_b32 s2, v237, 21
	v_readlane_b32 s3, v237, 22
	v_mov_b32_e32 v31, 0
	s_andn2_b64 vcc, exec, s[2:3]
	s_cbranch_vccnz .LBB0_1091
	s_waitcnt lgkmcnt(0)
	v_mov_b32_e32 v31, v134
	v_cmp_ne_u32_e32 vcc, s0, v31
	s_nop 1
	v_cndmask_b32_e32 v31, 0, v31, vcc
	v_not_b32_e32 v34, v31
	v_cmp_gt_i32_e32 vcc, 0, v31
	s_nop 1
	v_cndmask_b32_e64 v31, -|v31|, v34, vcc

; template <int NJ>
; DI void b1_select(const float* sc, int nj, unsigned* mo) {
;     ...
; #pragma unroll
;   for (int j = 0; j < NJ; ++j) {
;     unsigned k = 0u;
;     if (j < nj) {
;       unsigned u = __float_as_uint(sc[64 * j + lane]);
;       u = (u == 0x80000000u) ? 0u : u;
;       k = (u & 0x80000000u) ? ~u : (u | 0x80000000u);
;     }
;     key[j] = k;
;   }
.LBB0_1103:
	s_and_b64 vcc, exec, s[12:13]
	s_cbranch_vccz .LBB0_1155
	v_mov_b32_e32 v0, v158
	v_readlane_b32 s0, v238, 63
	v_and_b32_e32 v0, 63, v0
	v_mov_b32_e32 v2, 0
	v_lshl_add_u32 v10, v0, 2, s0
	ds_read_b32 v104, v10 offset:256
	ds_read_b32 v105, v10 offset:512
	ds_read_b32 v106, v10 offset:768
	ds_read_b32 v107, v10 offset:1024
	ds_read_b32 v108, v10 offset:1280
	ds_read_b32 v109, v10 offset:1536
	ds_read_b32 v110, v10 offset:1792
	ds_read_b32 v9, v10
	s_and_b64 vcc, exec, s[40:41]
	v_mov_b32_e32 v5, 0
	s_cbranch_vccnz .LBB0_1106
	s_waitcnt lgkmcnt(0)
	v_mov_b32_e32 v3, v104
	v_cmp_ne_u32_e32 vcc, s65, v3
	s_nop 1
	v_cndmask_b32_e32 v3, 0, v3, vcc
	v_not_b32_e32 v4, v3
	v_cmp_gt_i32_e32 vcc, 0, v3
	s_nop 1
	v_cndmask_b32_e64 v5, -|v3|, v4, vcc
.LBB0_1106:
	s_cmp_gt_u32 s8, 4
	s_cselect_b64 s[20:21], -1, 0
	s_cmp_lt_u32 s8, 5
	s_cbranch_scc1 .LBB0_1108
	s_waitcnt lgkmcnt(0)
	v_mov_b32_e32 v2, v105
	v_cmp_ne_u32_e32 vcc, s65, v2
	s_nop 1
	v_cndmask_b32_e32 v2, 0, v2, vcc
	v_not_b32_e32 v3, v2
	v_cmp_gt_i32_e32 vcc, 0, v2
	s_nop 1
	v_cndmask_b32_e64 v2, -|v2|, v3, vcc
.LBB0_1108:
	s_cmp_gt_u32 s8, 6
	v_mov_b32_e32 v3, 0
	s_cselect_b64 s[22:23], -1, 0
	s_cmp_lt_u32 s8, 7
	v_mov_b32_e32 v6, 0
	s_cbranch_scc1 .LBB0_1110
	s_waitcnt lgkmcnt(0)
	v_mov_b32_e32 v4, v106
	v_cmp_ne_u32_e32 vcc, s65, v4
	s_nop 1
	v_cndmask_b32_e32 v4, 0, v4, vcc
	v_not_b32_e32 v6, v4
	v_cmp_gt_i32_e32 vcc, 0, v4
	s_nop 1
	v_cndmask_b32_e64 v6, -|v4|, v6, vcc
.LBB0_1110:
	s_cmp_gt_u32 s8, 8
	s_cselect_b64 s[24:25], -1, 0
	s_cmp_lt_u32 s8, 9
	s_cbranch_scc1 .LBB0_1112
	s_waitcnt lgkmcnt(0)
	v_mov_b32_e32 v3, v107
	v_cmp_ne_u32_e32 vcc, s65, v3
	s_nop 1
	v_cndmask_b32_e32 v3, 0, v3, vcc
	v_not_b32_e32 v4, v3
	v_cmp_gt_i32_e32 vcc, 0, v3
	s_nop 1
	v_cndmask_b32_e64 v3, -|v3|, v4, vcc
.LBB0_1112:
	s_cmp_gt_u32 s8, 10
	v_mov_b32_e32 v4, 0
	s_cselect_b64 s[26:27], -1, 0
	s_cmp_lt_u32 s8, 11
	v_mov_b32_e32 v7, 0
	s_cbranch_scc1 .LBB0_1114
	s_waitcnt lgkmcnt(0)
	v_mov_b32_e32 v7, v108
	v_cmp_ne_u32_e32 vcc, s65, v7
	s_nop 1
	v_cndmask_b32_e32 v7, 0, v7, vcc
	v_not_b32_e32 v8, v7
	v_cmp_gt_i32_e32 vcc, 0, v7
	s_nop 1
	v_cndmask_b32_e64 v7, -|v7|, v8, vcc
.LBB0_1114:
	s_cmp_gt_u32 s8, 12
	s_cselect_b64 s[28:29], -1, 0
	s_cmp_lt_u32 s8, 13
	s_cbranch_scc1 .LBB0_1116
	s_waitcnt lgkmcnt(0)
	v_mov_b32_e32 v4, v109
	v_cmp_ne_u32_e32 vcc, s65, v4
	s_nop 1
	v_cndmask_b32_e32 v4, 0, v4, vcc
	v_not_b32_e32 v8, v4
	v_cmp_gt_i32_e32 vcc, 0, v4
	s_nop 1
	v_cndmask_b32_e64 v4, -|v4|, v8, vcc
.LBB0_1116:
	s_cmp_gt_u32 s8, 14
	s_cselect_b64 s[18:19], -1, 0
	s_cmp_lt_u32 s8, 15
	v_mov_b32_e32 v8, 0
	s_cbranch_scc1 .LBB0_1118
	s_waitcnt lgkmcnt(0)
	v_mov_b32_e32 v8, v110
	v_cmp_ne_u32_e32 vcc, s65, v8
	s_nop 1
	v_cndmask_b32_e32 v8, 0, v8, vcc
	v_not_b32_e32 v10, v8
	v_cmp_gt_i32_e32 vcc, 0, v8
	s_nop 1
	v_cndmask_b32_e64 v8, -|v8|, v10, vcc

; template <int NJ>
; DI void b1_select(const float* sc, int nj, unsigned* mo) {
;     ...
; #pragma unroll
;   for (int j = 0; j < NJ; ++j) {
;     unsigned k = 0u;
;     if (j < nj) {
;       unsigned u = __float_as_uint(sc[64 * j + lane]);
;       u = (u == 0x80000000u) ? 0u : u;
;       k = (u & 0x80000000u) ? ~u : (u | 0x80000000u);
;     }
;     key[j] = k;
;   }
.LBB0_1129:
	s_or_b64 exec, exec, s[16:17]
	v_mov_b32_e32 v0, v158
	v_readlane_b32 s0, v238, 63
	v_and_b32_e32 v0, 63, v0
	v_mov_b32_e32 v2, 0
	v_lshl_add_u32 v10, v0, 2, s0
	ds_read_b32 v104, v10 offset:8448
	ds_read_b32 v105, v10 offset:8960
	ds_read_b32 v106, v10 offset:9472
	ds_read_b32 v107, v10 offset:9728
	ds_read_b32 v108, v10 offset:9984
	ds_read_b32 v9, v10 offset:8192
	s_and_b64 vcc, exec, s[40:41]
	v_mov_b32_e32 v5, 0
	s_cbranch_vccnz .LBB0_1146
	s_waitcnt lgkmcnt(0)
	v_mov_b32_e32 v3, v104
	v_cmp_ne_u32_e32 vcc, s65, v3
	s_nop 1
	v_cndmask_b32_e32 v3, 0, v3, vcc
	v_not_b32_e32 v4, v3
	v_cmp_gt_i32_e32 vcc, 0, v3
	s_nop 1
	v_cndmask_b32_e64 v5, -|v3|, v4, vcc
	s_andn2_b64 vcc, exec, s[20:21]
	s_cbranch_vccz .LBB0_1147

; template <int NJ>
; DI void b1_select(const float* sc, int nj, unsigned* mo) {
;     ...
; #pragma unroll
;   for (int j = 0; j < NJ; ++j) {
;     unsigned k = 0u;
;     if (j < nj) {
;       unsigned u = __float_as_uint(sc[64 * j + lane]);
;       u = (u == 0x80000000u) ? 0u : u;
;       k = (u & 0x80000000u) ? ~u : (u | 0x80000000u);
;     }
;     key[j] = k;
;   }
.LBB0_1132:
	s_waitcnt lgkmcnt(0)
	v_mov_b32_e32 v4, v105
	v_cmp_ne_u32_e32 vcc, s65, v4
	s_nop 1
	v_cndmask_b32_e32 v4, 0, v4, vcc
	v_not_b32_e32 v6, v4
	v_cmp_gt_i32_e32 vcc, 0, v4
	s_nop 1
	v_cndmask_b32_e64 v6, -|v4|, v6, vcc
	s_andn2_b64 vcc, exec, s[24:25]
	s_cbranch_vccz .LBB0_1149

; template <int NJ>
; DI void b1_select(const float* sc, int nj, unsigned* mo) {
;     ...
; #pragma unroll
;   for (int j = 0; j < NJ; ++j) {
;     unsigned k = 0u;
;     if (j < nj) {
;       unsigned u = __float_as_uint(sc[64 * j + lane]);
;       u = (u == 0x80000000u) ? 0u : u;
;       k = (u & 0x80000000u) ? ~u : (u | 0x80000000u);
;     }
;     key[j] = k;
;   }
.LBB0_1134:
	s_waitcnt lgkmcnt(0)
	v_mov_b32_e32 v7, v106
	v_cmp_ne_u32_e32 vcc, s65, v7
	s_nop 1
	v_cndmask_b32_e32 v7, 0, v7, vcc
	v_not_b32_e32 v8, v7
	v_cmp_gt_i32_e32 vcc, 0, v7
	s_nop 1
	v_cndmask_b32_e64 v7, -|v7|, v8, vcc
.LBB0_1135:
	s_andn2_b64 vcc, exec, s[28:29]
	v_readlane_b32 s26, v237, 13
	s_cbranch_vccnz .LBB0_1137
	s_waitcnt lgkmcnt(0)
	v_mov_b32_e32 v4, v107
	v_cmp_ne_u32_e32 vcc, s65, v4
	s_nop 1
	v_cndmask_b32_e32 v4, 0, v4, vcc
	v_not_b32_e32 v8, v4
	v_cmp_gt_i32_e32 vcc, 0, v4
	s_nop 1
	v_cndmask_b32_e64 v4, -|v4|, v8, vcc
.LBB0_1137:
	v_mov_b32_e32 v8, 0
	s_andn2_b64 vcc, exec, s[18:19]
	s_cbranch_vccnz .LBB0_1139
	s_waitcnt lgkmcnt(0)
	v_mov_b32_e32 v8, v108
	v_cmp_ne_u32_e32 vcc, s65, v8
	s_nop 1
	v_cndmask_b32_e32 v8, 0, v8, vcc
	v_not_b32_e32 v10, v8
	v_cmp_gt_i32_e32 vcc, 0, v8
	s_nop 1
	v_cndmask_b32_e64 v8, -|v8|, v10, vcc
